# Z_E1
# speedup vs baseline: 1.0206x; 1.0170x over previous
;     __device__ bool next(int i, Unit& u) const { if (!base.next(i >> 1, u)) return false; u.sub = i & 1; return true; }
; #define PG8_STAGE(bufoff, gbase, voff) do { _Pragma("unroll") for (int _i = 0; _i < 2; ++_i) \
;         __builtin_amdgcn_global_load_lds((const unsigned*)((const char*)(gbase) + (voff)[_i]), (PG8_LAS unsigned*)(lds + (bufoff) + ldsw + _i * 8192), 16, 0, 0); } while (0)
; #define PG8_LDA(dst, b, h) do { _Pragma("unroll") for (int m = 0; m < 4; ++m) _Pragma("unroll") for (int k = 0; k < 2; ++k) dst[m][k] = *(const PG8_LAS bf16x8*)(lds + PG8_SA(b, h) + aoff + m * 2048 + k * 1024); } while (0)
; #define PG8_LDB(dst, b, h) do { _Pragma("unroll") for (int n = 0; n < 2; ++n) _Pragma("unroll") for (int k = 0; k < 2; ++k) dst[n][k] = *(const PG8_LAS bf16x8*)(lds + PG8_SB(b, h) + boff + n * 2048 + k * 1024); } while (0)
; #define PG8_WAIT_V(n) asm volatile("s_waitcnt vmcnt(" #n ")" ::: "memory")
; template <class Epi, class Sched, bool ALIGN_EPI = false, bool SP2 = false, bool DUAL = false>
; __device__ __forceinline__ void gemm_phase(PG8_LAS unsigned char* lds, const Gemm g, const Sched& S, const Epi& E) {
;     ...
;         const bool has_next = S.next(ui + 1, nxt);
;         const char* nA = has_next ? (const char*)((DUAL && nxt.sub) ? g.A2 : g.A) + (size_t)nxt.pm * tstep : cA; const char* nB = has_next ? (const char*)((DUAL && nxt.sub) ? g.Bt2 : g.Bt) + (size_t)nxt.pn * tstep : cB;
;         for (int t = 0; t < nt; t += 2) {
;             const bool last = (t == nt - 2);
;             const char* a1 = cA + (size_t)(t + 1) * kstep;
;             const char* a2 = last ? nA : cA + (size_t)(t + 2) * kstep; const char* b2 = last ? nB : cB + (size_t)(t + 2) * kstep;
;             const char* a3 = a2 + kstep; const char* b3 = b2 + kstep;
;             if (last && has_next) S.a_ready(nxt);
;             if constexpr (SP2) {
;             PG8_LDB(B0, 0, 0); PG8_LDB(B1, 0, 1); PG8_SCHED; PG8_LDA(At, 0, 0); PG8_STAGE(PG8_SA(1, 1), a1 + hstep, voffA);
;             PG8_WAIT_V(8); PG8_WAIT_L(0); PG8_BAR; PG8_MMA(0, 0, At, B0); PG8_MMA(0, 1, At, B1); PG8_BAR; PG8_SCHED;
;             PG8_LDA(At, 0, 1); PG8_STAGE(PG8_SB(0, 0), b2, voffB); PG8_STAGE(PG8_SB(0, 1), b2 + hstep, voffB); PG8_STAGE(PG8_SA(0, 0), a2, voffA);
;             PG8_WAIT_V(8); PG8_WAIT_L(0); PG8_BAR; PG8_MMA(1, 0, At, B0); PG8_MMA(1, 1, At, B1); PG8_BAR; PG8_SCHED;
.LBB0_251:
	s_ashr_i32 s87, s86, 31
	s_lshl_b64 s[16:17], s[86:87], 20
	s_add_u32 s92, s58, s16
	s_addc_u32 s93, s59, s17
	s_and_b64 s[16:17], s[4:5], exec
	s_cselect_b32 s7, s93, s11
	s_cselect_b32 s9, s92, s10
	s_ashr_i32 s1, s0, 31
	s_lshl_b64 s[16:17], s[0:1], 20
	s_add_u32 s88, s90, s16
	s_addc_u32 s89, s91, s17
	s_and_b64 s[16:17], s[4:5], exec
	s_cselect_b32 s1, s89, s15
	s_cselect_b32 s45, s88, s14
	s_add_u32 s10, s10, 0x80080
	s_addc_u32 s11, s11, 0
	s_add_u32 s46, s14, 0x100
	s_addc_u32 s47, s15, 0
	s_mov_b32 s48, -2
	ds_read_b128 v[80:83], v199
	ds_read_b128 v[84:87], v199 offset:1024
	ds_read_b128 v[88:91], v199 offset:2048
	ds_read_b128 v[92:95], v199 offset:3072
	ds_read_b128 v[144:147], v202
	ds_read_b128 v[148:151], v202 offset:1024
	ds_read_b128 v[152:155], v202 offset:2048
	ds_read_b128 v[156:159], v202 offset:3072
	s_add_u32 s14, s10, 0xfff80080
	s_addc_u32 s15, s11, -1
	s_cmp_eq_u32 s48, 28
	s_cselect_b32 s17, s7, s15
	s_cselect_b32 s16, s9, s14
	s_cselect_b32 s15, s1, s47
	s_cselect_b32 s14, s45, s46
	v_lshl_add_u64 v[192:193], s[10:11], 0, v[186:187]
	s_add_i32 m0, s19, 0xc000
	ds_read_b128 v[208:211], v203
	ds_read_b128 v[212:215], v203 offset:1024
	ds_read_b128 v[216:219], v203 offset:2048
	ds_read_b128 v[220:223], v203 offset:3072
	ds_read_b128 v[232:235], v203 offset:4096
	ds_read_b128 v[236:239], v203 offset:5120
	ds_read_b128 v[240:243], v203 offset:6144
	ds_read_b128 v[244:247], v203 offset:7168
	global_load_lds_dwordx4 v[192:193], off
	v_lshl_add_u64 v[192:193], s[10:11], 0, v[188:189]
	s_add_i32 m0, s19, 0xe000
	s_nop 0
	global_load_lds_dwordx4 v[192:193], off
	s_waitcnt vmcnt(8)
	s_waitcnt lgkmcnt(0)
	s_setprio 1
	s_barrier
	v_mfma_f32_16x16x32_bf16 v[140:143], v[80:83], v[208:211], 0
	v_mfma_f32_16x16x32_bf16 v[132:135], v[88:91], v[208:211], 0
	v_mfma_f32_16x16x32_bf16 v[124:127], v[80:83], v[216:219], 0
	v_mfma_f32_16x16x32_bf16 v[120:123], v[88:91], v[216:219], 0
	v_mfma_f32_16x16x32_bf16 v[108:111], v[80:83], v[232:235], 0
	v_mfma_f32_16x16x32_bf16 v[104:107], v[88:91], v[232:235], 0
	v_mfma_f32_16x16x32_bf16 v[76:79], v[80:83], v[240:243], 0
	v_mfma_f32_16x16x32_bf16 v[72:75], v[88:91], v[240:243], 0
	v_mfma_f32_16x16x32_bf16 v[140:143], v[84:87], v[212:215], v[140:143]
	v_mfma_f32_16x16x32_bf16 v[132:135], v[92:95], v[212:215], v[132:135]
	v_mfma_f32_16x16x32_bf16 v[124:127], v[84:87], v[220:223], v[124:127]
	v_mfma_f32_16x16x32_bf16 v[120:123], v[92:95], v[220:223], v[120:123]
	v_mfma_f32_16x16x32_bf16 v[108:111], v[84:87], v[236:239], v[108:111]
	v_mfma_f32_16x16x32_bf16 v[104:107], v[92:95], v[236:239], v[104:107]
	v_mfma_f32_16x16x32_bf16 v[76:79], v[84:87], v[244:247], v[76:79]
	v_mfma_f32_16x16x32_bf16 v[72:75], v[92:95], v[244:247], v[72:75]
	s_setprio 0
	s_setprio 1
	v_mfma_f32_16x16x32_bf16 v[136:139], v[144:147], v[208:211], 0
	v_mfma_f32_16x16x32_bf16 v[128:131], v[152:155], v[208:211], 0
	v_mfma_f32_16x16x32_bf16 v[116:119], v[144:147], v[216:219], 0
	v_mfma_f32_16x16x32_bf16 v[112:115], v[152:155], v[216:219], 0
	v_mfma_f32_16x16x32_bf16 v[100:103], v[144:147], v[232:235], 0
	v_mfma_f32_16x16x32_bf16 v[96:99], v[152:155], v[232:235], 0
	v_mfma_f32_16x16x32_bf16 v[68:71], v[144:147], v[240:243], 0
	v_mfma_f32_16x16x32_bf16 v[64:67], v[152:155], v[240:243], 0
	v_mfma_f32_16x16x32_bf16 v[136:139], v[148:151], v[212:215], v[136:139]
	v_mfma_f32_16x16x32_bf16 v[128:131], v[156:159], v[212:215], v[128:131]
	v_mfma_f32_16x16x32_bf16 v[116:119], v[148:151], v[220:223], v[116:119]
	v_mfma_f32_16x16x32_bf16 v[112:115], v[156:159], v[220:223], v[112:115]
	v_mfma_f32_16x16x32_bf16 v[100:103], v[148:151], v[236:239], v[100:103]
	v_mfma_f32_16x16x32_bf16 v[96:99], v[156:159], v[236:239], v[96:99]
	v_mfma_f32_16x16x32_bf16 v[68:71], v[148:151], v[244:247], v[68:71]
	v_mfma_f32_16x16x32_bf16 v[64:67], v[156:159], v[244:247], v[64:67]
	s_barrier
	s_setprio 0
	s_add_i32 s49, s31, s18
	v_lshl_add_u64 v[192:193], s[14:15], 0, v[166:167]
	s_mov_b32 m0, s49
	ds_read_b128 v[208:211], v203 offset:16384
	ds_read_b128 v[212:215], v203 offset:17408
	ds_read_b128 v[216:219], v203 offset:18432
	ds_read_b128 v[220:223], v203 offset:19456
	ds_read_b128 v[232:235], v203 offset:20480
	ds_read_b128 v[236:239], v203 offset:21504
	ds_read_b128 v[240:243], v203 offset:22528
	ds_read_b128 v[244:247], v203 offset:23552
	global_load_lds_dwordx4 v[192:193], off
	s_add_i32 m0, s49, 0x2000
	s_add_u32 s50, s14, 0x80000
	v_lshl_add_u64 v[248:249], s[14:15], 0, v[170:171]
	s_addc_u32 s51, s15, 0
	s_add_i32 s49, s34, s18
	global_load_lds_dwordx4 v[248:249], off
	v_lshl_add_u64 v[250:251], s[50:51], 0, v[166:167]
	s_mov_b32 m0, s49
	v_lshl_add_u64 v[252:253], s[16:17], 0, v[168:169]
	global_load_lds_dwordx4 v[250:251], off
	v_lshl_add_u64 v[250:251], s[50:51], 0, v[170:171]
	s_add_i32 m0, s49, 0x2000
	s_nop 0
	global_load_lds_dwordx4 v[250:251], off
	v_lshl_add_u64 v[250:251], s[16:17], 0, v[164:165]
	s_mov_b32 m0, s19
	s_nop 0
	global_load_lds_dwordx4 v[250:251], off
	s_mov_b32 m0, s20
	s_nop 0
	global_load_lds_dwordx4 v[252:253], off
	s_waitcnt vmcnt(8)
	s_waitcnt lgkmcnt(0)
	s_setprio 1
	s_barrier
; #define PG8_STAGE(bufoff, gbase, voff) do { _Pragma("unroll") for (int _i = 0; _i < 2; ++_i) \
;         __builtin_amdgcn_global_load_lds((const unsigned*)((const char*)(gbase) + (voff)[_i]), (PG8_LAS unsigned*)(lds + (bufoff) + ldsw + _i * 8192), 16, 0, 0); } while (0)
; #define PG8_LDA(dst, b, h) do { _Pragma("unroll") for (int m = 0; m < 4; ++m) _Pragma("unroll") for (int k = 0; k < 2; ++k) dst[m][k] = *(const PG8_LAS bf16x8*)(lds + PG8_SA(b, h) + aoff + m * 2048 + k * 1024); } while (0)
; #define PG8_LDB(dst, b, h) do { _Pragma("unroll") for (int n = 0; n < 2; ++n) _Pragma("unroll") for (int k = 0; k < 2; ++k) dst[n][k] = *(const PG8_LAS bf16x8*)(lds + PG8_SB(b, h) + boff + n * 2048 + k * 1024); } while (0)
; #define PG8_MMA(ai, bj, At, Bt) do { __builtin_amdgcn_s_setprio(1); _Pragma("unroll") for (int m = 0; m < 4; ++m) _Pragma("unroll") for (int n = 0; n < 2; ++n) _Pragma("unroll") for (int k = 0; k < 2; ++k) \
;         acc[ai][bj][m][n] = __builtin_amdgcn_mfma_f32_16x16x32_bf16(Bt[n][k], At[m][k], acc[ai][bj][m][n], 0, 0, 0); __builtin_amdgcn_s_setprio(0); } while (0)
; #define PG8_WAIT_V(n) asm volatile("s_waitcnt vmcnt(" #n ")" ::: "memory")
; #define PG8_WAIT_L(n) asm volatile("s_waitcnt lgkmcnt(" #n ")" ::: "memory")
; #define PG8_BAR __builtin_amdgcn_s_barrier()
; #define PG8_SCHED __builtin_amdgcn_sched_barrier(0)
; template <class Epi, class Sched, bool ALIGN_EPI = false, bool SP2 = false, bool DUAL = false>
; __device__ __forceinline__ void gemm_phase(PG8_LAS unsigned char* lds, const Gemm g, const Sched& S, const Epi& E) {
;     ...
;             PG8_WAIT_V(8); PG8_WAIT_L(0); PG8_BAR; PG8_MMA(1, 0, At, B0); PG8_MMA(1, 1, At, B1); PG8_BAR; PG8_SCHED;
;             PG8_LDB(B0, 1, 0); PG8_LDB(B1, 1, 1); PG8_SCHED; PG8_LDA(At, 1, 0); PG8_STAGE(PG8_SA(0, 1), a2 + hstep, voffA);
;             PG8_WAIT_V(8); PG8_WAIT_L(0); PG8_BAR; PG8_MMA(0, 0, At, B0); PG8_MMA(0, 1, At, B1); PG8_BAR; PG8_SCHED;
	v_mfma_f32_16x16x32_bf16 v[60:63], v[80:83], v[208:211], 0
	v_mfma_f32_16x16x32_bf16 v[56:59], v[88:91], v[208:211], 0
	v_mfma_f32_16x16x32_bf16 v[44:47], v[80:83], v[216:219], 0
	v_mfma_f32_16x16x32_bf16 v[40:43], v[88:91], v[216:219], 0
	v_mfma_f32_16x16x32_bf16 v[28:31], v[80:83], v[232:235], 0
	v_mfma_f32_16x16x32_bf16 v[24:27], v[88:91], v[232:235], 0
	v_mfma_f32_16x16x32_bf16 v[12:15], v[80:83], v[240:243], 0
	v_mfma_f32_16x16x32_bf16 v[8:11], v[88:91], v[240:243], 0
	v_mfma_f32_16x16x32_bf16 v[60:63], v[84:87], v[212:215], v[60:63]
	v_mfma_f32_16x16x32_bf16 v[56:59], v[92:95], v[212:215], v[56:59]
	v_mfma_f32_16x16x32_bf16 v[44:47], v[84:87], v[220:223], v[44:47]
	v_mfma_f32_16x16x32_bf16 v[40:43], v[92:95], v[220:223], v[40:43]
	v_mfma_f32_16x16x32_bf16 v[28:31], v[84:87], v[236:239], v[28:31]
	v_mfma_f32_16x16x32_bf16 v[24:27], v[92:95], v[236:239], v[24:27]
	v_mfma_f32_16x16x32_bf16 v[12:15], v[84:87], v[244:247], v[12:15]
	v_mfma_f32_16x16x32_bf16 v[8:11], v[92:95], v[244:247], v[8:11]
	s_setprio 0
	s_setprio 1
	v_mfma_f32_16x16x32_bf16 v[52:55], v[144:147], v[208:211], 0
	v_mfma_f32_16x16x32_bf16 v[48:51], v[152:155], v[208:211], 0
	v_mfma_f32_16x16x32_bf16 v[36:39], v[144:147], v[216:219], 0
	v_mfma_f32_16x16x32_bf16 v[32:35], v[152:155], v[216:219], 0
	v_mfma_f32_16x16x32_bf16 v[20:23], v[144:147], v[232:235], 0
	v_mfma_f32_16x16x32_bf16 v[16:19], v[152:155], v[232:235], 0
	v_mfma_f32_16x16x32_bf16 v[4:7], v[144:147], v[240:243], 0
	v_mfma_f32_16x16x32_bf16 v[0:3], v[152:155], v[240:243], 0
	v_mfma_f32_16x16x32_bf16 v[52:55], v[148:151], v[212:215], v[52:55]
	v_mfma_f32_16x16x32_bf16 v[48:51], v[156:159], v[212:215], v[48:51]
	v_mfma_f32_16x16x32_bf16 v[36:39], v[148:151], v[220:223], v[36:39]
	v_mfma_f32_16x16x32_bf16 v[32:35], v[156:159], v[220:223], v[32:35]
	v_mfma_f32_16x16x32_bf16 v[20:23], v[148:151], v[236:239], v[20:23]
	v_mfma_f32_16x16x32_bf16 v[16:19], v[156:159], v[236:239], v[16:19]
	v_mfma_f32_16x16x32_bf16 v[4:7], v[148:151], v[244:247], v[4:7]
	v_mfma_f32_16x16x32_bf16 v[0:3], v[156:159], v[244:247], v[0:3]
	s_barrier
	s_setprio 0
	s_add_i32 s49, 0, 0x18000
	s_add_i32 s50, 0, 0x1c000
	v_add_u32_e32 v92, s49, v196
	v_add_u32_e32 v156, s50, v196
	ds_read_b128 v[80:83], v92
	ds_read_b128 v[84:87], v92 offset:1024
	ds_read_b128 v[88:91], v92 offset:2048
	ds_read_b128 v[92:95], v92 offset:3072
	ds_read_b128 v[144:147], v156
	ds_read_b128 v[148:151], v156 offset:1024
	ds_read_b128 v[152:155], v156 offset:2048
	ds_read_b128 v[156:159], v156 offset:3072
	s_add_u32 s16, s16, 0x80000
	s_addc_u32 s17, s17, 0
	s_mov_b32 m0, s21
	v_lshl_add_u64 v[228:229], s[16:17], 0, v[164:165]
	ds_read_b128 v[208:211], v203 offset:32768
	ds_read_b128 v[212:215], v203 offset:33792
	ds_read_b128 v[216:219], v203 offset:34816
	ds_read_b128 v[220:223], v203 offset:35840
	ds_read_b128 v[232:235], v203 offset:36864
	ds_read_b128 v[236:239], v203 offset:37888
	ds_read_b128 v[240:243], v203 offset:38912
	ds_read_b128 v[244:247], v203 offset:39936
	global_load_lds_dwordx4 v[228:229], off
	v_lshl_add_u64 v[228:229], s[16:17], 0, v[168:169]
	s_mov_b32 m0, s22
	s_nop 0
	global_load_lds_dwordx4 v[228:229], off
	s_waitcnt vmcnt(8)
	s_waitcnt lgkmcnt(0)
	s_setprio 1
	s_barrier
	v_mfma_f32_16x16x32_bf16 v[140:143], v[80:83], v[208:211], v[140:143]
	v_mfma_f32_16x16x32_bf16 v[132:135], v[88:91], v[208:211], v[132:135]
	v_mfma_f32_16x16x32_bf16 v[124:127], v[80:83], v[216:219], v[124:127]
	v_mfma_f32_16x16x32_bf16 v[120:123], v[88:91], v[216:219], v[120:123]
	v_mfma_f32_16x16x32_bf16 v[108:111], v[80:83], v[232:235], v[108:111]
	v_mfma_f32_16x16x32_bf16 v[104:107], v[88:91], v[232:235], v[104:107]
	v_mfma_f32_16x16x32_bf16 v[76:79], v[80:83], v[240:243], v[76:79]
	v_mfma_f32_16x16x32_bf16 v[72:75], v[88:91], v[240:243], v[72:75]
	v_mfma_f32_16x16x32_bf16 v[140:143], v[84:87], v[212:215], v[140:143]
	v_mfma_f32_16x16x32_bf16 v[132:135], v[92:95], v[212:215], v[132:135]
	v_mfma_f32_16x16x32_bf16 v[124:127], v[84:87], v[220:223], v[124:127]
	v_mfma_f32_16x16x32_bf16 v[120:123], v[92:95], v[220:223], v[120:123]
	v_mfma_f32_16x16x32_bf16 v[108:111], v[84:87], v[236:239], v[108:111]
	v_mfma_f32_16x16x32_bf16 v[104:107], v[92:95], v[236:239], v[104:107]
	v_mfma_f32_16x16x32_bf16 v[76:79], v[84:87], v[244:247], v[76:79]
	v_mfma_f32_16x16x32_bf16 v[72:75], v[92:95], v[244:247], v[72:75]
	s_setprio 0
	s_setprio 1
	v_mfma_f32_16x16x32_bf16 v[136:139], v[144:147], v[208:211], v[136:139]
	v_mfma_f32_16x16x32_bf16 v[128:131], v[152:155], v[208:211], v[128:131]
	v_mfma_f32_16x16x32_bf16 v[116:119], v[144:147], v[216:219], v[116:119]
	v_mfma_f32_16x16x32_bf16 v[112:115], v[152:155], v[216:219], v[112:115]
	v_mfma_f32_16x16x32_bf16 v[100:103], v[144:147], v[232:235], v[100:103]
	v_mfma_f32_16x16x32_bf16 v[96:99], v[152:155], v[232:235], v[96:99]
	v_mfma_f32_16x16x32_bf16 v[68:71], v[144:147], v[240:243], v[68:71]
	v_mfma_f32_16x16x32_bf16 v[64:67], v[152:155], v[240:243], v[64:67]
	v_mfma_f32_16x16x32_bf16 v[136:139], v[148:151], v[212:215], v[136:139]
	v_mfma_f32_16x16x32_bf16 v[128:131], v[156:159], v[212:215], v[128:131]
	v_mfma_f32_16x16x32_bf16 v[116:119], v[148:151], v[220:223], v[116:119]
	v_mfma_f32_16x16x32_bf16 v[112:115], v[156:159], v[220:223], v[112:115]
	v_mfma_f32_16x16x32_bf16 v[100:103], v[148:151], v[236:239], v[100:103]
	v_mfma_f32_16x16x32_bf16 v[96:99], v[156:159], v[236:239], v[96:99]
	v_mfma_f32_16x16x32_bf16 v[68:71], v[148:151], v[244:247], v[68:71]
	v_mfma_f32_16x16x32_bf16 v[64:67], v[156:159], v[244:247], v[64:67]
	s_barrier
; #define PG8_STAGE(bufoff, gbase, voff) do { _Pragma("unroll") for (int _i = 0; _i < 2; ++_i) \
;         __builtin_amdgcn_global_load_lds((const unsigned*)((const char*)(gbase) + (voff)[_i]), (PG8_LAS unsigned*)(lds + (bufoff) + ldsw + _i * 8192), 16, 0, 0); } while (0)
; #define PG8_LDA(dst, b, h) do { _Pragma("unroll") for (int m = 0; m < 4; ++m) _Pragma("unroll") for (int k = 0; k < 2; ++k) dst[m][k] = *(const PG8_LAS bf16x8*)(lds + PG8_SA(b, h) + aoff + m * 2048 + k * 1024); } while (0)
; #define PG8_LDB(dst, b, h) do { _Pragma("unroll") for (int n = 0; n < 2; ++n) _Pragma("unroll") for (int k = 0; k < 2; ++k) dst[n][k] = *(const PG8_LAS bf16x8*)(lds + PG8_SB(b, h) + boff + n * 2048 + k * 1024); } while (0)
; #define PG8_MMA(ai, bj, At, Bt) do { __builtin_amdgcn_s_setprio(1); _Pragma("unroll") for (int m = 0; m < 4; ++m) _Pragma("unroll") for (int n = 0; n < 2; ++n) _Pragma("unroll") for (int k = 0; k < 2; ++k) \
;         acc[ai][bj][m][n] = __builtin_amdgcn_mfma_f32_16x16x32_bf16(Bt[n][k], At[m][k], acc[ai][bj][m][n], 0, 0, 0); __builtin_amdgcn_s_setprio(0); } while (0)
; #define PG8_BAR __builtin_amdgcn_s_barrier()
; template <class Epi, class Sched, bool ALIGN_EPI = false, bool SP2 = false, bool DUAL = false>
; __device__ __forceinline__ void gemm_phase(PG8_LAS unsigned char* lds, const Gemm g, const Sched& S, const Epi& E) {
;     ...
;             PG8_LDB(B0, 0, 0); PG8_LDB(B1, 0, 1); PG8_SCHED; PG8_LDA(At, 0, 0); PG8_STAGE(PG8_SA(1, 1), a1 + hstep, voffA);
;             PG8_WAIT_V(8); PG8_WAIT_L(0); PG8_BAR; PG8_MMA(0, 0, At, B0); PG8_MMA(0, 1, At, B1); PG8_BAR; PG8_SCHED;
;             PG8_LDA(At, 0, 1); PG8_STAGE(PG8_SB(0, 0), b2, voffB); PG8_STAGE(PG8_SB(0, 1), b2 + hstep, voffB); PG8_STAGE(PG8_SA(0, 0), a2, voffA);
;             PG8_WAIT_V(8); PG8_WAIT_L(0); PG8_BAR; PG8_MMA(1, 0, At, B0); PG8_MMA(1, 1, At, B1); PG8_BAR; PG8_SCHED;
;             PG8_LDB(B0, 1, 0); PG8_LDB(B1, 1, 1); PG8_SCHED; PG8_LDA(At, 1, 0); PG8_STAGE(PG8_SA(0, 1), a2 + hstep, voffA);
;             PG8_WAIT_V(8); PG8_WAIT_L(0); PG8_BAR; PG8_MMA(0, 0, At, B0); PG8_MMA(0, 1, At, B1); PG8_BAR; PG8_SCHED;
;             PG8_LDA(At, 1, 1); PG8_STAGE(PG8_SB(1, 0), b3, voffB); PG8_STAGE(PG8_SB(1, 1), b3 + hstep, voffB); PG8_STAGE(PG8_SA(1, 0), a3, voffA);
;             PG8_WAIT_V(8); PG8_WAIT_L(0); PG8_BAR; PG8_MMA(1, 0, At, B0); PG8_MMA(1, 1, At, B1); PG8_BAR; PG8_SCHED;
	s_setprio 0
	s_add_i32 s16, s49, s18
	v_lshl_add_u64 v[192:193], v[192:193], 0, s[76:77]
	s_mov_b32 m0, s16
	ds_read_b128 v[208:211], v203 offset:49152
	ds_read_b128 v[212:215], v203 offset:50176
	ds_read_b128 v[216:219], v203 offset:51200
	ds_read_b128 v[220:223], v203 offset:52224
	ds_read_b128 v[232:235], v203 offset:53248
	ds_read_b128 v[236:239], v203 offset:54272
	ds_read_b128 v[240:243], v203 offset:55296
	ds_read_b128 v[244:247], v203 offset:56320
	global_load_lds_dwordx4 v[192:193], off
	s_add_i32 m0, s16, 0x2000
	s_add_u32 s14, s14, 0x80080
	v_lshl_add_u64 v[192:193], v[248:249], 0, s[76:77]
	s_addc_u32 s15, s15, 0
	s_add_i32 s16, s50, s18
	global_load_lds_dwordx4 v[192:193], off
	v_lshl_add_u64 v[192:193], s[14:15], 0, v[166:167]
	s_mov_b32 m0, s16
	s_nop 0
	global_load_lds_dwordx4 v[192:193], off
	v_lshl_add_u64 v[192:193], s[14:15], 0, v[170:171]
	s_add_i32 m0, s16, 0x2000
	s_nop 0
	global_load_lds_dwordx4 v[192:193], off
	v_lshl_add_u64 v[192:193], v[250:251], 0, s[76:77]
	s_mov_b32 m0, s27
	s_nop 0
	global_load_lds_dwordx4 v[192:193], off
	v_lshl_add_u64 v[192:193], v[252:253], 0, s[76:77]
	s_mov_b32 m0, s28
	s_nop 0
	global_load_lds_dwordx4 v[192:193], off
	s_waitcnt vmcnt(8)
	s_waitcnt lgkmcnt(0)
	s_setprio 1
	s_barrier
	v_mfma_f32_16x16x32_bf16 v[60:63], v[80:83], v[208:211], v[60:63]
	v_mfma_f32_16x16x32_bf16 v[56:59], v[88:91], v[208:211], v[56:59]
	v_mfma_f32_16x16x32_bf16 v[44:47], v[80:83], v[216:219], v[44:47]
	v_mfma_f32_16x16x32_bf16 v[40:43], v[88:91], v[216:219], v[40:43]
	v_mfma_f32_16x16x32_bf16 v[28:31], v[80:83], v[232:235], v[28:31]
	v_mfma_f32_16x16x32_bf16 v[24:27], v[88:91], v[232:235], v[24:27]
	v_mfma_f32_16x16x32_bf16 v[12:15], v[80:83], v[240:243], v[12:15]
	v_mfma_f32_16x16x32_bf16 v[8:11], v[88:91], v[240:243], v[8:11]
	v_mfma_f32_16x16x32_bf16 v[60:63], v[84:87], v[212:215], v[60:63]
	v_mfma_f32_16x16x32_bf16 v[56:59], v[92:95], v[212:215], v[56:59]
	v_mfma_f32_16x16x32_bf16 v[44:47], v[84:87], v[220:223], v[44:47]
	v_mfma_f32_16x16x32_bf16 v[40:43], v[92:95], v[220:223], v[40:43]
	v_mfma_f32_16x16x32_bf16 v[28:31], v[84:87], v[236:239], v[28:31]
	v_mfma_f32_16x16x32_bf16 v[24:27], v[92:95], v[236:239], v[24:27]
	v_mfma_f32_16x16x32_bf16 v[12:15], v[84:87], v[244:247], v[12:15]
	v_mfma_f32_16x16x32_bf16 v[8:11], v[92:95], v[244:247], v[8:11]
	s_setprio 0
	s_setprio 1
	v_mfma_f32_16x16x32_bf16 v[52:55], v[144:147], v[208:211], v[52:55]
	v_mfma_f32_16x16x32_bf16 v[48:51], v[152:155], v[208:211], v[48:51]
	v_mfma_f32_16x16x32_bf16 v[36:39], v[144:147], v[216:219], v[36:39]
	v_mfma_f32_16x16x32_bf16 v[32:35], v[152:155], v[216:219], v[32:35]
	v_mfma_f32_16x16x32_bf16 v[20:23], v[144:147], v[232:235], v[20:23]
	v_mfma_f32_16x16x32_bf16 v[16:19], v[152:155], v[232:235], v[16:19]
	v_mfma_f32_16x16x32_bf16 v[4:7], v[144:147], v[240:243], v[4:7]
	v_mfma_f32_16x16x32_bf16 v[0:3], v[152:155], v[240:243], v[0:3]
	v_mfma_f32_16x16x32_bf16 v[52:55], v[148:151], v[212:215], v[52:55]
	v_mfma_f32_16x16x32_bf16 v[48:51], v[156:159], v[212:215], v[48:51]
	v_mfma_f32_16x16x32_bf16 v[36:39], v[148:151], v[220:223], v[36:39]
	v_mfma_f32_16x16x32_bf16 v[32:35], v[156:159], v[220:223], v[32:35]
	v_mfma_f32_16x16x32_bf16 v[20:23], v[148:151], v[236:239], v[20:23]
	v_mfma_f32_16x16x32_bf16 v[16:19], v[156:159], v[236:239], v[16:19]
	v_mfma_f32_16x16x32_bf16 v[4:7], v[148:151], v[244:247], v[4:7]
	v_mfma_f32_16x16x32_bf16 v[0:3], v[156:159], v[244:247], v[0:3]
	s_barrier
	s_setprio 0
	s_add_i32 s48, s48, 2
	s_add_u32 s10, s10, 0x100
	s_addc_u32 s11, s11, 0
	s_add_u32 s46, s46, 0x100
	s_addc_u32 s47, s47, 0
.LBB0_252:
	ds_read_b128 v[80:83], v199
	ds_read_b128 v[84:87], v199 offset:1024
	ds_read_b128 v[88:91], v199 offset:2048
	ds_read_b128 v[92:95], v199 offset:3072
	ds_read_b128 v[144:147], v202
	ds_read_b128 v[148:151], v202 offset:1024
	ds_read_b128 v[152:155], v202 offset:2048
	ds_read_b128 v[156:159], v202 offset:3072
	s_add_u32 s14, s10, 0xfff80080
	s_addc_u32 s15, s11, -1
	s_cmp_eq_u32 s48, 28
	s_cselect_b32 s17, s7, s15
	s_cselect_b32 s16, s9, s14
	s_cselect_b32 s15, s1, s47
	s_cselect_b32 s14, s45, s46
	v_lshl_add_u64 v[192:193], s[10:11], 0, v[186:187]
	s_add_i32 m0, s19, 0xc000
	ds_read_b128 v[208:211], v203
	ds_read_b128 v[212:215], v203 offset:1024
	ds_read_b128 v[216:219], v203 offset:2048
	ds_read_b128 v[220:223], v203 offset:3072
	ds_read_b128 v[232:235], v203 offset:4096
	ds_read_b128 v[236:239], v203 offset:5120
	ds_read_b128 v[240:243], v203 offset:6144
	ds_read_b128 v[244:247], v203 offset:7168
	global_load_lds_dwordx4 v[192:193], off
	v_lshl_add_u64 v[192:193], s[10:11], 0, v[188:189]
	s_add_i32 m0, s19, 0xe000
	s_nop 0
	global_load_lds_dwordx4 v[192:193], off
	s_waitcnt vmcnt(8)
	s_waitcnt lgkmcnt(0)
	s_setprio 1
	s_barrier
; #define PG8_STAGE(bufoff, gbase, voff) do { _Pragma("unroll") for (int _i = 0; _i < 2; ++_i) \
;         __builtin_amdgcn_global_load_lds((const unsigned*)((const char*)(gbase) + (voff)[_i]), (PG8_LAS unsigned*)(lds + (bufoff) + ldsw + _i * 8192), 16, 0, 0); } while (0)
; #define PG8_LDA(dst, b, h) do { _Pragma("unroll") for (int m = 0; m < 4; ++m) _Pragma("unroll") for (int k = 0; k < 2; ++k) dst[m][k] = *(const PG8_LAS bf16x8*)(lds + PG8_SA(b, h) + aoff + m * 2048 + k * 1024); } while (0)
; #define PG8_MMA(ai, bj, At, Bt) do { __builtin_amdgcn_s_setprio(1); _Pragma("unroll") for (int m = 0; m < 4; ++m) _Pragma("unroll") for (int n = 0; n < 2; ++n) _Pragma("unroll") for (int k = 0; k < 2; ++k) \
;         acc[ai][bj][m][n] = __builtin_amdgcn_mfma_f32_16x16x32_bf16(Bt[n][k], At[m][k], acc[ai][bj][m][n], 0, 0, 0); __builtin_amdgcn_s_setprio(0); } while (0)
; #define PG8_WAIT_V(n) asm volatile("s_waitcnt vmcnt(" #n ")" ::: "memory")
; #define PG8_WAIT_L(n) asm volatile("s_waitcnt lgkmcnt(" #n ")" ::: "memory")
; #define PG8_BAR __builtin_amdgcn_s_barrier()
; #define PG8_SCHED __builtin_amdgcn_sched_barrier(0)
; template <class Epi, class Sched, bool ALIGN_EPI = false, bool SP2 = false, bool DUAL = false>
; __device__ __forceinline__ void gemm_phase(PG8_LAS unsigned char* lds, const Gemm g, const Sched& S, const Epi& E) {
;     ...
;             PG8_WAIT_V(8); PG8_WAIT_L(0); PG8_BAR; PG8_MMA(0, 0, At, B0); PG8_MMA(0, 1, At, B1); PG8_BAR; PG8_SCHED;
;             PG8_LDA(At, 0, 1); PG8_STAGE(PG8_SB(0, 0), b2, voffB); PG8_STAGE(PG8_SB(0, 1), b2 + hstep, voffB); PG8_STAGE(PG8_SA(0, 0), a2, voffA);
;             PG8_WAIT_V(8); PG8_WAIT_L(0); PG8_BAR; PG8_MMA(1, 0, At, B0); PG8_MMA(1, 1, At, B1); PG8_BAR; PG8_SCHED;
	v_mfma_f32_16x16x32_bf16 v[140:143], v[80:83], v[208:211], v[140:143]
	v_mfma_f32_16x16x32_bf16 v[132:135], v[88:91], v[208:211], v[132:135]
	v_mfma_f32_16x16x32_bf16 v[124:127], v[80:83], v[216:219], v[124:127]
	v_mfma_f32_16x16x32_bf16 v[120:123], v[88:91], v[216:219], v[120:123]
	v_mfma_f32_16x16x32_bf16 v[108:111], v[80:83], v[232:235], v[108:111]
	v_mfma_f32_16x16x32_bf16 v[104:107], v[88:91], v[232:235], v[104:107]
	v_mfma_f32_16x16x32_bf16 v[76:79], v[80:83], v[240:243], v[76:79]
	v_mfma_f32_16x16x32_bf16 v[72:75], v[88:91], v[240:243], v[72:75]
	v_mfma_f32_16x16x32_bf16 v[140:143], v[84:87], v[212:215], v[140:143]
	v_mfma_f32_16x16x32_bf16 v[132:135], v[92:95], v[212:215], v[132:135]
	v_mfma_f32_16x16x32_bf16 v[124:127], v[84:87], v[220:223], v[124:127]
	v_mfma_f32_16x16x32_bf16 v[120:123], v[92:95], v[220:223], v[120:123]
	v_mfma_f32_16x16x32_bf16 v[108:111], v[84:87], v[236:239], v[108:111]
	v_mfma_f32_16x16x32_bf16 v[104:107], v[92:95], v[236:239], v[104:107]
	v_mfma_f32_16x16x32_bf16 v[76:79], v[84:87], v[244:247], v[76:79]
	v_mfma_f32_16x16x32_bf16 v[72:75], v[92:95], v[244:247], v[72:75]
	s_setprio 0
	s_setprio 1
	v_mfma_f32_16x16x32_bf16 v[136:139], v[144:147], v[208:211], v[136:139]
	v_mfma_f32_16x16x32_bf16 v[128:131], v[152:155], v[208:211], v[128:131]
	v_mfma_f32_16x16x32_bf16 v[116:119], v[144:147], v[216:219], v[116:119]
	v_mfma_f32_16x16x32_bf16 v[112:115], v[152:155], v[216:219], v[112:115]
	v_mfma_f32_16x16x32_bf16 v[100:103], v[144:147], v[232:235], v[100:103]
	v_mfma_f32_16x16x32_bf16 v[96:99], v[152:155], v[232:235], v[96:99]
	v_mfma_f32_16x16x32_bf16 v[68:71], v[144:147], v[240:243], v[68:71]
	v_mfma_f32_16x16x32_bf16 v[64:67], v[152:155], v[240:243], v[64:67]
	v_mfma_f32_16x16x32_bf16 v[136:139], v[148:151], v[212:215], v[136:139]
	v_mfma_f32_16x16x32_bf16 v[128:131], v[156:159], v[212:215], v[128:131]
	v_mfma_f32_16x16x32_bf16 v[116:119], v[148:151], v[220:223], v[116:119]
	v_mfma_f32_16x16x32_bf16 v[112:115], v[156:159], v[220:223], v[112:115]
	v_mfma_f32_16x16x32_bf16 v[100:103], v[148:151], v[236:239], v[100:103]
	v_mfma_f32_16x16x32_bf16 v[96:99], v[156:159], v[236:239], v[96:99]
	v_mfma_f32_16x16x32_bf16 v[68:71], v[148:151], v[244:247], v[68:71]
	v_mfma_f32_16x16x32_bf16 v[64:67], v[156:159], v[244:247], v[64:67]
	s_barrier
	s_setprio 0
	s_add_i32 s49, s31, s18
	v_lshl_add_u64 v[192:193], s[14:15], 0, v[166:167]
	s_mov_b32 m0, s49
	ds_read_b128 v[208:211], v203 offset:16384
	ds_read_b128 v[212:215], v203 offset:17408
	ds_read_b128 v[216:219], v203 offset:18432
	ds_read_b128 v[220:223], v203 offset:19456
	ds_read_b128 v[232:235], v203 offset:20480
	ds_read_b128 v[236:239], v203 offset:21504
	ds_read_b128 v[240:243], v203 offset:22528
	ds_read_b128 v[244:247], v203 offset:23552
	global_load_lds_dwordx4 v[192:193], off
	s_add_i32 m0, s49, 0x2000
	s_add_u32 s50, s14, 0x80000
	v_lshl_add_u64 v[248:249], s[14:15], 0, v[170:171]
	s_addc_u32 s51, s15, 0
	s_add_i32 s49, s34, s18
	global_load_lds_dwordx4 v[248:249], off
	v_lshl_add_u64 v[250:251], s[50:51], 0, v[166:167]
	s_mov_b32 m0, s49
	v_lshl_add_u64 v[252:253], s[16:17], 0, v[168:169]
	global_load_lds_dwordx4 v[250:251], off
	v_lshl_add_u64 v[250:251], s[50:51], 0, v[170:171]
	s_add_i32 m0, s49, 0x2000
	s_nop 0
	global_load_lds_dwordx4 v[250:251], off
	v_lshl_add_u64 v[250:251], s[16:17], 0, v[164:165]
	s_mov_b32 m0, s19
	s_nop 0
	global_load_lds_dwordx4 v[250:251], off
	s_mov_b32 m0, s20
	s_nop 0
	global_load_lds_dwordx4 v[252:253], off
	s_waitcnt vmcnt(8)
	s_waitcnt lgkmcnt(0)
	s_setprio 1
	s_barrier
	v_mfma_f32_16x16x32_bf16 v[60:63], v[80:83], v[208:211], v[60:63]
	v_mfma_f32_16x16x32_bf16 v[56:59], v[88:91], v[208:211], v[56:59]
	v_mfma_f32_16x16x32_bf16 v[44:47], v[80:83], v[216:219], v[44:47]
	v_mfma_f32_16x16x32_bf16 v[40:43], v[88:91], v[216:219], v[40:43]
	v_mfma_f32_16x16x32_bf16 v[28:31], v[80:83], v[232:235], v[28:31]
	v_mfma_f32_16x16x32_bf16 v[24:27], v[88:91], v[232:235], v[24:27]
	v_mfma_f32_16x16x32_bf16 v[12:15], v[80:83], v[240:243], v[12:15]
	v_mfma_f32_16x16x32_bf16 v[8:11], v[88:91], v[240:243], v[8:11]
	v_mfma_f32_16x16x32_bf16 v[60:63], v[84:87], v[212:215], v[60:63]
	v_mfma_f32_16x16x32_bf16 v[56:59], v[92:95], v[212:215], v[56:59]
	v_mfma_f32_16x16x32_bf16 v[44:47], v[84:87], v[220:223], v[44:47]
	v_mfma_f32_16x16x32_bf16 v[40:43], v[92:95], v[220:223], v[40:43]
	v_mfma_f32_16x16x32_bf16 v[28:31], v[84:87], v[236:239], v[28:31]
	v_mfma_f32_16x16x32_bf16 v[24:27], v[92:95], v[236:239], v[24:27]
	v_mfma_f32_16x16x32_bf16 v[12:15], v[84:87], v[244:247], v[12:15]
	v_mfma_f32_16x16x32_bf16 v[8:11], v[92:95], v[244:247], v[8:11]
	s_setprio 0
	s_setprio 1
	v_mfma_f32_16x16x32_bf16 v[52:55], v[144:147], v[208:211], v[52:55]
	v_mfma_f32_16x16x32_bf16 v[48:51], v[152:155], v[208:211], v[48:51]
	v_mfma_f32_16x16x32_bf16 v[36:39], v[144:147], v[216:219], v[36:39]
	v_mfma_f32_16x16x32_bf16 v[32:35], v[152:155], v[216:219], v[32:35]
	v_mfma_f32_16x16x32_bf16 v[20:23], v[144:147], v[232:235], v[20:23]
	v_mfma_f32_16x16x32_bf16 v[16:19], v[152:155], v[232:235], v[16:19]
	v_mfma_f32_16x16x32_bf16 v[4:7], v[144:147], v[240:243], v[4:7]
	v_mfma_f32_16x16x32_bf16 v[0:3], v[152:155], v[240:243], v[0:3]
	v_mfma_f32_16x16x32_bf16 v[52:55], v[148:151], v[212:215], v[52:55]
	v_mfma_f32_16x16x32_bf16 v[48:51], v[156:159], v[212:215], v[48:51]
	v_mfma_f32_16x16x32_bf16 v[36:39], v[148:151], v[220:223], v[36:39]
	v_mfma_f32_16x16x32_bf16 v[32:35], v[156:159], v[220:223], v[32:35]
	v_mfma_f32_16x16x32_bf16 v[20:23], v[148:151], v[236:239], v[20:23]
	v_mfma_f32_16x16x32_bf16 v[16:19], v[156:159], v[236:239], v[16:19]
	v_mfma_f32_16x16x32_bf16 v[4:7], v[148:151], v[244:247], v[4:7]
	v_mfma_f32_16x16x32_bf16 v[0:3], v[156:159], v[244:247], v[0:3]
	s_barrier
; #define PG8_STAGE(bufoff, gbase, voff) do { _Pragma("unroll") for (int _i = 0; _i < 2; ++_i) \
;         __builtin_amdgcn_global_load_lds((const unsigned*)((const char*)(gbase) + (voff)[_i]), (PG8_LAS unsigned*)(lds + (bufoff) + ldsw + _i * 8192), 16, 0, 0); } while (0)
; #define PG8_LDA(dst, b, h) do { _Pragma("unroll") for (int m = 0; m < 4; ++m) _Pragma("unroll") for (int k = 0; k < 2; ++k) dst[m][k] = *(const PG8_LAS bf16x8*)(lds + PG8_SA(b, h) + aoff + m * 2048 + k * 1024); } while (0)
; #define PG8_LDB(dst, b, h) do { _Pragma("unroll") for (int n = 0; n < 2; ++n) _Pragma("unroll") for (int k = 0; k < 2; ++k) dst[n][k] = *(const PG8_LAS bf16x8*)(lds + PG8_SB(b, h) + boff + n * 2048 + k * 1024); } while (0)
; #define PG8_MMA(ai, bj, At, Bt) do { __builtin_amdgcn_s_setprio(1); _Pragma("unroll") for (int m = 0; m < 4; ++m) _Pragma("unroll") for (int n = 0; n < 2; ++n) _Pragma("unroll") for (int k = 0; k < 2; ++k) \
;         acc[ai][bj][m][n] = __builtin_amdgcn_mfma_f32_16x16x32_bf16(Bt[n][k], At[m][k], acc[ai][bj][m][n], 0, 0, 0); __builtin_amdgcn_s_setprio(0); } while (0)
; #define PG8_WAIT_V(n) asm volatile("s_waitcnt vmcnt(" #n ")" ::: "memory")
; #define PG8_WAIT_L(n) asm volatile("s_waitcnt lgkmcnt(" #n ")" ::: "memory")
; #define PG8_BAR __builtin_amdgcn_s_barrier()
; #define PG8_SCHED __builtin_amdgcn_sched_barrier(0)
; template <class Epi, class Sched, bool ALIGN_EPI = false, bool SP2 = false, bool DUAL = false>
; __device__ __forceinline__ void gemm_phase(PG8_LAS unsigned char* lds, const Gemm g, const Sched& S, const Epi& E) {
;     ...
;             PG8_LDB(B0, 1, 0); PG8_LDB(B1, 1, 1); PG8_SCHED; PG8_LDA(At, 1, 0); PG8_STAGE(PG8_SA(0, 1), a2 + hstep, voffA);
;             PG8_WAIT_V(8); PG8_WAIT_L(0); PG8_BAR; PG8_MMA(0, 0, At, B0); PG8_MMA(0, 1, At, B1); PG8_BAR; PG8_SCHED;
	s_setprio 0
	s_add_i32 s49, 0, 0x18000
	s_add_i32 s50, 0, 0x1c000
	v_add_u32_e32 v92, s49, v196
	v_add_u32_e32 v156, s50, v196
	ds_read_b128 v[80:83], v92
	ds_read_b128 v[84:87], v92 offset:1024
	ds_read_b128 v[88:91], v92 offset:2048
	ds_read_b128 v[92:95], v92 offset:3072
	ds_read_b128 v[144:147], v156
	ds_read_b128 v[148:151], v156 offset:1024
	ds_read_b128 v[152:155], v156 offset:2048
	ds_read_b128 v[156:159], v156 offset:3072
	s_add_u32 s16, s16, 0x80000
	s_addc_u32 s17, s17, 0
	s_mov_b32 m0, s21
	v_lshl_add_u64 v[228:229], s[16:17], 0, v[164:165]
	ds_read_b128 v[208:211], v203 offset:32768
	ds_read_b128 v[212:215], v203 offset:33792
	ds_read_b128 v[216:219], v203 offset:34816
	ds_read_b128 v[220:223], v203 offset:35840
	ds_read_b128 v[232:235], v203 offset:36864
	ds_read_b128 v[236:239], v203 offset:37888
	ds_read_b128 v[240:243], v203 offset:38912
	ds_read_b128 v[244:247], v203 offset:39936
	global_load_lds_dwordx4 v[228:229], off
	v_lshl_add_u64 v[228:229], s[16:17], 0, v[168:169]
	s_mov_b32 m0, s22
	s_nop 0
	global_load_lds_dwordx4 v[228:229], off
	s_waitcnt vmcnt(8)
	s_waitcnt lgkmcnt(0)
	s_setprio 1
	s_barrier
	v_mfma_f32_16x16x32_bf16 v[140:143], v[80:83], v[208:211], v[140:143]
	v_mfma_f32_16x16x32_bf16 v[132:135], v[88:91], v[208:211], v[132:135]
	v_mfma_f32_16x16x32_bf16 v[124:127], v[80:83], v[216:219], v[124:127]
	v_mfma_f32_16x16x32_bf16 v[120:123], v[88:91], v[216:219], v[120:123]
	v_mfma_f32_16x16x32_bf16 v[108:111], v[80:83], v[232:235], v[108:111]
	v_mfma_f32_16x16x32_bf16 v[104:107], v[88:91], v[232:235], v[104:107]
	v_mfma_f32_16x16x32_bf16 v[76:79], v[80:83], v[240:243], v[76:79]
	v_mfma_f32_16x16x32_bf16 v[72:75], v[88:91], v[240:243], v[72:75]
	v_mfma_f32_16x16x32_bf16 v[140:143], v[84:87], v[212:215], v[140:143]
	v_mfma_f32_16x16x32_bf16 v[132:135], v[92:95], v[212:215], v[132:135]
	v_mfma_f32_16x16x32_bf16 v[124:127], v[84:87], v[220:223], v[124:127]
	v_mfma_f32_16x16x32_bf16 v[120:123], v[92:95], v[220:223], v[120:123]
	v_mfma_f32_16x16x32_bf16 v[108:111], v[84:87], v[236:239], v[108:111]
	v_mfma_f32_16x16x32_bf16 v[104:107], v[92:95], v[236:239], v[104:107]
	v_mfma_f32_16x16x32_bf16 v[76:79], v[84:87], v[244:247], v[76:79]
	v_mfma_f32_16x16x32_bf16 v[72:75], v[92:95], v[244:247], v[72:75]
	s_setprio 0
	s_setprio 1
	v_mfma_f32_16x16x32_bf16 v[136:139], v[144:147], v[208:211], v[136:139]
	v_mfma_f32_16x16x32_bf16 v[128:131], v[152:155], v[208:211], v[128:131]
	v_mfma_f32_16x16x32_bf16 v[116:119], v[144:147], v[216:219], v[116:119]
	v_mfma_f32_16x16x32_bf16 v[112:115], v[152:155], v[216:219], v[112:115]
	v_mfma_f32_16x16x32_bf16 v[100:103], v[144:147], v[232:235], v[100:103]
	v_mfma_f32_16x16x32_bf16 v[96:99], v[152:155], v[232:235], v[96:99]
	v_mfma_f32_16x16x32_bf16 v[68:71], v[144:147], v[240:243], v[68:71]
	v_mfma_f32_16x16x32_bf16 v[64:67], v[152:155], v[240:243], v[64:67]
	v_mfma_f32_16x16x32_bf16 v[136:139], v[148:151], v[212:215], v[136:139]
	v_mfma_f32_16x16x32_bf16 v[128:131], v[156:159], v[212:215], v[128:131]
	v_mfma_f32_16x16x32_bf16 v[116:119], v[148:151], v[220:223], v[116:119]
	v_mfma_f32_16x16x32_bf16 v[112:115], v[156:159], v[220:223], v[112:115]
	v_mfma_f32_16x16x32_bf16 v[100:103], v[148:151], v[236:239], v[100:103]
	v_mfma_f32_16x16x32_bf16 v[96:99], v[156:159], v[236:239], v[96:99]
	v_mfma_f32_16x16x32_bf16 v[68:71], v[148:151], v[244:247], v[68:71]
	v_mfma_f32_16x16x32_bf16 v[64:67], v[156:159], v[244:247], v[64:67]
	s_barrier
; #define PG8_STAGE(bufoff, gbase, voff) do { _Pragma("unroll") for (int _i = 0; _i < 2; ++_i) \
;         __builtin_amdgcn_global_load_lds((const unsigned*)((const char*)(gbase) + (voff)[_i]), (PG8_LAS unsigned*)(lds + (bufoff) + ldsw + _i * 8192), 16, 0, 0); } while (0)
; #define PG8_LDA(dst, b, h) do { _Pragma("unroll") for (int m = 0; m < 4; ++m) _Pragma("unroll") for (int k = 0; k < 2; ++k) dst[m][k] = *(const PG8_LAS bf16x8*)(lds + PG8_SA(b, h) + aoff + m * 2048 + k * 1024); } while (0)
; #define PG8_MMA(ai, bj, At, Bt) do { __builtin_amdgcn_s_setprio(1); _Pragma("unroll") for (int m = 0; m < 4; ++m) _Pragma("unroll") for (int n = 0; n < 2; ++n) _Pragma("unroll") for (int k = 0; k < 2; ++k) \
;         acc[ai][bj][m][n] = __builtin_amdgcn_mfma_f32_16x16x32_bf16(Bt[n][k], At[m][k], acc[ai][bj][m][n], 0, 0, 0); __builtin_amdgcn_s_setprio(0); } while (0)
; #define PG8_WAIT_V(n) asm volatile("s_waitcnt vmcnt(" #n ")" ::: "memory")
; #define PG8_WAIT_L(n) asm volatile("s_waitcnt lgkmcnt(" #n ")" ::: "memory")
; #define PG8_BAR __builtin_amdgcn_s_barrier()
; #define PG8_SCHED __builtin_amdgcn_sched_barrier(0)
; template <class Epi, class Sched, bool ALIGN_EPI = false, bool SP2 = false, bool DUAL = false>
; __device__ __forceinline__ void gemm_phase(PG8_LAS unsigned char* lds, const Gemm g, const Sched& S, const Epi& E) {
;     ...
;             PG8_LDA(At, 1, 1); PG8_STAGE(PG8_SB(1, 0), b3, voffB); PG8_STAGE(PG8_SB(1, 1), b3 + hstep, voffB); PG8_STAGE(PG8_SA(1, 0), a3, voffA);
;             PG8_WAIT_V(8); PG8_WAIT_L(0); PG8_BAR; PG8_MMA(1, 0, At, B0); PG8_MMA(1, 1, At, B1); PG8_BAR; PG8_SCHED;
;     ...
;         if constexpr (ALIGN_EPI) { if (wr == 0) PG8_BAR; }
	s_setprio 0
	s_add_i32 s16, s49, s18
	v_lshl_add_u64 v[192:193], v[192:193], 0, s[76:77]
	s_mov_b32 m0, s16
	ds_read_b128 v[208:211], v203 offset:49152
	ds_read_b128 v[212:215], v203 offset:50176
	ds_read_b128 v[216:219], v203 offset:51200
	ds_read_b128 v[220:223], v203 offset:52224
	ds_read_b128 v[232:235], v203 offset:53248
	ds_read_b128 v[236:239], v203 offset:54272
	ds_read_b128 v[240:243], v203 offset:55296
	ds_read_b128 v[244:247], v203 offset:56320
	global_load_lds_dwordx4 v[192:193], off
	s_add_i32 m0, s16, 0x2000
	s_add_u32 s14, s14, 0x80080
	v_lshl_add_u64 v[192:193], v[248:249], 0, s[76:77]
	s_addc_u32 s15, s15, 0
	s_add_i32 s16, s50, s18
	global_load_lds_dwordx4 v[192:193], off
	v_lshl_add_u64 v[192:193], s[14:15], 0, v[166:167]
	s_mov_b32 m0, s16
	s_nop 0
	global_load_lds_dwordx4 v[192:193], off
	v_lshl_add_u64 v[192:193], s[14:15], 0, v[170:171]
	s_add_i32 m0, s16, 0x2000
	s_nop 0
	global_load_lds_dwordx4 v[192:193], off
	v_lshl_add_u64 v[192:193], v[250:251], 0, s[76:77]
	s_mov_b32 m0, s27
	s_nop 0
	global_load_lds_dwordx4 v[192:193], off
	v_lshl_add_u64 v[192:193], v[252:253], 0, s[76:77]
	s_mov_b32 m0, s28
	s_nop 0
	global_load_lds_dwordx4 v[192:193], off
	s_waitcnt vmcnt(8)
	s_waitcnt lgkmcnt(0)
	s_setprio 1
	s_barrier
	v_mfma_f32_16x16x32_bf16 v[60:63], v[80:83], v[208:211], v[60:63]
	v_mfma_f32_16x16x32_bf16 v[56:59], v[88:91], v[208:211], v[56:59]
	v_mfma_f32_16x16x32_bf16 v[44:47], v[80:83], v[216:219], v[44:47]
	v_mfma_f32_16x16x32_bf16 v[40:43], v[88:91], v[216:219], v[40:43]
	v_mfma_f32_16x16x32_bf16 v[28:31], v[80:83], v[232:235], v[28:31]
	v_mfma_f32_16x16x32_bf16 v[24:27], v[88:91], v[232:235], v[24:27]
	v_mfma_f32_16x16x32_bf16 v[12:15], v[80:83], v[240:243], v[12:15]
	v_mfma_f32_16x16x32_bf16 v[8:11], v[88:91], v[240:243], v[8:11]
	v_mfma_f32_16x16x32_bf16 v[60:63], v[84:87], v[212:215], v[60:63]
	v_mfma_f32_16x16x32_bf16 v[56:59], v[92:95], v[212:215], v[56:59]
	v_mfma_f32_16x16x32_bf16 v[44:47], v[84:87], v[220:223], v[44:47]
	v_mfma_f32_16x16x32_bf16 v[40:43], v[92:95], v[220:223], v[40:43]
	v_mfma_f32_16x16x32_bf16 v[28:31], v[84:87], v[236:239], v[28:31]
	v_mfma_f32_16x16x32_bf16 v[24:27], v[92:95], v[236:239], v[24:27]
	v_mfma_f32_16x16x32_bf16 v[12:15], v[84:87], v[244:247], v[12:15]
	v_mfma_f32_16x16x32_bf16 v[8:11], v[92:95], v[244:247], v[8:11]
	s_setprio 0
	s_setprio 1
	v_mfma_f32_16x16x32_bf16 v[52:55], v[144:147], v[208:211], v[52:55]
	v_mfma_f32_16x16x32_bf16 v[48:51], v[152:155], v[208:211], v[48:51]
	v_mfma_f32_16x16x32_bf16 v[36:39], v[144:147], v[216:219], v[36:39]
	v_mfma_f32_16x16x32_bf16 v[32:35], v[152:155], v[216:219], v[32:35]
	v_mfma_f32_16x16x32_bf16 v[20:23], v[144:147], v[232:235], v[20:23]
	v_mfma_f32_16x16x32_bf16 v[16:19], v[152:155], v[232:235], v[16:19]
	v_mfma_f32_16x16x32_bf16 v[4:7], v[144:147], v[240:243], v[4:7]
	v_mfma_f32_16x16x32_bf16 v[0:3], v[152:155], v[240:243], v[0:3]
	v_mfma_f32_16x16x32_bf16 v[52:55], v[148:151], v[212:215], v[52:55]
	v_mfma_f32_16x16x32_bf16 v[48:51], v[156:159], v[212:215], v[48:51]
	v_mfma_f32_16x16x32_bf16 v[36:39], v[148:151], v[220:223], v[36:39]
	v_mfma_f32_16x16x32_bf16 v[32:35], v[156:159], v[220:223], v[32:35]
	v_mfma_f32_16x16x32_bf16 v[20:23], v[148:151], v[236:239], v[20:23]
	v_mfma_f32_16x16x32_bf16 v[16:19], v[156:159], v[236:239], v[16:19]
	v_mfma_f32_16x16x32_bf16 v[4:7], v[148:151], v[244:247], v[4:7]
	v_mfma_f32_16x16x32_bf16 v[0:3], v[156:159], v[244:247], v[0:3]
	s_barrier
	s_setprio 0
	s_add_i32 s48, s48, 2
	s_add_u32 s10, s10, 0x100
	s_addc_u32 s11, s11, 0
	s_add_u32 s46, s46, 0x100
	s_addc_u32 s47, s47, 0
	s_cmp_gt_u32 s48, 29
	s_cbranch_scc0 .LBB0_252
	s_and_b64 vcc, exec, s[38:39]
	s_cbranch_vccz .LBB0_255
	s_barrier

; #define PG8_STAGE(bufoff, gbase, voff) do { _Pragma("unroll") for (int _i = 0; _i < 2; ++_i) \
;         __builtin_amdgcn_global_load_lds((const unsigned*)((const char*)(gbase) + (voff)[_i]), (PG8_LAS unsigned*)(lds + (bufoff) + ldsw + _i * 8192), 16, 0, 0); } while (0)
; #define PG8_LDA(dst, b, h) do { _Pragma("unroll") for (int m = 0; m < 4; ++m) _Pragma("unroll") for (int k = 0; k < 2; ++k) dst[m][k] = *(const PG8_LAS bf16x8*)(lds + PG8_SA(b, h) + aoff + m * 2048 + k * 1024); } while (0)
; #define PG8_LDB(dst, b, h) do { _Pragma("unroll") for (int n = 0; n < 2; ++n) _Pragma("unroll") for (int k = 0; k < 2; ++k) dst[n][k] = *(const PG8_LAS bf16x8*)(lds + PG8_SB(b, h) + boff + n * 2048 + k * 1024); } while (0)
; #define PG8_MMA(ai, bj, At, Bt) do { __builtin_amdgcn_s_setprio(1); _Pragma("unroll") for (int m = 0; m < 4; ++m) _Pragma("unroll") for (int n = 0; n < 2; ++n) _Pragma("unroll") for (int k = 0; k < 2; ++k) \
;         acc[ai][bj][m][n] = __builtin_amdgcn_mfma_f32_16x16x32_bf16(Bt[n][k], At[m][k], acc[ai][bj][m][n], 0, 0, 0); __builtin_amdgcn_s_setprio(0); } while (0)
; #define PG8_WAIT_V(n) asm volatile("s_waitcnt vmcnt(" #n ")" ::: "memory")
; #define PG8_WAIT_L(n) asm volatile("s_waitcnt lgkmcnt(" #n ")" ::: "memory")
; #define PG8_BAR __builtin_amdgcn_s_barrier()
; #define PG8_SCHED __builtin_amdgcn_sched_barrier(0)
; template <class Epi, class Sched, bool ALIGN_EPI = false, bool SP2 = false, bool DUAL = false>
; __device__ __forceinline__ void gemm_phase(PG8_LAS unsigned char* lds, const Gemm g, const Sched& S, const Epi& E) {
;     ...
;             PG8_LDB(B0, 0, 0); PG8_LDB(B1, 0, 1); PG8_SCHED; PG8_LDA(At, 0, 0); PG8_STAGE(PG8_SA(1, 1), a1 + hstep, voffA);
;             PG8_WAIT_V(8); PG8_WAIT_L(0); PG8_BAR; PG8_MMA(0, 0, At, B0); PG8_MMA(0, 1, At, B1); PG8_BAR; PG8_SCHED;
;             PG8_LDA(At, 0, 1); PG8_STAGE(PG8_SB(0, 0), b2, voffB); PG8_STAGE(PG8_SB(0, 1), b2 + hstep, voffB); PG8_STAGE(PG8_SA(0, 0), a2, voffA);
;             PG8_WAIT_V(8); PG8_WAIT_L(0); PG8_BAR; PG8_MMA(1, 0, At, B0); PG8_MMA(1, 1, At, B1); PG8_BAR; PG8_SCHED;
.LBB0_805:
	v_add_u32_e32 v1, s44, v235
	ds_read_b128 v[132:135], v1
	ds_read_b128 v[136:139], v1 offset:1024
	ds_read_b128 v[140:143], v1 offset:2048
	ds_read_b128 v[144:147], v1 offset:3072
	v_add_u32_e32 v1, s45, v235
	ds_read_b128 v[148:151], v1
	ds_read_b128 v[152:155], v1 offset:1024
	ds_read_b128 v[156:159], v1 offset:2048
	ds_read_b128 v[160:163], v1 offset:3072
	s_add_u32 s16, s14, 0xfff80080
	s_addc_u32 s17, s15, -1
	s_cmp_eq_u32 s75, 28
	s_cselect_b32 s19, s50, s17
	s_cselect_b32 s18, s51, s16
	s_cselect_b32 s17, s65, s73
	s_cselect_b32 s16, s67, s72
	v_lshl_add_u64 v[2:3], s[14:15], 0, v[192:193]
	s_add_i32 m0, s28, 0xc000
	ds_read_b128 v[164:167], v237
	ds_read_b128 v[168:171], v237 offset:1024
	ds_read_b128 v[172:175], v237 offset:2048
	ds_read_b128 v[176:179], v237 offset:3072
	ds_read_b128 v[180:183], v237 offset:4096
	ds_read_b128 v[202:205], v237 offset:5120
	ds_read_b128 v[206:209], v237 offset:6144
	ds_read_b128 v[210:213], v237 offset:7168
	global_load_lds_dwordx4 v[2:3], off
	v_lshl_add_u64 v[2:3], s[14:15], 0, v[194:195]
	s_add_i32 m0, s28, 0xe000
	s_nop 0
	global_load_lds_dwordx4 v[2:3], off
	s_waitcnt vmcnt(8)
	s_waitcnt lgkmcnt(0)
	s_setprio 1
	s_barrier
	v_mfma_f32_16x16x32_bf16 v[128:131], v[132:135], v[164:167], v[128:131]
	v_mfma_f32_16x16x32_bf16 v[124:127], v[140:143], v[164:167], v[124:127]
	v_mfma_f32_16x16x32_bf16 v[120:123], v[132:135], v[172:175], v[120:123]
	v_mfma_f32_16x16x32_bf16 v[116:119], v[140:143], v[172:175], v[116:119]
	v_mfma_f32_16x16x32_bf16 v[112:115], v[132:135], v[180:183], v[112:115]
	v_mfma_f32_16x16x32_bf16 v[108:111], v[140:143], v[180:183], v[108:111]
	v_mfma_f32_16x16x32_bf16 v[104:107], v[132:135], v[206:209], v[104:107]
	v_mfma_f32_16x16x32_bf16 v[100:103], v[140:143], v[206:209], v[100:103]
	v_mfma_f32_16x16x32_bf16 v[128:131], v[136:139], v[168:171], v[128:131]
	v_mfma_f32_16x16x32_bf16 v[124:127], v[144:147], v[168:171], v[124:127]
	v_mfma_f32_16x16x32_bf16 v[120:123], v[136:139], v[176:179], v[120:123]
	v_mfma_f32_16x16x32_bf16 v[116:119], v[144:147], v[176:179], v[116:119]
	v_mfma_f32_16x16x32_bf16 v[112:115], v[136:139], v[202:205], v[112:115]
	v_mfma_f32_16x16x32_bf16 v[108:111], v[144:147], v[202:205], v[108:111]
	v_mfma_f32_16x16x32_bf16 v[104:107], v[136:139], v[210:213], v[104:107]
	v_mfma_f32_16x16x32_bf16 v[100:103], v[144:147], v[210:213], v[100:103]
	s_setprio 0
	s_setprio 1
	v_mfma_f32_16x16x32_bf16 v[96:99], v[148:151], v[164:167], v[96:99]
	v_mfma_f32_16x16x32_bf16 v[92:95], v[156:159], v[164:167], v[92:95]
	v_mfma_f32_16x16x32_bf16 v[88:91], v[148:151], v[172:175], v[88:91]
	v_mfma_f32_16x16x32_bf16 v[84:87], v[156:159], v[172:175], v[84:87]
	v_mfma_f32_16x16x32_bf16 v[80:83], v[148:151], v[180:183], v[80:83]
	v_mfma_f32_16x16x32_bf16 v[76:79], v[156:159], v[180:183], v[76:79]
	v_mfma_f32_16x16x32_bf16 v[72:75], v[148:151], v[206:209], v[72:75]
	v_mfma_f32_16x16x32_bf16 v[68:71], v[156:159], v[206:209], v[68:71]
	v_mfma_f32_16x16x32_bf16 v[96:99], v[152:155], v[168:171], v[96:99]
	v_mfma_f32_16x16x32_bf16 v[92:95], v[160:163], v[168:171], v[92:95]
	v_mfma_f32_16x16x32_bf16 v[88:91], v[152:155], v[176:179], v[88:91]
	v_mfma_f32_16x16x32_bf16 v[84:87], v[160:163], v[176:179], v[84:87]
	v_mfma_f32_16x16x32_bf16 v[80:83], v[152:155], v[202:205], v[80:83]
	v_mfma_f32_16x16x32_bf16 v[76:79], v[160:163], v[202:205], v[76:79]
	v_mfma_f32_16x16x32_bf16 v[72:75], v[152:155], v[210:213], v[72:75]
	v_mfma_f32_16x16x32_bf16 v[68:71], v[160:163], v[210:213], v[68:71]
	s_barrier
	s_setprio 0
	s_add_i32 s76, s44, s27
	v_lshl_add_u64 v[214:215], s[16:17], 0, v[186:187]
	s_mov_b32 m0, s76
	ds_read_b128 v[164:167], v237 offset:16384
	ds_read_b128 v[168:171], v237 offset:17408
	ds_read_b128 v[172:175], v237 offset:18432
	ds_read_b128 v[176:179], v237 offset:19456
	ds_read_b128 v[180:183], v237 offset:20480
	ds_read_b128 v[202:205], v237 offset:21504
	ds_read_b128 v[206:209], v237 offset:22528
	ds_read_b128 v[210:213], v237 offset:23552
	global_load_lds_dwordx4 v[214:215], off
	s_add_i32 m0, s76, 0x2000
	s_add_u32 s76, s16, 0x80000
	v_lshl_add_u64 v[216:217], s[16:17], 0, v[190:191]
	s_addc_u32 s77, s17, 0
	s_add_i32 s78, s45, s27
	global_load_lds_dwordx4 v[216:217], off
	v_lshl_add_u64 v[2:3], s[76:77], 0, v[186:187]
	s_mov_b32 m0, s78
	v_lshl_add_u64 v[218:219], s[18:19], 0, v[184:185]
	global_load_lds_dwordx4 v[2:3], off
	v_lshl_add_u64 v[2:3], s[76:77], 0, v[190:191]
	s_add_i32 m0, s78, 0x2000
	v_lshl_add_u64 v[220:221], s[18:19], 0, v[188:189]
	global_load_lds_dwordx4 v[2:3], off
	s_mov_b32 m0, s28
	s_nop 0
	global_load_lds_dwordx4 v[218:219], off
	s_mov_b32 m0, s29
	s_nop 0
	global_load_lds_dwordx4 v[220:221], off
	s_waitcnt vmcnt(8)
	s_waitcnt lgkmcnt(0)
	s_setprio 1
	s_barrier
; #define PG8_STAGE(bufoff, gbase, voff) do { _Pragma("unroll") for (int _i = 0; _i < 2; ++_i) \
;         __builtin_amdgcn_global_load_lds((const unsigned*)((const char*)(gbase) + (voff)[_i]), (PG8_LAS unsigned*)(lds + (bufoff) + ldsw + _i * 8192), 16, 0, 0); } while (0)
; #define PG8_LDA(dst, b, h) do { _Pragma("unroll") for (int m = 0; m < 4; ++m) _Pragma("unroll") for (int k = 0; k < 2; ++k) dst[m][k] = *(const PG8_LAS bf16x8*)(lds + PG8_SA(b, h) + aoff + m * 2048 + k * 1024); } while (0)
; #define PG8_LDB(dst, b, h) do { _Pragma("unroll") for (int n = 0; n < 2; ++n) _Pragma("unroll") for (int k = 0; k < 2; ++k) dst[n][k] = *(const PG8_LAS bf16x8*)(lds + PG8_SB(b, h) + boff + n * 2048 + k * 1024); } while (0)
; #define PG8_MMA(ai, bj, At, Bt) do { __builtin_amdgcn_s_setprio(1); _Pragma("unroll") for (int m = 0; m < 4; ++m) _Pragma("unroll") for (int n = 0; n < 2; ++n) _Pragma("unroll") for (int k = 0; k < 2; ++k) \
;         acc[ai][bj][m][n] = __builtin_amdgcn_mfma_f32_16x16x32_bf16(Bt[n][k], At[m][k], acc[ai][bj][m][n], 0, 0, 0); __builtin_amdgcn_s_setprio(0); } while (0)
; #define PG8_WAIT_V(n) asm volatile("s_waitcnt vmcnt(" #n ")" ::: "memory")
; #define PG8_WAIT_L(n) asm volatile("s_waitcnt lgkmcnt(" #n ")" ::: "memory")
; #define PG8_BAR __builtin_amdgcn_s_barrier()
; #define PG8_SCHED __builtin_amdgcn_sched_barrier(0)
; template <class Epi, class Sched, bool ALIGN_EPI = false, bool SP2 = false, bool DUAL = false>
; __device__ __forceinline__ void gemm_phase(PG8_LAS unsigned char* lds, const Gemm g, const Sched& S, const Epi& E) {
;     ...
;             PG8_WAIT_V(8); PG8_WAIT_L(0); PG8_BAR; PG8_MMA(1, 0, At, B0); PG8_MMA(1, 1, At, B1); PG8_BAR; PG8_SCHED;
;             PG8_LDB(B0, 1, 0); PG8_LDB(B1, 1, 1); PG8_SCHED; PG8_LDA(At, 1, 0); PG8_STAGE(PG8_SA(0, 1), a2 + hstep, voffA);
;             PG8_WAIT_V(8); PG8_WAIT_L(0); PG8_BAR; PG8_MMA(0, 0, At, B0); PG8_MMA(0, 1, At, B1); PG8_BAR; PG8_SCHED;
	v_mfma_f32_16x16x32_bf16 v[64:67], v[132:135], v[164:167], v[64:67]
	v_mfma_f32_16x16x32_bf16 v[60:63], v[140:143], v[164:167], v[60:63]
	v_mfma_f32_16x16x32_bf16 v[56:59], v[132:135], v[172:175], v[56:59]
	v_mfma_f32_16x16x32_bf16 v[52:55], v[140:143], v[172:175], v[52:55]
	v_mfma_f32_16x16x32_bf16 v[48:51], v[132:135], v[180:183], v[48:51]
	v_mfma_f32_16x16x32_bf16 v[44:47], v[140:143], v[180:183], v[44:47]
	v_mfma_f32_16x16x32_bf16 v[40:43], v[132:135], v[206:209], v[40:43]
	v_mfma_f32_16x16x32_bf16 v[36:39], v[140:143], v[206:209], v[36:39]
	v_mfma_f32_16x16x32_bf16 v[64:67], v[136:139], v[168:171], v[64:67]
	v_mfma_f32_16x16x32_bf16 v[60:63], v[144:147], v[168:171], v[60:63]
	v_mfma_f32_16x16x32_bf16 v[56:59], v[136:139], v[176:179], v[56:59]
	v_mfma_f32_16x16x32_bf16 v[52:55], v[144:147], v[176:179], v[52:55]
	v_mfma_f32_16x16x32_bf16 v[48:51], v[136:139], v[202:205], v[48:51]
	v_mfma_f32_16x16x32_bf16 v[44:47], v[144:147], v[202:205], v[44:47]
	v_mfma_f32_16x16x32_bf16 v[40:43], v[136:139], v[210:213], v[40:43]
	v_mfma_f32_16x16x32_bf16 v[36:39], v[144:147], v[210:213], v[36:39]
	s_setprio 0
	s_setprio 1
	v_mfma_f32_16x16x32_bf16 v[32:35], v[148:151], v[164:167], v[32:35]
	v_mfma_f32_16x16x32_bf16 v[28:31], v[156:159], v[164:167], v[28:31]
	v_mfma_f32_16x16x32_bf16 v[24:27], v[148:151], v[172:175], v[24:27]
	v_mfma_f32_16x16x32_bf16 v[20:23], v[156:159], v[172:175], v[20:23]
	v_mfma_f32_16x16x32_bf16 v[16:19], v[148:151], v[180:183], v[16:19]
	v_mfma_f32_16x16x32_bf16 v[12:15], v[156:159], v[180:183], v[12:15]
	v_mfma_f32_16x16x32_bf16 v[8:11], v[148:151], v[206:209], v[8:11]
	v_mfma_f32_16x16x32_bf16 v[2:5], v[156:159], v[206:209], v[4:7]
	v_mfma_f32_16x16x32_bf16 v[32:35], v[152:155], v[168:171], v[32:35]
	v_mfma_f32_16x16x32_bf16 v[28:31], v[160:163], v[168:171], v[28:31]
	v_mfma_f32_16x16x32_bf16 v[24:27], v[152:155], v[176:179], v[24:27]
	v_mfma_f32_16x16x32_bf16 v[20:23], v[160:163], v[176:179], v[20:23]
	v_mfma_f32_16x16x32_bf16 v[16:19], v[152:155], v[202:205], v[16:19]
	v_mfma_f32_16x16x32_bf16 v[12:15], v[160:163], v[202:205], v[12:15]
	v_mfma_f32_16x16x32_bf16 v[8:11], v[152:155], v[210:213], v[8:11]
	v_mfma_f32_16x16x32_bf16 v[2:5], v[160:163], v[210:213], v[2:5]
	s_barrier
	s_setprio 0
	s_add_i32 s76, 0, 0x18000
	v_add_u32_e32 v1, s76, v235
	s_add_i32 s77, 0, 0x1c000
	ds_read_b128 v[132:135], v1
	ds_read_b128 v[136:139], v1 offset:1024
	ds_read_b128 v[140:143], v1 offset:2048
	ds_read_b128 v[144:147], v1 offset:3072
	v_add_u32_e32 v1, s77, v235
	ds_read_b128 v[148:151], v1
	ds_read_b128 v[152:155], v1 offset:1024
	ds_read_b128 v[156:159], v1 offset:2048
	ds_read_b128 v[160:163], v1 offset:3072
	s_add_u32 s18, s18, 0x80000
	s_addc_u32 s19, s19, 0
	s_mov_b32 m0, s34
	v_lshl_add_u64 v[6:7], s[18:19], 0, v[184:185]
	ds_read_b128 v[164:167], v237 offset:32768
	ds_read_b128 v[168:171], v237 offset:33792
	ds_read_b128 v[172:175], v237 offset:34816
	ds_read_b128 v[176:179], v237 offset:35840
	ds_read_b128 v[180:183], v237 offset:36864
	ds_read_b128 v[202:205], v237 offset:37888
	ds_read_b128 v[206:209], v237 offset:38912
	ds_read_b128 v[210:213], v237 offset:39936
	global_load_lds_dwordx4 v[6:7], off
	v_lshl_add_u64 v[6:7], s[18:19], 0, v[188:189]
	s_mov_b32 m0, s35
	s_nop 0
	global_load_lds_dwordx4 v[6:7], off
	s_waitcnt vmcnt(8)
	s_waitcnt lgkmcnt(0)
	s_setprio 1
	s_barrier
	v_mfma_f32_16x16x32_bf16 v[128:131], v[132:135], v[164:167], v[128:131]
	v_mfma_f32_16x16x32_bf16 v[124:127], v[140:143], v[164:167], v[124:127]
	v_mfma_f32_16x16x32_bf16 v[120:123], v[132:135], v[172:175], v[120:123]
	v_mfma_f32_16x16x32_bf16 v[116:119], v[140:143], v[172:175], v[116:119]
	v_mfma_f32_16x16x32_bf16 v[112:115], v[132:135], v[180:183], v[112:115]
	v_mfma_f32_16x16x32_bf16 v[108:111], v[140:143], v[180:183], v[108:111]
	v_mfma_f32_16x16x32_bf16 v[104:107], v[132:135], v[206:209], v[104:107]
	v_mfma_f32_16x16x32_bf16 v[100:103], v[140:143], v[206:209], v[100:103]
	v_mfma_f32_16x16x32_bf16 v[128:131], v[136:139], v[168:171], v[128:131]
	v_mfma_f32_16x16x32_bf16 v[124:127], v[144:147], v[168:171], v[124:127]
	v_mfma_f32_16x16x32_bf16 v[120:123], v[136:139], v[176:179], v[120:123]
	v_mfma_f32_16x16x32_bf16 v[116:119], v[144:147], v[176:179], v[116:119]
	v_mfma_f32_16x16x32_bf16 v[112:115], v[136:139], v[202:205], v[112:115]
	v_mfma_f32_16x16x32_bf16 v[108:111], v[144:147], v[202:205], v[108:111]
	v_mfma_f32_16x16x32_bf16 v[104:107], v[136:139], v[210:213], v[104:107]
	v_mfma_f32_16x16x32_bf16 v[100:103], v[144:147], v[210:213], v[100:103]
	s_setprio 0
	s_setprio 1
	v_mfma_f32_16x16x32_bf16 v[96:99], v[148:151], v[164:167], v[96:99]
	v_mfma_f32_16x16x32_bf16 v[92:95], v[156:159], v[164:167], v[92:95]
	v_mfma_f32_16x16x32_bf16 v[88:91], v[148:151], v[172:175], v[88:91]
	v_mfma_f32_16x16x32_bf16 v[84:87], v[156:159], v[172:175], v[84:87]
	v_mfma_f32_16x16x32_bf16 v[80:83], v[148:151], v[180:183], v[80:83]
	v_mfma_f32_16x16x32_bf16 v[76:79], v[156:159], v[180:183], v[76:79]
	v_mfma_f32_16x16x32_bf16 v[72:75], v[148:151], v[206:209], v[72:75]
	v_mfma_f32_16x16x32_bf16 v[68:71], v[156:159], v[206:209], v[68:71]
	v_mfma_f32_16x16x32_bf16 v[96:99], v[152:155], v[168:171], v[96:99]
	v_mfma_f32_16x16x32_bf16 v[92:95], v[160:163], v[168:171], v[92:95]
	v_mfma_f32_16x16x32_bf16 v[88:91], v[152:155], v[176:179], v[88:91]
	v_mfma_f32_16x16x32_bf16 v[84:87], v[160:163], v[176:179], v[84:87]
	v_mfma_f32_16x16x32_bf16 v[80:83], v[152:155], v[202:205], v[80:83]
	v_mfma_f32_16x16x32_bf16 v[76:79], v[160:163], v[202:205], v[76:79]
	v_mfma_f32_16x16x32_bf16 v[72:75], v[152:155], v[210:213], v[72:75]
	v_mfma_f32_16x16x32_bf16 v[68:71], v[160:163], v[210:213], v[68:71]
	s_barrier
; #define PG8_STAGE(bufoff, gbase, voff) do { _Pragma("unroll") for (int _i = 0; _i < 2; ++_i) \
;         __builtin_amdgcn_global_load_lds((const unsigned*)((const char*)(gbase) + (voff)[_i]), (PG8_LAS unsigned*)(lds + (bufoff) + ldsw + _i * 8192), 16, 0, 0); } while (0)
; #define PG8_LDA(dst, b, h) do { _Pragma("unroll") for (int m = 0; m < 4; ++m) _Pragma("unroll") for (int k = 0; k < 2; ++k) dst[m][k] = *(const PG8_LAS bf16x8*)(lds + PG8_SA(b, h) + aoff + m * 2048 + k * 1024); } while (0)
; #define PG8_MMA(ai, bj, At, Bt) do { __builtin_amdgcn_s_setprio(1); _Pragma("unroll") for (int m = 0; m < 4; ++m) _Pragma("unroll") for (int n = 0; n < 2; ++n) _Pragma("unroll") for (int k = 0; k < 2; ++k) \
;         acc[ai][bj][m][n] = __builtin_amdgcn_mfma_f32_16x16x32_bf16(Bt[n][k], At[m][k], acc[ai][bj][m][n], 0, 0, 0); __builtin_amdgcn_s_setprio(0); } while (0)
; #define PG8_WAIT_V(n) asm volatile("s_waitcnt vmcnt(" #n ")" ::: "memory")
; #define PG8_WAIT_L(n) asm volatile("s_waitcnt lgkmcnt(" #n ")" ::: "memory")
; #define PG8_BAR __builtin_amdgcn_s_barrier()
; #define PG8_SCHED __builtin_amdgcn_sched_barrier(0)
; template <class Epi, class Sched, bool ALIGN_EPI = false, bool SP2 = false, bool DUAL = false>
; __device__ __forceinline__ void gemm_phase(PG8_LAS unsigned char* lds, const Gemm g, const Sched& S, const Epi& E) {
;     ...
;             PG8_LDA(At, 1, 1); PG8_STAGE(PG8_SB(1, 0), b3, voffB); PG8_STAGE(PG8_SB(1, 1), b3 + hstep, voffB); PG8_STAGE(PG8_SA(1, 0), a3, voffA);
;             PG8_WAIT_V(8); PG8_WAIT_L(0); PG8_BAR; PG8_MMA(1, 0, At, B0); PG8_MMA(1, 1, At, B1); PG8_BAR; PG8_SCHED;
;     ...
;         if constexpr (ALIGN_EPI) { if (wr == 0) PG8_BAR; }
	s_setprio 0
	s_add_i32 s18, s76, s27
	v_lshl_add_u64 v[6:7], v[214:215], 0, s[36:37]
	s_mov_b32 m0, s18
	ds_read_b128 v[164:167], v237 offset:49152
	ds_read_b128 v[168:171], v237 offset:50176
	ds_read_b128 v[172:175], v237 offset:51200
	ds_read_b128 v[176:179], v237 offset:52224
	ds_read_b128 v[180:183], v237 offset:53248
	ds_read_b128 v[202:205], v237 offset:54272
	ds_read_b128 v[206:209], v237 offset:55296
	ds_read_b128 v[210:213], v237 offset:56320
	global_load_lds_dwordx4 v[6:7], off
	s_add_i32 m0, s18, 0x2000
	s_add_u32 s16, s16, 0x80080
	v_lshl_add_u64 v[6:7], v[216:217], 0, s[36:37]
	s_addc_u32 s17, s17, 0
	s_add_i32 s18, s77, s27
	global_load_lds_dwordx4 v[6:7], off
	v_lshl_add_u64 v[6:7], s[16:17], 0, v[186:187]
	s_mov_b32 m0, s18
	s_nop 0
	global_load_lds_dwordx4 v[6:7], off
	v_lshl_add_u64 v[6:7], s[16:17], 0, v[190:191]
	s_add_i32 m0, s18, 0x2000
	s_nop 0
	global_load_lds_dwordx4 v[6:7], off
	v_lshl_add_u64 v[6:7], v[218:219], 0, s[36:37]
	s_mov_b32 m0, s42
	s_nop 0
	global_load_lds_dwordx4 v[6:7], off
	v_lshl_add_u64 v[6:7], v[220:221], 0, s[36:37]
	s_mov_b32 m0, s43
	s_nop 0
	global_load_lds_dwordx4 v[6:7], off
	s_waitcnt vmcnt(8)
	s_waitcnt lgkmcnt(0)
	s_setprio 1
	s_barrier
	v_mfma_f32_16x16x32_bf16 v[64:67], v[132:135], v[164:167], v[64:67]
	v_mfma_f32_16x16x32_bf16 v[60:63], v[140:143], v[164:167], v[60:63]
	v_mfma_f32_16x16x32_bf16 v[56:59], v[132:135], v[172:175], v[56:59]
	v_mfma_f32_16x16x32_bf16 v[52:55], v[140:143], v[172:175], v[52:55]
	v_mfma_f32_16x16x32_bf16 v[48:51], v[132:135], v[180:183], v[48:51]
	v_mfma_f32_16x16x32_bf16 v[44:47], v[140:143], v[180:183], v[44:47]
	v_mfma_f32_16x16x32_bf16 v[40:43], v[132:135], v[206:209], v[40:43]
	v_mfma_f32_16x16x32_bf16 v[36:39], v[140:143], v[206:209], v[36:39]
	v_mfma_f32_16x16x32_bf16 v[64:67], v[136:139], v[168:171], v[64:67]
	v_mfma_f32_16x16x32_bf16 v[60:63], v[144:147], v[168:171], v[60:63]
	v_mfma_f32_16x16x32_bf16 v[56:59], v[136:139], v[176:179], v[56:59]
	v_mfma_f32_16x16x32_bf16 v[52:55], v[144:147], v[176:179], v[52:55]
	v_mfma_f32_16x16x32_bf16 v[48:51], v[136:139], v[202:205], v[48:51]
	v_mfma_f32_16x16x32_bf16 v[44:47], v[144:147], v[202:205], v[44:47]
	v_mfma_f32_16x16x32_bf16 v[40:43], v[136:139], v[210:213], v[40:43]
	v_mfma_f32_16x16x32_bf16 v[36:39], v[144:147], v[210:213], v[36:39]
	s_setprio 0
	s_setprio 1
	v_mfma_f32_16x16x32_bf16 v[32:35], v[148:151], v[164:167], v[32:35]
	v_mfma_f32_16x16x32_bf16 v[28:31], v[156:159], v[164:167], v[28:31]
	v_mfma_f32_16x16x32_bf16 v[24:27], v[148:151], v[172:175], v[24:27]
	v_mfma_f32_16x16x32_bf16 v[20:23], v[156:159], v[172:175], v[20:23]
	v_mfma_f32_16x16x32_bf16 v[16:19], v[148:151], v[180:183], v[16:19]
	v_mfma_f32_16x16x32_bf16 v[12:15], v[156:159], v[180:183], v[12:15]
	v_mfma_f32_16x16x32_bf16 v[6:9], v[148:151], v[206:209], v[8:11]
	v_mfma_f32_16x16x32_bf16 v[2:5], v[156:159], v[206:209], v[2:5]
	v_mfma_f32_16x16x32_bf16 v[32:35], v[152:155], v[168:171], v[32:35]
	v_mfma_f32_16x16x32_bf16 v[28:31], v[160:163], v[168:171], v[28:31]
	v_mfma_f32_16x16x32_bf16 v[24:27], v[152:155], v[176:179], v[24:27]
	v_mfma_f32_16x16x32_bf16 v[20:23], v[160:163], v[176:179], v[20:23]
	v_mfma_f32_16x16x32_bf16 v[16:19], v[152:155], v[202:205], v[16:19]
	v_mfma_f32_16x16x32_bf16 v[12:15], v[160:163], v[202:205], v[12:15]
	v_mfma_f32_16x16x32_bf16 v[8:11], v[152:155], v[210:213], v[6:9]
	v_mfma_f32_16x16x32_bf16 v[4:7], v[160:163], v[210:213], v[2:5]
	s_barrier
	s_setprio 0
	s_add_i32 s75, s75, 2
	s_add_u32 s14, s14, 0x100
	s_addc_u32 s15, s15, 0
	s_add_u32 s72, s72, 0x100
	s_addc_u32 s73, s73, 0
	s_cmp_gt_u32 s75, 29
	s_cbranch_scc0 .LBB0_805
	s_and_b64 vcc, exec, s[38:39]
	s_cbranch_vccz .LBB0_808
	s_barrier

;     __device__ bool next(int i, Unit& u) const { if (!base.next(i >> 1, u)) return false; u.sub = i & 1; return true; }
; #define PG8_STAGE(bufoff, gbase, voff) do { _Pragma("unroll") for (int _i = 0; _i < 2; ++_i) \
;         __builtin_amdgcn_global_load_lds((const unsigned*)((const char*)(gbase) + (voff)[_i]), (PG8_LAS unsigned*)(lds + (bufoff) + ldsw + _i * 8192), 16, 0, 0); } while (0)
; #define PG8_LDA(dst, b, h) do { _Pragma("unroll") for (int m = 0; m < 4; ++m) _Pragma("unroll") for (int k = 0; k < 2; ++k) dst[m][k] = *(const PG8_LAS bf16x8*)(lds + PG8_SA(b, h) + aoff + m * 2048 + k * 1024); } while (0)
; #define PG8_LDB(dst, b, h) do { _Pragma("unroll") for (int n = 0; n < 2; ++n) _Pragma("unroll") for (int k = 0; k < 2; ++k) dst[n][k] = *(const PG8_LAS bf16x8*)(lds + PG8_SB(b, h) + boff + n * 2048 + k * 1024); } while (0)
; #define PG8_WAIT_V(n) asm volatile("s_waitcnt vmcnt(" #n ")" ::: "memory")
; template <class Epi, class Sched, bool ALIGN_EPI = false, bool SP2 = false, bool DUAL = false>
; __device__ __forceinline__ void gemm_phase(PG8_LAS unsigned char* lds, const Gemm g, const Sched& S, const Epi& E) {
;     ...
;         const bool has_next = S.next(ui + 1, nxt);
;         const char* nA = has_next ? (const char*)((DUAL && nxt.sub) ? g.A2 : g.A) + (size_t)nxt.pm * tstep : cA; const char* nB = has_next ? (const char*)((DUAL && nxt.sub) ? g.Bt2 : g.Bt) + (size_t)nxt.pn * tstep : cB;
;         for (int t = 0; t < nt; t += 2) {
;             const bool last = (t == nt - 2);
;             const char* a1 = cA + (size_t)(t + 1) * kstep;
;             const char* a2 = last ? nA : cA + (size_t)(t + 2) * kstep; const char* b2 = last ? nB : cB + (size_t)(t + 2) * kstep;
;             const char* a3 = a2 + kstep; const char* b3 = b2 + kstep;
;             if (last && has_next) S.a_ready(nxt);
;             if constexpr (SP2) {
;             PG8_LDB(B0, 0, 0); PG8_LDB(B1, 0, 1); PG8_SCHED; PG8_LDA(At, 0, 0); PG8_STAGE(PG8_SA(1, 1), a1 + hstep, voffA);
;             PG8_WAIT_V(8); PG8_WAIT_L(0); PG8_BAR; PG8_MMA(0, 0, At, B0); PG8_MMA(0, 1, At, B1); PG8_BAR; PG8_SCHED;
;             PG8_LDA(At, 0, 1); PG8_STAGE(PG8_SB(0, 0), b2, voffB); PG8_STAGE(PG8_SB(0, 1), b2 + hstep, voffB); PG8_STAGE(PG8_SA(0, 0), a2, voffA);
;             PG8_WAIT_V(8); PG8_WAIT_L(0); PG8_BAR; PG8_MMA(1, 0, At, B0); PG8_MMA(1, 1, At, B1); PG8_BAR; PG8_SCHED;
.LBB0_895:
	s_ashr_i32 s61, s60, 31
	s_lshl_b64 s[18:19], s[60:61], 20
	s_add_u32 s62, s10, s18
	s_addc_u32 s63, s11, s19
	s_and_b64 s[18:19], s[6:7], exec
	s_cselect_b32 s18, s63, s17
	s_cselect_b32 s19, s62, s16
	s_ashr_i32 s41, s40, 31
	s_lshl_b64 s[64:65], s[40:41], 20
	s_add_u32 s64, s12, s64
	s_addc_u32 s65, s13, s65
	s_and_b64 s[68:69], s[6:7], exec
	s_cselect_b32 s41, s65, s15
	s_cselect_b32 s61, s64, s14
	s_add_u32 s68, s16, 0x80080
	s_addc_u32 s69, s17, 0
	s_add_u32 s67, s14, 0x100
	s_addc_u32 s70, s15, 0
	s_mov_b32 s71, -2
	s_waitcnt lgkmcnt(0)
	ds_read_b128 v[128:131], v218
	ds_read_b128 v[132:135], v218 offset:1024
	ds_read_b128 v[136:139], v218 offset:2048
	ds_read_b128 v[140:143], v218 offset:3072
	ds_read_b128 v[144:147], v219
	ds_read_b128 v[148:151], v219 offset:1024
	ds_read_b128 v[152:155], v219 offset:2048
	ds_read_b128 v[156:159], v219 offset:3072
	s_add_u32 s14, s68, 0xfff80080
	s_addc_u32 s15, s69, -1
	s_cmp_eq_u32 s71, 28
	s_cselect_b32 s17, s18, s15
	s_cselect_b32 s16, s19, s14
	s_cselect_b32 s15, s41, s70
	s_cselect_b32 s14, s61, s67
	v_lshl_add_u64 v[222:223], s[68:69], 0, v[188:189]
	s_add_i32 m0, s27, 0xc000
	ds_read_b128 v[160:163], v220
	ds_read_b128 v[164:167], v220 offset:1024
	ds_read_b128 v[168:171], v220 offset:2048
	ds_read_b128 v[172:175], v220 offset:3072
	ds_read_b128 v[196:199], v220 offset:4096
	ds_read_b128 v[202:205], v220 offset:5120
	ds_read_b128 v[206:209], v220 offset:6144
	ds_read_b128 v[232:235], v220 offset:7168
	global_load_lds_dwordx4 v[222:223], off
	v_lshl_add_u64 v[222:223], s[68:69], 0, v[190:191]
	s_add_i32 m0, s27, 0xe000
	s_nop 0
	global_load_lds_dwordx4 v[222:223], off
	s_waitcnt vmcnt(8)
	s_waitcnt lgkmcnt(0)
	s_setprio 1
	s_barrier
	v_mfma_f32_16x16x32_bf16 v[124:127], v[128:131], v[160:163], 0
	v_mfma_f32_16x16x32_bf16 v[120:123], v[136:139], v[160:163], 0
	v_mfma_f32_16x16x32_bf16 v[108:111], v[128:131], v[168:171], 0
	v_mfma_f32_16x16x32_bf16 v[104:107], v[136:139], v[168:171], 0
	v_mfma_f32_16x16x32_bf16 v[92:95], v[128:131], v[196:199], 0
	v_mfma_f32_16x16x32_bf16 v[88:91], v[136:139], v[196:199], 0
	v_mfma_f32_16x16x32_bf16 v[76:79], v[128:131], v[206:209], 0
	v_mfma_f32_16x16x32_bf16 v[72:75], v[136:139], v[206:209], 0
	v_mfma_f32_16x16x32_bf16 v[124:127], v[132:135], v[164:167], v[124:127]
	v_mfma_f32_16x16x32_bf16 v[120:123], v[140:143], v[164:167], v[120:123]
	v_mfma_f32_16x16x32_bf16 v[108:111], v[132:135], v[172:175], v[108:111]
	v_mfma_f32_16x16x32_bf16 v[104:107], v[140:143], v[172:175], v[104:107]
	v_mfma_f32_16x16x32_bf16 v[92:95], v[132:135], v[202:205], v[92:95]
	v_mfma_f32_16x16x32_bf16 v[88:91], v[140:143], v[202:205], v[88:91]
	v_mfma_f32_16x16x32_bf16 v[76:79], v[132:135], v[232:235], v[76:79]
	v_mfma_f32_16x16x32_bf16 v[72:75], v[140:143], v[232:235], v[72:75]
	s_setprio 0
	s_setprio 1
	v_mfma_f32_16x16x32_bf16 v[116:119], v[144:147], v[160:163], 0
	v_mfma_f32_16x16x32_bf16 v[112:115], v[152:155], v[160:163], 0
	v_mfma_f32_16x16x32_bf16 v[100:103], v[144:147], v[168:171], 0
	v_mfma_f32_16x16x32_bf16 v[96:99], v[152:155], v[168:171], 0
	v_mfma_f32_16x16x32_bf16 v[84:87], v[144:147], v[196:199], 0
	v_mfma_f32_16x16x32_bf16 v[80:83], v[152:155], v[196:199], 0
	v_mfma_f32_16x16x32_bf16 v[68:71], v[144:147], v[206:209], 0
	v_mfma_f32_16x16x32_bf16 v[64:67], v[152:155], v[206:209], 0
	v_mfma_f32_16x16x32_bf16 v[116:119], v[148:151], v[164:167], v[116:119]
	v_mfma_f32_16x16x32_bf16 v[112:115], v[156:159], v[164:167], v[112:115]
	v_mfma_f32_16x16x32_bf16 v[100:103], v[148:151], v[172:175], v[100:103]
	v_mfma_f32_16x16x32_bf16 v[96:99], v[156:159], v[172:175], v[96:99]
	v_mfma_f32_16x16x32_bf16 v[84:87], v[148:151], v[202:205], v[84:87]
	v_mfma_f32_16x16x32_bf16 v[80:83], v[156:159], v[202:205], v[80:83]
	v_mfma_f32_16x16x32_bf16 v[68:71], v[148:151], v[232:235], v[68:71]
	v_mfma_f32_16x16x32_bf16 v[64:67], v[156:159], v[232:235], v[64:67]
	s_barrier
	s_setprio 0
	s_add_i32 s72, s48, s26
	v_lshl_add_u64 v[222:223], s[14:15], 0, v[182:183]
	s_mov_b32 m0, s72
	ds_read_b128 v[160:163], v220 offset:16384
	ds_read_b128 v[164:167], v220 offset:17408
	ds_read_b128 v[168:171], v220 offset:18432
	ds_read_b128 v[172:175], v220 offset:19456
	ds_read_b128 v[196:199], v220 offset:20480
	ds_read_b128 v[202:205], v220 offset:21504
	ds_read_b128 v[206:209], v220 offset:22528
	ds_read_b128 v[232:235], v220 offset:23552
	global_load_lds_dwordx4 v[222:223], off
	s_add_i32 m0, s72, 0x2000
	s_add_u32 s72, s14, 0x80000
	v_lshl_add_u64 v[228:229], s[14:15], 0, v[186:187]
	s_addc_u32 s73, s15, 0
	s_add_i32 s74, s49, s26
	global_load_lds_dwordx4 v[228:229], off
	v_lshl_add_u64 v[236:237], s[72:73], 0, v[182:183]
	s_mov_b32 m0, s74
	v_lshl_add_u64 v[238:239], s[16:17], 0, v[184:185]
	global_load_lds_dwordx4 v[236:237], off
	v_lshl_add_u64 v[236:237], s[72:73], 0, v[186:187]
	s_add_i32 m0, s74, 0x2000
	s_nop 0
	global_load_lds_dwordx4 v[236:237], off
	v_lshl_add_u64 v[236:237], s[16:17], 0, v[180:181]
	s_mov_b32 m0, s27
	s_nop 0
	global_load_lds_dwordx4 v[236:237], off
	s_mov_b32 m0, s28
	s_nop 0
	global_load_lds_dwordx4 v[238:239], off
	s_waitcnt vmcnt(8)
	s_waitcnt lgkmcnt(0)
	s_setprio 1
	s_barrier
; #define PG8_STAGE(bufoff, gbase, voff) do { _Pragma("unroll") for (int _i = 0; _i < 2; ++_i) \
;         __builtin_amdgcn_global_load_lds((const unsigned*)((const char*)(gbase) + (voff)[_i]), (PG8_LAS unsigned*)(lds + (bufoff) + ldsw + _i * 8192), 16, 0, 0); } while (0)
; #define PG8_LDA(dst, b, h) do { _Pragma("unroll") for (int m = 0; m < 4; ++m) _Pragma("unroll") for (int k = 0; k < 2; ++k) dst[m][k] = *(const PG8_LAS bf16x8*)(lds + PG8_SA(b, h) + aoff + m * 2048 + k * 1024); } while (0)
; #define PG8_LDB(dst, b, h) do { _Pragma("unroll") for (int n = 0; n < 2; ++n) _Pragma("unroll") for (int k = 0; k < 2; ++k) dst[n][k] = *(const PG8_LAS bf16x8*)(lds + PG8_SB(b, h) + boff + n * 2048 + k * 1024); } while (0)
; #define PG8_MMA(ai, bj, At, Bt) do { __builtin_amdgcn_s_setprio(1); _Pragma("unroll") for (int m = 0; m < 4; ++m) _Pragma("unroll") for (int n = 0; n < 2; ++n) _Pragma("unroll") for (int k = 0; k < 2; ++k) \
;         acc[ai][bj][m][n] = __builtin_amdgcn_mfma_f32_16x16x32_bf16(Bt[n][k], At[m][k], acc[ai][bj][m][n], 0, 0, 0); __builtin_amdgcn_s_setprio(0); } while (0)
; #define PG8_WAIT_V(n) asm volatile("s_waitcnt vmcnt(" #n ")" ::: "memory")
; #define PG8_WAIT_L(n) asm volatile("s_waitcnt lgkmcnt(" #n ")" ::: "memory")
; #define PG8_BAR __builtin_amdgcn_s_barrier()
; #define PG8_SCHED __builtin_amdgcn_sched_barrier(0)
; template <class Epi, class Sched, bool ALIGN_EPI = false, bool SP2 = false, bool DUAL = false>
; __device__ __forceinline__ void gemm_phase(PG8_LAS unsigned char* lds, const Gemm g, const Sched& S, const Epi& E) {
;     ...
;             PG8_WAIT_V(8); PG8_WAIT_L(0); PG8_BAR; PG8_MMA(1, 0, At, B0); PG8_MMA(1, 1, At, B1); PG8_BAR; PG8_SCHED;
;             PG8_LDB(B0, 1, 0); PG8_LDB(B1, 1, 1); PG8_SCHED; PG8_LDA(At, 1, 0); PG8_STAGE(PG8_SA(0, 1), a2 + hstep, voffA);
;             PG8_WAIT_V(8); PG8_WAIT_L(0); PG8_BAR; PG8_MMA(0, 0, At, B0); PG8_MMA(0, 1, At, B1); PG8_BAR; PG8_SCHED;
	v_mfma_f32_16x16x32_bf16 v[60:63], v[128:131], v[160:163], 0
	v_mfma_f32_16x16x32_bf16 v[56:59], v[136:139], v[160:163], 0
	v_mfma_f32_16x16x32_bf16 v[44:47], v[128:131], v[168:171], 0
	v_mfma_f32_16x16x32_bf16 v[40:43], v[136:139], v[168:171], 0
	v_mfma_f32_16x16x32_bf16 v[28:31], v[128:131], v[196:199], 0
	v_mfma_f32_16x16x32_bf16 v[24:27], v[136:139], v[196:199], 0
	v_mfma_f32_16x16x32_bf16 v[12:15], v[128:131], v[206:209], 0
	v_mfma_f32_16x16x32_bf16 v[8:11], v[136:139], v[206:209], 0
	v_mfma_f32_16x16x32_bf16 v[60:63], v[132:135], v[164:167], v[60:63]
	v_mfma_f32_16x16x32_bf16 v[56:59], v[140:143], v[164:167], v[56:59]
	v_mfma_f32_16x16x32_bf16 v[44:47], v[132:135], v[172:175], v[44:47]
	v_mfma_f32_16x16x32_bf16 v[40:43], v[140:143], v[172:175], v[40:43]
	v_mfma_f32_16x16x32_bf16 v[28:31], v[132:135], v[202:205], v[28:31]
	v_mfma_f32_16x16x32_bf16 v[24:27], v[140:143], v[202:205], v[24:27]
	v_mfma_f32_16x16x32_bf16 v[12:15], v[132:135], v[232:235], v[12:15]
	v_mfma_f32_16x16x32_bf16 v[8:11], v[140:143], v[232:235], v[8:11]
	s_setprio 0
	s_setprio 1
	v_mfma_f32_16x16x32_bf16 v[52:55], v[144:147], v[160:163], 0
	v_mfma_f32_16x16x32_bf16 v[48:51], v[152:155], v[160:163], 0
	v_mfma_f32_16x16x32_bf16 v[36:39], v[144:147], v[168:171], 0
	v_mfma_f32_16x16x32_bf16 v[32:35], v[152:155], v[168:171], 0
	v_mfma_f32_16x16x32_bf16 v[20:23], v[144:147], v[196:199], 0
	v_mfma_f32_16x16x32_bf16 v[16:19], v[152:155], v[196:199], 0
	v_mfma_f32_16x16x32_bf16 v[4:7], v[144:147], v[206:209], 0
	v_mfma_f32_16x16x32_bf16 v[0:3], v[152:155], v[206:209], 0
	v_mfma_f32_16x16x32_bf16 v[52:55], v[148:151], v[164:167], v[52:55]
	v_mfma_f32_16x16x32_bf16 v[48:51], v[156:159], v[164:167], v[48:51]
	v_mfma_f32_16x16x32_bf16 v[36:39], v[148:151], v[172:175], v[36:39]
	v_mfma_f32_16x16x32_bf16 v[32:35], v[156:159], v[172:175], v[32:35]
	v_mfma_f32_16x16x32_bf16 v[20:23], v[148:151], v[202:205], v[20:23]
	v_mfma_f32_16x16x32_bf16 v[16:19], v[156:159], v[202:205], v[16:19]
	v_mfma_f32_16x16x32_bf16 v[4:7], v[148:151], v[232:235], v[4:7]
	v_mfma_f32_16x16x32_bf16 v[0:3], v[156:159], v[232:235], v[0:3]
	s_barrier
	s_setprio 0
	s_add_i32 s72, 0, 0x18000
	s_add_i32 s73, 0, 0x1c000
	v_add_u32_e32 v140, s72, v216
	v_add_u32_e32 v156, s73, v216
	ds_read_b128 v[128:131], v140
	ds_read_b128 v[132:135], v140 offset:1024
	ds_read_b128 v[136:139], v140 offset:2048
	ds_read_b128 v[140:143], v140 offset:3072
	ds_read_b128 v[144:147], v156
	ds_read_b128 v[148:151], v156 offset:1024
	ds_read_b128 v[152:155], v156 offset:2048
	ds_read_b128 v[156:159], v156 offset:3072
	s_add_u32 s16, s16, 0x80000
	s_addc_u32 s17, s17, 0
	s_mov_b32 m0, s29
	v_lshl_add_u64 v[240:241], s[16:17], 0, v[180:181]
	ds_read_b128 v[160:163], v220 offset:32768
	ds_read_b128 v[164:167], v220 offset:33792
	ds_read_b128 v[168:171], v220 offset:34816
	ds_read_b128 v[172:175], v220 offset:35840
	ds_read_b128 v[196:199], v220 offset:36864
	ds_read_b128 v[202:205], v220 offset:37888
	ds_read_b128 v[206:209], v220 offset:38912
	ds_read_b128 v[232:235], v220 offset:39936
	global_load_lds_dwordx4 v[240:241], off
	v_lshl_add_u64 v[240:241], s[16:17], 0, v[184:185]
	s_mov_b32 m0, s34
	s_nop 0
	global_load_lds_dwordx4 v[240:241], off
	s_waitcnt vmcnt(8)
	s_waitcnt lgkmcnt(0)
	s_setprio 1
	s_barrier
	v_mfma_f32_16x16x32_bf16 v[124:127], v[128:131], v[160:163], v[124:127]
	v_mfma_f32_16x16x32_bf16 v[120:123], v[136:139], v[160:163], v[120:123]
	v_mfma_f32_16x16x32_bf16 v[108:111], v[128:131], v[168:171], v[108:111]
	v_mfma_f32_16x16x32_bf16 v[104:107], v[136:139], v[168:171], v[104:107]
	v_mfma_f32_16x16x32_bf16 v[92:95], v[128:131], v[196:199], v[92:95]
	v_mfma_f32_16x16x32_bf16 v[88:91], v[136:139], v[196:199], v[88:91]
	v_mfma_f32_16x16x32_bf16 v[76:79], v[128:131], v[206:209], v[76:79]
	v_mfma_f32_16x16x32_bf16 v[72:75], v[136:139], v[206:209], v[72:75]
	v_mfma_f32_16x16x32_bf16 v[124:127], v[132:135], v[164:167], v[124:127]
	v_mfma_f32_16x16x32_bf16 v[120:123], v[140:143], v[164:167], v[120:123]
	v_mfma_f32_16x16x32_bf16 v[108:111], v[132:135], v[172:175], v[108:111]
	v_mfma_f32_16x16x32_bf16 v[104:107], v[140:143], v[172:175], v[104:107]
	v_mfma_f32_16x16x32_bf16 v[92:95], v[132:135], v[202:205], v[92:95]
	v_mfma_f32_16x16x32_bf16 v[88:91], v[140:143], v[202:205], v[88:91]
	v_mfma_f32_16x16x32_bf16 v[76:79], v[132:135], v[232:235], v[76:79]
	v_mfma_f32_16x16x32_bf16 v[72:75], v[140:143], v[232:235], v[72:75]
	s_setprio 0
	s_setprio 1
	v_mfma_f32_16x16x32_bf16 v[116:119], v[144:147], v[160:163], v[116:119]
	v_mfma_f32_16x16x32_bf16 v[112:115], v[152:155], v[160:163], v[112:115]
	v_mfma_f32_16x16x32_bf16 v[100:103], v[144:147], v[168:171], v[100:103]
	v_mfma_f32_16x16x32_bf16 v[96:99], v[152:155], v[168:171], v[96:99]
	v_mfma_f32_16x16x32_bf16 v[84:87], v[144:147], v[196:199], v[84:87]
	v_mfma_f32_16x16x32_bf16 v[80:83], v[152:155], v[196:199], v[80:83]
	v_mfma_f32_16x16x32_bf16 v[68:71], v[144:147], v[206:209], v[68:71]
	v_mfma_f32_16x16x32_bf16 v[64:67], v[152:155], v[206:209], v[64:67]
	v_mfma_f32_16x16x32_bf16 v[116:119], v[148:151], v[164:167], v[116:119]
	v_mfma_f32_16x16x32_bf16 v[112:115], v[156:159], v[164:167], v[112:115]
	v_mfma_f32_16x16x32_bf16 v[100:103], v[148:151], v[172:175], v[100:103]
	v_mfma_f32_16x16x32_bf16 v[96:99], v[156:159], v[172:175], v[96:99]
	v_mfma_f32_16x16x32_bf16 v[84:87], v[148:151], v[202:205], v[84:87]
	v_mfma_f32_16x16x32_bf16 v[80:83], v[156:159], v[202:205], v[80:83]
	v_mfma_f32_16x16x32_bf16 v[68:71], v[148:151], v[232:235], v[68:71]
	v_mfma_f32_16x16x32_bf16 v[64:67], v[156:159], v[232:235], v[64:67]
	s_barrier
; #define PG8_STAGE(bufoff, gbase, voff) do { _Pragma("unroll") for (int _i = 0; _i < 2; ++_i) \
;         __builtin_amdgcn_global_load_lds((const unsigned*)((const char*)(gbase) + (voff)[_i]), (PG8_LAS unsigned*)(lds + (bufoff) + ldsw + _i * 8192), 16, 0, 0); } while (0)
; #define PG8_LDA(dst, b, h) do { _Pragma("unroll") for (int m = 0; m < 4; ++m) _Pragma("unroll") for (int k = 0; k < 2; ++k) dst[m][k] = *(const PG8_LAS bf16x8*)(lds + PG8_SA(b, h) + aoff + m * 2048 + k * 1024); } while (0)
; #define PG8_LDB(dst, b, h) do { _Pragma("unroll") for (int n = 0; n < 2; ++n) _Pragma("unroll") for (int k = 0; k < 2; ++k) dst[n][k] = *(const PG8_LAS bf16x8*)(lds + PG8_SB(b, h) + boff + n * 2048 + k * 1024); } while (0)
; #define PG8_MMA(ai, bj, At, Bt) do { __builtin_amdgcn_s_setprio(1); _Pragma("unroll") for (int m = 0; m < 4; ++m) _Pragma("unroll") for (int n = 0; n < 2; ++n) _Pragma("unroll") for (int k = 0; k < 2; ++k) \
;         acc[ai][bj][m][n] = __builtin_amdgcn_mfma_f32_16x16x32_bf16(Bt[n][k], At[m][k], acc[ai][bj][m][n], 0, 0, 0); __builtin_amdgcn_s_setprio(0); } while (0)
; #define PG8_BAR __builtin_amdgcn_s_barrier()
; template <class Epi, class Sched, bool ALIGN_EPI = false, bool SP2 = false, bool DUAL = false>
; __device__ __forceinline__ void gemm_phase(PG8_LAS unsigned char* lds, const Gemm g, const Sched& S, const Epi& E) {
;     ...
;             PG8_LDB(B0, 0, 0); PG8_LDB(B1, 0, 1); PG8_SCHED; PG8_LDA(At, 0, 0); PG8_STAGE(PG8_SA(1, 1), a1 + hstep, voffA);
;             PG8_WAIT_V(8); PG8_WAIT_L(0); PG8_BAR; PG8_MMA(0, 0, At, B0); PG8_MMA(0, 1, At, B1); PG8_BAR; PG8_SCHED;
;             PG8_LDA(At, 0, 1); PG8_STAGE(PG8_SB(0, 0), b2, voffB); PG8_STAGE(PG8_SB(0, 1), b2 + hstep, voffB); PG8_STAGE(PG8_SA(0, 0), a2, voffA);
;             PG8_WAIT_V(8); PG8_WAIT_L(0); PG8_BAR; PG8_MMA(1, 0, At, B0); PG8_MMA(1, 1, At, B1); PG8_BAR; PG8_SCHED;
;             PG8_LDB(B0, 1, 0); PG8_LDB(B1, 1, 1); PG8_SCHED; PG8_LDA(At, 1, 0); PG8_STAGE(PG8_SA(0, 1), a2 + hstep, voffA);
;             PG8_WAIT_V(8); PG8_WAIT_L(0); PG8_BAR; PG8_MMA(0, 0, At, B0); PG8_MMA(0, 1, At, B1); PG8_BAR; PG8_SCHED;
;             PG8_LDA(At, 1, 1); PG8_STAGE(PG8_SB(1, 0), b3, voffB); PG8_STAGE(PG8_SB(1, 1), b3 + hstep, voffB); PG8_STAGE(PG8_SA(1, 0), a3, voffA);
;             PG8_WAIT_V(8); PG8_WAIT_L(0); PG8_BAR; PG8_MMA(1, 0, At, B0); PG8_MMA(1, 1, At, B1); PG8_BAR; PG8_SCHED;
	s_setprio 0
	s_add_i32 s16, s72, s26
	v_lshl_add_u64 v[222:223], v[222:223], 0, s[36:37]
	s_mov_b32 m0, s16
	ds_read_b128 v[160:163], v220 offset:49152
	ds_read_b128 v[164:167], v220 offset:50176
	ds_read_b128 v[168:171], v220 offset:51200
	ds_read_b128 v[172:175], v220 offset:52224
	ds_read_b128 v[196:199], v220 offset:53248
	ds_read_b128 v[202:205], v220 offset:54272
	ds_read_b128 v[206:209], v220 offset:55296
	ds_read_b128 v[232:235], v220 offset:56320
	global_load_lds_dwordx4 v[222:223], off
	s_add_i32 m0, s16, 0x2000
	s_add_u32 s14, s14, 0x80080
	v_lshl_add_u64 v[222:223], v[228:229], 0, s[36:37]
	s_addc_u32 s15, s15, 0
	s_add_i32 s16, s73, s26
	global_load_lds_dwordx4 v[222:223], off
	v_lshl_add_u64 v[222:223], s[14:15], 0, v[182:183]
	s_mov_b32 m0, s16
	s_nop 0
	global_load_lds_dwordx4 v[222:223], off
	v_lshl_add_u64 v[222:223], s[14:15], 0, v[186:187]
	s_add_i32 m0, s16, 0x2000
	s_nop 0
	global_load_lds_dwordx4 v[222:223], off
	v_lshl_add_u64 v[222:223], v[236:237], 0, s[36:37]
	s_mov_b32 m0, s44
	s_nop 0
	global_load_lds_dwordx4 v[222:223], off
	v_lshl_add_u64 v[222:223], v[238:239], 0, s[36:37]
	s_mov_b32 m0, s45
	s_nop 0
	global_load_lds_dwordx4 v[222:223], off
	s_waitcnt vmcnt(8)
	s_waitcnt lgkmcnt(0)
	s_setprio 1
	s_barrier
	v_mfma_f32_16x16x32_bf16 v[60:63], v[128:131], v[160:163], v[60:63]
	v_mfma_f32_16x16x32_bf16 v[56:59], v[136:139], v[160:163], v[56:59]
	v_mfma_f32_16x16x32_bf16 v[44:47], v[128:131], v[168:171], v[44:47]
	v_mfma_f32_16x16x32_bf16 v[40:43], v[136:139], v[168:171], v[40:43]
	v_mfma_f32_16x16x32_bf16 v[28:31], v[128:131], v[196:199], v[28:31]
	v_mfma_f32_16x16x32_bf16 v[24:27], v[136:139], v[196:199], v[24:27]
	v_mfma_f32_16x16x32_bf16 v[12:15], v[128:131], v[206:209], v[12:15]
	v_mfma_f32_16x16x32_bf16 v[8:11], v[136:139], v[206:209], v[8:11]
	v_mfma_f32_16x16x32_bf16 v[60:63], v[132:135], v[164:167], v[60:63]
	v_mfma_f32_16x16x32_bf16 v[56:59], v[140:143], v[164:167], v[56:59]
	v_mfma_f32_16x16x32_bf16 v[44:47], v[132:135], v[172:175], v[44:47]
	v_mfma_f32_16x16x32_bf16 v[40:43], v[140:143], v[172:175], v[40:43]
	v_mfma_f32_16x16x32_bf16 v[28:31], v[132:135], v[202:205], v[28:31]
	v_mfma_f32_16x16x32_bf16 v[24:27], v[140:143], v[202:205], v[24:27]
	v_mfma_f32_16x16x32_bf16 v[12:15], v[132:135], v[232:235], v[12:15]
	v_mfma_f32_16x16x32_bf16 v[8:11], v[140:143], v[232:235], v[8:11]
	s_setprio 0
	s_setprio 1
	v_mfma_f32_16x16x32_bf16 v[52:55], v[144:147], v[160:163], v[52:55]
	v_mfma_f32_16x16x32_bf16 v[48:51], v[152:155], v[160:163], v[48:51]
	v_mfma_f32_16x16x32_bf16 v[36:39], v[144:147], v[168:171], v[36:39]
	v_mfma_f32_16x16x32_bf16 v[32:35], v[152:155], v[168:171], v[32:35]
	v_mfma_f32_16x16x32_bf16 v[20:23], v[144:147], v[196:199], v[20:23]
	v_mfma_f32_16x16x32_bf16 v[16:19], v[152:155], v[196:199], v[16:19]
	v_mfma_f32_16x16x32_bf16 v[4:7], v[144:147], v[206:209], v[4:7]
	v_mfma_f32_16x16x32_bf16 v[0:3], v[152:155], v[206:209], v[0:3]
	v_mfma_f32_16x16x32_bf16 v[52:55], v[148:151], v[164:167], v[52:55]
	v_mfma_f32_16x16x32_bf16 v[48:51], v[156:159], v[164:167], v[48:51]
	v_mfma_f32_16x16x32_bf16 v[36:39], v[148:151], v[172:175], v[36:39]
	v_mfma_f32_16x16x32_bf16 v[32:35], v[156:159], v[172:175], v[32:35]
	v_mfma_f32_16x16x32_bf16 v[20:23], v[148:151], v[202:205], v[20:23]
	v_mfma_f32_16x16x32_bf16 v[16:19], v[156:159], v[202:205], v[16:19]
	v_mfma_f32_16x16x32_bf16 v[4:7], v[148:151], v[232:235], v[4:7]
	v_mfma_f32_16x16x32_bf16 v[0:3], v[156:159], v[232:235], v[0:3]
	s_barrier
	s_setprio 0
	s_add_i32 s71, s71, 2
	s_add_u32 s68, s68, 0x100
	s_addc_u32 s69, s69, 0
	s_add_u32 s67, s67, 0x100
	s_addc_u32 s70, s70, 0
.LBB0_896:
	ds_read_b128 v[128:131], v218
	ds_read_b128 v[132:135], v218 offset:1024
	ds_read_b128 v[136:139], v218 offset:2048
	ds_read_b128 v[140:143], v218 offset:3072
	ds_read_b128 v[144:147], v219
	ds_read_b128 v[148:151], v219 offset:1024
	ds_read_b128 v[152:155], v219 offset:2048
	ds_read_b128 v[156:159], v219 offset:3072
	s_add_u32 s14, s68, 0xfff80080
	s_addc_u32 s15, s69, -1
	s_cmp_eq_u32 s71, 28
	s_cselect_b32 s17, s18, s15
	s_cselect_b32 s16, s19, s14
	s_cselect_b32 s15, s41, s70
	s_cselect_b32 s14, s61, s67
	v_lshl_add_u64 v[222:223], s[68:69], 0, v[188:189]
	s_add_i32 m0, s27, 0xc000
	ds_read_b128 v[160:163], v220
	ds_read_b128 v[164:167], v220 offset:1024
	ds_read_b128 v[168:171], v220 offset:2048
	ds_read_b128 v[172:175], v220 offset:3072
	ds_read_b128 v[196:199], v220 offset:4096
	ds_read_b128 v[202:205], v220 offset:5120
	ds_read_b128 v[206:209], v220 offset:6144
	ds_read_b128 v[232:235], v220 offset:7168
	global_load_lds_dwordx4 v[222:223], off
	v_lshl_add_u64 v[222:223], s[68:69], 0, v[190:191]
	s_add_i32 m0, s27, 0xe000
	s_nop 0
	global_load_lds_dwordx4 v[222:223], off
	s_waitcnt vmcnt(8)
	s_waitcnt lgkmcnt(0)
	s_setprio 1
	s_barrier
; #define PG8_STAGE(bufoff, gbase, voff) do { _Pragma("unroll") for (int _i = 0; _i < 2; ++_i) \
;         __builtin_amdgcn_global_load_lds((const unsigned*)((const char*)(gbase) + (voff)[_i]), (PG8_LAS unsigned*)(lds + (bufoff) + ldsw + _i * 8192), 16, 0, 0); } while (0)
; #define PG8_LDA(dst, b, h) do { _Pragma("unroll") for (int m = 0; m < 4; ++m) _Pragma("unroll") for (int k = 0; k < 2; ++k) dst[m][k] = *(const PG8_LAS bf16x8*)(lds + PG8_SA(b, h) + aoff + m * 2048 + k * 1024); } while (0)
; #define PG8_MMA(ai, bj, At, Bt) do { __builtin_amdgcn_s_setprio(1); _Pragma("unroll") for (int m = 0; m < 4; ++m) _Pragma("unroll") for (int n = 0; n < 2; ++n) _Pragma("unroll") for (int k = 0; k < 2; ++k) \
;         acc[ai][bj][m][n] = __builtin_amdgcn_mfma_f32_16x16x32_bf16(Bt[n][k], At[m][k], acc[ai][bj][m][n], 0, 0, 0); __builtin_amdgcn_s_setprio(0); } while (0)
; #define PG8_WAIT_V(n) asm volatile("s_waitcnt vmcnt(" #n ")" ::: "memory")
; #define PG8_WAIT_L(n) asm volatile("s_waitcnt lgkmcnt(" #n ")" ::: "memory")
; #define PG8_BAR __builtin_amdgcn_s_barrier()
; #define PG8_SCHED __builtin_amdgcn_sched_barrier(0)
; template <class Epi, class Sched, bool ALIGN_EPI = false, bool SP2 = false, bool DUAL = false>
; __device__ __forceinline__ void gemm_phase(PG8_LAS unsigned char* lds, const Gemm g, const Sched& S, const Epi& E) {
;     ...
;             PG8_WAIT_V(8); PG8_WAIT_L(0); PG8_BAR; PG8_MMA(0, 0, At, B0); PG8_MMA(0, 1, At, B1); PG8_BAR; PG8_SCHED;
;             PG8_LDA(At, 0, 1); PG8_STAGE(PG8_SB(0, 0), b2, voffB); PG8_STAGE(PG8_SB(0, 1), b2 + hstep, voffB); PG8_STAGE(PG8_SA(0, 0), a2, voffA);
;             PG8_WAIT_V(8); PG8_WAIT_L(0); PG8_BAR; PG8_MMA(1, 0, At, B0); PG8_MMA(1, 1, At, B1); PG8_BAR; PG8_SCHED;
	v_mfma_f32_16x16x32_bf16 v[124:127], v[128:131], v[160:163], v[124:127]
	v_mfma_f32_16x16x32_bf16 v[120:123], v[136:139], v[160:163], v[120:123]
	v_mfma_f32_16x16x32_bf16 v[108:111], v[128:131], v[168:171], v[108:111]
	v_mfma_f32_16x16x32_bf16 v[104:107], v[136:139], v[168:171], v[104:107]
	v_mfma_f32_16x16x32_bf16 v[92:95], v[128:131], v[196:199], v[92:95]
	v_mfma_f32_16x16x32_bf16 v[88:91], v[136:139], v[196:199], v[88:91]
	v_mfma_f32_16x16x32_bf16 v[76:79], v[128:131], v[206:209], v[76:79]
	v_mfma_f32_16x16x32_bf16 v[72:75], v[136:139], v[206:209], v[72:75]
	v_mfma_f32_16x16x32_bf16 v[124:127], v[132:135], v[164:167], v[124:127]
	v_mfma_f32_16x16x32_bf16 v[120:123], v[140:143], v[164:167], v[120:123]
	v_mfma_f32_16x16x32_bf16 v[108:111], v[132:135], v[172:175], v[108:111]
	v_mfma_f32_16x16x32_bf16 v[104:107], v[140:143], v[172:175], v[104:107]
	v_mfma_f32_16x16x32_bf16 v[92:95], v[132:135], v[202:205], v[92:95]
	v_mfma_f32_16x16x32_bf16 v[88:91], v[140:143], v[202:205], v[88:91]
	v_mfma_f32_16x16x32_bf16 v[76:79], v[132:135], v[232:235], v[76:79]
	v_mfma_f32_16x16x32_bf16 v[72:75], v[140:143], v[232:235], v[72:75]
	s_setprio 0
	s_setprio 1
	v_mfma_f32_16x16x32_bf16 v[116:119], v[144:147], v[160:163], v[116:119]
	v_mfma_f32_16x16x32_bf16 v[112:115], v[152:155], v[160:163], v[112:115]
	v_mfma_f32_16x16x32_bf16 v[100:103], v[144:147], v[168:171], v[100:103]
	v_mfma_f32_16x16x32_bf16 v[96:99], v[152:155], v[168:171], v[96:99]
	v_mfma_f32_16x16x32_bf16 v[84:87], v[144:147], v[196:199], v[84:87]
	v_mfma_f32_16x16x32_bf16 v[80:83], v[152:155], v[196:199], v[80:83]
	v_mfma_f32_16x16x32_bf16 v[68:71], v[144:147], v[206:209], v[68:71]
	v_mfma_f32_16x16x32_bf16 v[64:67], v[152:155], v[206:209], v[64:67]
	v_mfma_f32_16x16x32_bf16 v[116:119], v[148:151], v[164:167], v[116:119]
	v_mfma_f32_16x16x32_bf16 v[112:115], v[156:159], v[164:167], v[112:115]
	v_mfma_f32_16x16x32_bf16 v[100:103], v[148:151], v[172:175], v[100:103]
	v_mfma_f32_16x16x32_bf16 v[96:99], v[156:159], v[172:175], v[96:99]
	v_mfma_f32_16x16x32_bf16 v[84:87], v[148:151], v[202:205], v[84:87]
	v_mfma_f32_16x16x32_bf16 v[80:83], v[156:159], v[202:205], v[80:83]
	v_mfma_f32_16x16x32_bf16 v[68:71], v[148:151], v[232:235], v[68:71]
	v_mfma_f32_16x16x32_bf16 v[64:67], v[156:159], v[232:235], v[64:67]
	s_barrier
	s_setprio 0
	s_add_i32 s72, s48, s26
	v_lshl_add_u64 v[222:223], s[14:15], 0, v[182:183]
	s_mov_b32 m0, s72
	ds_read_b128 v[160:163], v220 offset:16384
	ds_read_b128 v[164:167], v220 offset:17408
	ds_read_b128 v[168:171], v220 offset:18432
	ds_read_b128 v[172:175], v220 offset:19456
	ds_read_b128 v[196:199], v220 offset:20480
	ds_read_b128 v[202:205], v220 offset:21504
	ds_read_b128 v[206:209], v220 offset:22528
	ds_read_b128 v[232:235], v220 offset:23552
	global_load_lds_dwordx4 v[222:223], off
	s_add_i32 m0, s72, 0x2000
	s_add_u32 s72, s14, 0x80000
	v_lshl_add_u64 v[228:229], s[14:15], 0, v[186:187]
	s_addc_u32 s73, s15, 0
	s_add_i32 s74, s49, s26
	global_load_lds_dwordx4 v[228:229], off
	v_lshl_add_u64 v[236:237], s[72:73], 0, v[182:183]
	s_mov_b32 m0, s74
	v_lshl_add_u64 v[238:239], s[16:17], 0, v[184:185]
	global_load_lds_dwordx4 v[236:237], off
	v_lshl_add_u64 v[236:237], s[72:73], 0, v[186:187]
	s_add_i32 m0, s74, 0x2000
	s_nop 0
	global_load_lds_dwordx4 v[236:237], off
	v_lshl_add_u64 v[236:237], s[16:17], 0, v[180:181]
	s_mov_b32 m0, s27
	s_nop 0
	global_load_lds_dwordx4 v[236:237], off
	s_mov_b32 m0, s28
	s_nop 0
	global_load_lds_dwordx4 v[238:239], off
	s_waitcnt vmcnt(8)
	s_waitcnt lgkmcnt(0)
	s_setprio 1
	s_barrier
	v_mfma_f32_16x16x32_bf16 v[60:63], v[128:131], v[160:163], v[60:63]
	v_mfma_f32_16x16x32_bf16 v[56:59], v[136:139], v[160:163], v[56:59]
	v_mfma_f32_16x16x32_bf16 v[44:47], v[128:131], v[168:171], v[44:47]
	v_mfma_f32_16x16x32_bf16 v[40:43], v[136:139], v[168:171], v[40:43]
	v_mfma_f32_16x16x32_bf16 v[28:31], v[128:131], v[196:199], v[28:31]
	v_mfma_f32_16x16x32_bf16 v[24:27], v[136:139], v[196:199], v[24:27]
	v_mfma_f32_16x16x32_bf16 v[12:15], v[128:131], v[206:209], v[12:15]
	v_mfma_f32_16x16x32_bf16 v[8:11], v[136:139], v[206:209], v[8:11]
	v_mfma_f32_16x16x32_bf16 v[60:63], v[132:135], v[164:167], v[60:63]
	v_mfma_f32_16x16x32_bf16 v[56:59], v[140:143], v[164:167], v[56:59]
	v_mfma_f32_16x16x32_bf16 v[44:47], v[132:135], v[172:175], v[44:47]
	v_mfma_f32_16x16x32_bf16 v[40:43], v[140:143], v[172:175], v[40:43]
	v_mfma_f32_16x16x32_bf16 v[28:31], v[132:135], v[202:205], v[28:31]
	v_mfma_f32_16x16x32_bf16 v[24:27], v[140:143], v[202:205], v[24:27]
	v_mfma_f32_16x16x32_bf16 v[12:15], v[132:135], v[232:235], v[12:15]
	v_mfma_f32_16x16x32_bf16 v[8:11], v[140:143], v[232:235], v[8:11]
	s_setprio 0
	s_setprio 1
	v_mfma_f32_16x16x32_bf16 v[52:55], v[144:147], v[160:163], v[52:55]
	v_mfma_f32_16x16x32_bf16 v[48:51], v[152:155], v[160:163], v[48:51]
	v_mfma_f32_16x16x32_bf16 v[36:39], v[144:147], v[168:171], v[36:39]
	v_mfma_f32_16x16x32_bf16 v[32:35], v[152:155], v[168:171], v[32:35]
	v_mfma_f32_16x16x32_bf16 v[20:23], v[144:147], v[196:199], v[20:23]
	v_mfma_f32_16x16x32_bf16 v[16:19], v[152:155], v[196:199], v[16:19]
	v_mfma_f32_16x16x32_bf16 v[4:7], v[144:147], v[206:209], v[4:7]
	v_mfma_f32_16x16x32_bf16 v[0:3], v[152:155], v[206:209], v[0:3]
	v_mfma_f32_16x16x32_bf16 v[52:55], v[148:151], v[164:167], v[52:55]
	v_mfma_f32_16x16x32_bf16 v[48:51], v[156:159], v[164:167], v[48:51]
	v_mfma_f32_16x16x32_bf16 v[36:39], v[148:151], v[172:175], v[36:39]
	v_mfma_f32_16x16x32_bf16 v[32:35], v[156:159], v[172:175], v[32:35]
	v_mfma_f32_16x16x32_bf16 v[20:23], v[148:151], v[202:205], v[20:23]
	v_mfma_f32_16x16x32_bf16 v[16:19], v[156:159], v[202:205], v[16:19]
	v_mfma_f32_16x16x32_bf16 v[4:7], v[148:151], v[232:235], v[4:7]
	v_mfma_f32_16x16x32_bf16 v[0:3], v[156:159], v[232:235], v[0:3]
	s_barrier
; #define PG8_STAGE(bufoff, gbase, voff) do { _Pragma("unroll") for (int _i = 0; _i < 2; ++_i) \
;         __builtin_amdgcn_global_load_lds((const unsigned*)((const char*)(gbase) + (voff)[_i]), (PG8_LAS unsigned*)(lds + (bufoff) + ldsw + _i * 8192), 16, 0, 0); } while (0)
; #define PG8_LDA(dst, b, h) do { _Pragma("unroll") for (int m = 0; m < 4; ++m) _Pragma("unroll") for (int k = 0; k < 2; ++k) dst[m][k] = *(const PG8_LAS bf16x8*)(lds + PG8_SA(b, h) + aoff + m * 2048 + k * 1024); } while (0)
; #define PG8_LDB(dst, b, h) do { _Pragma("unroll") for (int n = 0; n < 2; ++n) _Pragma("unroll") for (int k = 0; k < 2; ++k) dst[n][k] = *(const PG8_LAS bf16x8*)(lds + PG8_SB(b, h) + boff + n * 2048 + k * 1024); } while (0)
; #define PG8_MMA(ai, bj, At, Bt) do { __builtin_amdgcn_s_setprio(1); _Pragma("unroll") for (int m = 0; m < 4; ++m) _Pragma("unroll") for (int n = 0; n < 2; ++n) _Pragma("unroll") for (int k = 0; k < 2; ++k) \
;         acc[ai][bj][m][n] = __builtin_amdgcn_mfma_f32_16x16x32_bf16(Bt[n][k], At[m][k], acc[ai][bj][m][n], 0, 0, 0); __builtin_amdgcn_s_setprio(0); } while (0)
; #define PG8_WAIT_V(n) asm volatile("s_waitcnt vmcnt(" #n ")" ::: "memory")
; #define PG8_WAIT_L(n) asm volatile("s_waitcnt lgkmcnt(" #n ")" ::: "memory")
; #define PG8_BAR __builtin_amdgcn_s_barrier()
; #define PG8_SCHED __builtin_amdgcn_sched_barrier(0)
; template <class Epi, class Sched, bool ALIGN_EPI = false, bool SP2 = false, bool DUAL = false>
; __device__ __forceinline__ void gemm_phase(PG8_LAS unsigned char* lds, const Gemm g, const Sched& S, const Epi& E) {
;     ...
;             PG8_LDB(B0, 1, 0); PG8_LDB(B1, 1, 1); PG8_SCHED; PG8_LDA(At, 1, 0); PG8_STAGE(PG8_SA(0, 1), a2 + hstep, voffA);
;             PG8_WAIT_V(8); PG8_WAIT_L(0); PG8_BAR; PG8_MMA(0, 0, At, B0); PG8_MMA(0, 1, At, B1); PG8_BAR; PG8_SCHED;
	s_setprio 0
	s_add_i32 s72, 0, 0x18000
	s_add_i32 s73, 0, 0x1c000
	v_add_u32_e32 v140, s72, v216
	v_add_u32_e32 v156, s73, v216
	ds_read_b128 v[128:131], v140
	ds_read_b128 v[132:135], v140 offset:1024
	ds_read_b128 v[136:139], v140 offset:2048
	ds_read_b128 v[140:143], v140 offset:3072
	ds_read_b128 v[144:147], v156
	ds_read_b128 v[148:151], v156 offset:1024
	ds_read_b128 v[152:155], v156 offset:2048
	ds_read_b128 v[156:159], v156 offset:3072
	s_add_u32 s16, s16, 0x80000
	s_addc_u32 s17, s17, 0
	s_mov_b32 m0, s29
	v_lshl_add_u64 v[240:241], s[16:17], 0, v[180:181]
	ds_read_b128 v[160:163], v220 offset:32768
	ds_read_b128 v[164:167], v220 offset:33792
	ds_read_b128 v[168:171], v220 offset:34816
	ds_read_b128 v[172:175], v220 offset:35840
	ds_read_b128 v[196:199], v220 offset:36864
	ds_read_b128 v[202:205], v220 offset:37888
	ds_read_b128 v[206:209], v220 offset:38912
	ds_read_b128 v[232:235], v220 offset:39936
	global_load_lds_dwordx4 v[240:241], off
	v_lshl_add_u64 v[240:241], s[16:17], 0, v[184:185]
	s_mov_b32 m0, s34
	s_nop 0
	global_load_lds_dwordx4 v[240:241], off
	s_waitcnt vmcnt(8)
	s_waitcnt lgkmcnt(0)
	s_setprio 1
	s_barrier
	v_mfma_f32_16x16x32_bf16 v[124:127], v[128:131], v[160:163], v[124:127]
	v_mfma_f32_16x16x32_bf16 v[120:123], v[136:139], v[160:163], v[120:123]
	v_mfma_f32_16x16x32_bf16 v[108:111], v[128:131], v[168:171], v[108:111]
	v_mfma_f32_16x16x32_bf16 v[104:107], v[136:139], v[168:171], v[104:107]
	v_mfma_f32_16x16x32_bf16 v[92:95], v[128:131], v[196:199], v[92:95]
	v_mfma_f32_16x16x32_bf16 v[88:91], v[136:139], v[196:199], v[88:91]
	v_mfma_f32_16x16x32_bf16 v[76:79], v[128:131], v[206:209], v[76:79]
	v_mfma_f32_16x16x32_bf16 v[72:75], v[136:139], v[206:209], v[72:75]
	v_mfma_f32_16x16x32_bf16 v[124:127], v[132:135], v[164:167], v[124:127]
	v_mfma_f32_16x16x32_bf16 v[120:123], v[140:143], v[164:167], v[120:123]
	v_mfma_f32_16x16x32_bf16 v[108:111], v[132:135], v[172:175], v[108:111]
	v_mfma_f32_16x16x32_bf16 v[104:107], v[140:143], v[172:175], v[104:107]
	v_mfma_f32_16x16x32_bf16 v[92:95], v[132:135], v[202:205], v[92:95]
	v_mfma_f32_16x16x32_bf16 v[88:91], v[140:143], v[202:205], v[88:91]
	v_mfma_f32_16x16x32_bf16 v[76:79], v[132:135], v[232:235], v[76:79]
	v_mfma_f32_16x16x32_bf16 v[72:75], v[140:143], v[232:235], v[72:75]
	s_setprio 0
	s_setprio 1
	v_mfma_f32_16x16x32_bf16 v[116:119], v[144:147], v[160:163], v[116:119]
	v_mfma_f32_16x16x32_bf16 v[112:115], v[152:155], v[160:163], v[112:115]
	v_mfma_f32_16x16x32_bf16 v[100:103], v[144:147], v[168:171], v[100:103]
	v_mfma_f32_16x16x32_bf16 v[96:99], v[152:155], v[168:171], v[96:99]
	v_mfma_f32_16x16x32_bf16 v[84:87], v[144:147], v[196:199], v[84:87]
	v_mfma_f32_16x16x32_bf16 v[80:83], v[152:155], v[196:199], v[80:83]
	v_mfma_f32_16x16x32_bf16 v[68:71], v[144:147], v[206:209], v[68:71]
	v_mfma_f32_16x16x32_bf16 v[64:67], v[152:155], v[206:209], v[64:67]
	v_mfma_f32_16x16x32_bf16 v[116:119], v[148:151], v[164:167], v[116:119]
	v_mfma_f32_16x16x32_bf16 v[112:115], v[156:159], v[164:167], v[112:115]
	v_mfma_f32_16x16x32_bf16 v[100:103], v[148:151], v[172:175], v[100:103]
	v_mfma_f32_16x16x32_bf16 v[96:99], v[156:159], v[172:175], v[96:99]
	v_mfma_f32_16x16x32_bf16 v[84:87], v[148:151], v[202:205], v[84:87]
	v_mfma_f32_16x16x32_bf16 v[80:83], v[156:159], v[202:205], v[80:83]
	v_mfma_f32_16x16x32_bf16 v[68:71], v[148:151], v[232:235], v[68:71]
	v_mfma_f32_16x16x32_bf16 v[64:67], v[156:159], v[232:235], v[64:67]
	s_barrier
; #define PG8_STAGE(bufoff, gbase, voff) do { _Pragma("unroll") for (int _i = 0; _i < 2; ++_i) \
;         __builtin_amdgcn_global_load_lds((const unsigned*)((const char*)(gbase) + (voff)[_i]), (PG8_LAS unsigned*)(lds + (bufoff) + ldsw + _i * 8192), 16, 0, 0); } while (0)
; #define PG8_LDA(dst, b, h) do { _Pragma("unroll") for (int m = 0; m < 4; ++m) _Pragma("unroll") for (int k = 0; k < 2; ++k) dst[m][k] = *(const PG8_LAS bf16x8*)(lds + PG8_SA(b, h) + aoff + m * 2048 + k * 1024); } while (0)
; #define PG8_MMA(ai, bj, At, Bt) do { __builtin_amdgcn_s_setprio(1); _Pragma("unroll") for (int m = 0; m < 4; ++m) _Pragma("unroll") for (int n = 0; n < 2; ++n) _Pragma("unroll") for (int k = 0; k < 2; ++k) \
;         acc[ai][bj][m][n] = __builtin_amdgcn_mfma_f32_16x16x32_bf16(Bt[n][k], At[m][k], acc[ai][bj][m][n], 0, 0, 0); __builtin_amdgcn_s_setprio(0); } while (0)
; #define PG8_WAIT_V(n) asm volatile("s_waitcnt vmcnt(" #n ")" ::: "memory")
; #define PG8_WAIT_L(n) asm volatile("s_waitcnt lgkmcnt(" #n ")" ::: "memory")
; #define PG8_BAR __builtin_amdgcn_s_barrier()
; #define PG8_SCHED __builtin_amdgcn_sched_barrier(0)
; template <class Epi, class Sched, bool ALIGN_EPI = false, bool SP2 = false, bool DUAL = false>
; __device__ __forceinline__ void gemm_phase(PG8_LAS unsigned char* lds, const Gemm g, const Sched& S, const Epi& E) {
;     ...
;             PG8_LDA(At, 1, 1); PG8_STAGE(PG8_SB(1, 0), b3, voffB); PG8_STAGE(PG8_SB(1, 1), b3 + hstep, voffB); PG8_STAGE(PG8_SA(1, 0), a3, voffA);
;             PG8_WAIT_V(8); PG8_WAIT_L(0); PG8_BAR; PG8_MMA(1, 0, At, B0); PG8_MMA(1, 1, At, B1); PG8_BAR; PG8_SCHED;
;     ...
;         if constexpr (ALIGN_EPI) { if (wr == 0) PG8_BAR; }
	s_setprio 0
	s_add_i32 s16, s72, s26
	v_lshl_add_u64 v[222:223], v[222:223], 0, s[36:37]
	s_mov_b32 m0, s16
	ds_read_b128 v[160:163], v220 offset:49152
	ds_read_b128 v[164:167], v220 offset:50176
	ds_read_b128 v[168:171], v220 offset:51200
	ds_read_b128 v[172:175], v220 offset:52224
	ds_read_b128 v[196:199], v220 offset:53248
	ds_read_b128 v[202:205], v220 offset:54272
	ds_read_b128 v[206:209], v220 offset:55296
	ds_read_b128 v[232:235], v220 offset:56320
	global_load_lds_dwordx4 v[222:223], off
	s_add_i32 m0, s16, 0x2000
	s_add_u32 s14, s14, 0x80080
	v_lshl_add_u64 v[222:223], v[228:229], 0, s[36:37]
	s_addc_u32 s15, s15, 0
	s_add_i32 s16, s73, s26
	global_load_lds_dwordx4 v[222:223], off
	v_lshl_add_u64 v[222:223], s[14:15], 0, v[182:183]
	s_mov_b32 m0, s16
	s_nop 0
	global_load_lds_dwordx4 v[222:223], off
	v_lshl_add_u64 v[222:223], s[14:15], 0, v[186:187]
	s_add_i32 m0, s16, 0x2000
	s_nop 0
	global_load_lds_dwordx4 v[222:223], off
	v_lshl_add_u64 v[222:223], v[236:237], 0, s[36:37]
	s_mov_b32 m0, s44
	s_nop 0
	global_load_lds_dwordx4 v[222:223], off
	v_lshl_add_u64 v[222:223], v[238:239], 0, s[36:37]
	s_mov_b32 m0, s45
	s_nop 0
	global_load_lds_dwordx4 v[222:223], off
	s_waitcnt vmcnt(8)
	s_waitcnt lgkmcnt(0)
	s_setprio 1
	s_barrier
	v_mfma_f32_16x16x32_bf16 v[60:63], v[128:131], v[160:163], v[60:63]
	v_mfma_f32_16x16x32_bf16 v[56:59], v[136:139], v[160:163], v[56:59]
	v_mfma_f32_16x16x32_bf16 v[44:47], v[128:131], v[168:171], v[44:47]
	v_mfma_f32_16x16x32_bf16 v[40:43], v[136:139], v[168:171], v[40:43]
	v_mfma_f32_16x16x32_bf16 v[28:31], v[128:131], v[196:199], v[28:31]
	v_mfma_f32_16x16x32_bf16 v[24:27], v[136:139], v[196:199], v[24:27]
	v_mfma_f32_16x16x32_bf16 v[12:15], v[128:131], v[206:209], v[12:15]
	v_mfma_f32_16x16x32_bf16 v[8:11], v[136:139], v[206:209], v[8:11]
	v_mfma_f32_16x16x32_bf16 v[60:63], v[132:135], v[164:167], v[60:63]
	v_mfma_f32_16x16x32_bf16 v[56:59], v[140:143], v[164:167], v[56:59]
	v_mfma_f32_16x16x32_bf16 v[44:47], v[132:135], v[172:175], v[44:47]
	v_mfma_f32_16x16x32_bf16 v[40:43], v[140:143], v[172:175], v[40:43]
	v_mfma_f32_16x16x32_bf16 v[28:31], v[132:135], v[202:205], v[28:31]
	v_mfma_f32_16x16x32_bf16 v[24:27], v[140:143], v[202:205], v[24:27]
	v_mfma_f32_16x16x32_bf16 v[12:15], v[132:135], v[232:235], v[12:15]
	v_mfma_f32_16x16x32_bf16 v[8:11], v[140:143], v[232:235], v[8:11]
	s_setprio 0
	s_setprio 1
	v_mfma_f32_16x16x32_bf16 v[52:55], v[144:147], v[160:163], v[52:55]
	v_mfma_f32_16x16x32_bf16 v[48:51], v[152:155], v[160:163], v[48:51]
	v_mfma_f32_16x16x32_bf16 v[36:39], v[144:147], v[168:171], v[36:39]
	v_mfma_f32_16x16x32_bf16 v[32:35], v[152:155], v[168:171], v[32:35]
	v_mfma_f32_16x16x32_bf16 v[20:23], v[144:147], v[196:199], v[20:23]
	v_mfma_f32_16x16x32_bf16 v[16:19], v[152:155], v[196:199], v[16:19]
	v_mfma_f32_16x16x32_bf16 v[4:7], v[144:147], v[206:209], v[4:7]
	v_mfma_f32_16x16x32_bf16 v[0:3], v[152:155], v[206:209], v[0:3]
	v_mfma_f32_16x16x32_bf16 v[52:55], v[148:151], v[164:167], v[52:55]
	v_mfma_f32_16x16x32_bf16 v[48:51], v[156:159], v[164:167], v[48:51]
	v_mfma_f32_16x16x32_bf16 v[36:39], v[148:151], v[172:175], v[36:39]
	v_mfma_f32_16x16x32_bf16 v[32:35], v[156:159], v[172:175], v[32:35]
	v_mfma_f32_16x16x32_bf16 v[20:23], v[148:151], v[202:205], v[20:23]
	v_mfma_f32_16x16x32_bf16 v[16:19], v[156:159], v[202:205], v[16:19]
	v_mfma_f32_16x16x32_bf16 v[4:7], v[148:151], v[232:235], v[4:7]
	v_mfma_f32_16x16x32_bf16 v[0:3], v[156:159], v[232:235], v[0:3]
	s_barrier
	s_setprio 0
	s_add_i32 s71, s71, 2
	s_add_u32 s68, s68, 0x100
	s_addc_u32 s69, s69, 0
	s_add_u32 s67, s67, 0x100
	s_addc_u32 s70, s70, 0
	s_cmp_gt_u32 s71, 29
	s_cbranch_scc0 .LBB0_896
	s_and_b64 vcc, exec, s[38:39]
	s_cbranch_vccz .LBB0_899
	s_barrier

;     __device__ bool next(int i, Unit& u) const { if (!base.next(i >> 1, u)) return false; u.sub = i & 1; return true; }
; #define PG8_STAGE(bufoff, gbase, voff) do { _Pragma("unroll") for (int _i = 0; _i < 2; ++_i) \
;         __builtin_amdgcn_global_load_lds((const unsigned*)((const char*)(gbase) + (voff)[_i]), (PG8_LAS unsigned*)(lds + (bufoff) + ldsw + _i * 8192), 16, 0, 0); } while (0)
; #define PG8_LDA(dst, b, h) do { _Pragma("unroll") for (int m = 0; m < 4; ++m) _Pragma("unroll") for (int k = 0; k < 2; ++k) dst[m][k] = *(const PG8_LAS bf16x8*)(lds + PG8_SA(b, h) + aoff + m * 2048 + k * 1024); } while (0)
; #define PG8_LDB(dst, b, h) do { _Pragma("unroll") for (int n = 0; n < 2; ++n) _Pragma("unroll") for (int k = 0; k < 2; ++k) dst[n][k] = *(const PG8_LAS bf16x8*)(lds + PG8_SB(b, h) + boff + n * 2048 + k * 1024); } while (0)
; #define PG8_WAIT_V(n) asm volatile("s_waitcnt vmcnt(" #n ")" ::: "memory")
; template <class Epi, class Sched, bool ALIGN_EPI = false, bool SP2 = false, bool DUAL = false>
; __device__ __forceinline__ void gemm_phase(PG8_LAS unsigned char* lds, const Gemm g, const Sched& S, const Epi& E) {
;     ...
;         const bool has_next = S.next(ui + 1, nxt);
;         const char* nA = has_next ? (const char*)((DUAL && nxt.sub) ? g.A2 : g.A) + (size_t)nxt.pm * tstep : cA; const char* nB = has_next ? (const char*)((DUAL && nxt.sub) ? g.Bt2 : g.Bt) + (size_t)nxt.pn * tstep : cB;
;         for (int t = 0; t < nt; t += 2) {
;             const bool last = (t == nt - 2);
;             const char* a1 = cA + (size_t)(t + 1) * kstep;
;             const char* a2 = last ? nA : cA + (size_t)(t + 2) * kstep; const char* b2 = last ? nB : cB + (size_t)(t + 2) * kstep;
;             const char* a3 = a2 + kstep; const char* b3 = b2 + kstep;
;             if (last && has_next) S.a_ready(nxt);
;             if constexpr (SP2) {
;             PG8_LDB(B0, 0, 0); PG8_LDB(B1, 0, 1); PG8_SCHED; PG8_LDA(At, 0, 0); PG8_STAGE(PG8_SA(1, 1), a1 + hstep, voffA);
;             PG8_WAIT_V(8); PG8_WAIT_L(0); PG8_BAR; PG8_MMA(0, 0, At, B0); PG8_MMA(0, 1, At, B1); PG8_BAR; PG8_SCHED;
;             PG8_LDA(At, 0, 1); PG8_STAGE(PG8_SB(0, 0), b2, voffB); PG8_STAGE(PG8_SB(0, 1), b2 + hstep, voffB); PG8_STAGE(PG8_SA(0, 0), a2, voffA);
;             PG8_WAIT_V(8); PG8_WAIT_L(0); PG8_BAR; PG8_MMA(1, 0, At, B0); PG8_MMA(1, 1, At, B1); PG8_BAR; PG8_SCHED;
.LBB0_991:
	s_ashr_i32 s25, s24, 31
	s_lshl_b64 s[28:29], s[24:25], 20
	s_add_u32 s30, s19, s28
	s_addc_u32 s31, s21, s29
	s_and_b64 s[28:29], s[4:5], exec
	s_cselect_b32 s25, s31, s27
	s_cselect_b32 s28, s30, s26
	s_ashr_i32 s23, s22, 31
	s_lshl_b64 s[36:37], s[22:23], 20
	s_add_u32 s36, s8, s36
	s_addc_u32 s37, s9, s37
	s_and_b64 s[40:41], s[4:5], exec
	s_cselect_b32 s23, s37, s15
	s_cselect_b32 s29, s36, s14
	s_add_u32 s40, s26, 0x80080
	s_addc_u32 s41, s27, 0
	s_add_u32 s63, s14, 0x100
	s_addc_u32 s64, s15, 0
	s_mov_b32 s65, -2
	ds_read_b128 v[128:131], v215
	ds_read_b128 v[132:135], v215 offset:1024
	ds_read_b128 v[136:139], v215 offset:2048
	ds_read_b128 v[140:143], v215 offset:3072
	ds_read_b128 v[144:147], v216
	ds_read_b128 v[148:151], v216 offset:1024
	ds_read_b128 v[152:155], v216 offset:2048
	ds_read_b128 v[156:159], v216 offset:3072
	s_add_u32 s14, s40, 0xfff80080
	s_addc_u32 s15, s41, -1
	s_cmp_eq_u32 s65, 28
	s_cselect_b32 s27, s25, s15
	s_cselect_b32 s26, s28, s14
	s_cselect_b32 s15, s23, s64
	s_cselect_b32 s14, s29, s63
	v_lshl_add_u64 v[228:229], s[40:41], 0, v[180:181]
	s_add_i32 m0, s39, 0xc000
	ds_read_b128 v[160:163], v217
	ds_read_b128 v[164:167], v217 offset:1024
	ds_read_b128 v[188:191], v217 offset:2048
	ds_read_b128 v[192:195], v217 offset:3072
	ds_read_b128 v[196:199], v217 offset:4096
	ds_read_b128 v[202:205], v217 offset:5120
	ds_read_b128 v[206:209], v217 offset:6144
	ds_read_b128 v[220:223], v217 offset:7168
	global_load_lds_dwordx4 v[228:229], off
	v_lshl_add_u64 v[228:229], s[40:41], 0, v[182:183]
	s_add_i32 m0, s39, 0xe000
	s_nop 0
	global_load_lds_dwordx4 v[228:229], off
	s_waitcnt vmcnt(8)
	s_waitcnt lgkmcnt(0)
	s_setprio 1
	s_barrier
	v_mfma_f32_16x16x32_bf16 v[124:127], v[128:131], v[160:163], 0
	v_mfma_f32_16x16x32_bf16 v[120:123], v[136:139], v[160:163], 0
	v_mfma_f32_16x16x32_bf16 v[108:111], v[128:131], v[188:191], 0
	v_mfma_f32_16x16x32_bf16 v[104:107], v[136:139], v[188:191], 0
	v_mfma_f32_16x16x32_bf16 v[92:95], v[128:131], v[196:199], 0
	v_mfma_f32_16x16x32_bf16 v[88:91], v[136:139], v[196:199], 0
	v_mfma_f32_16x16x32_bf16 v[76:79], v[128:131], v[206:209], 0
	v_mfma_f32_16x16x32_bf16 v[72:75], v[136:139], v[206:209], 0
	v_mfma_f32_16x16x32_bf16 v[124:127], v[132:135], v[164:167], v[124:127]
	v_mfma_f32_16x16x32_bf16 v[120:123], v[140:143], v[164:167], v[120:123]
	v_mfma_f32_16x16x32_bf16 v[108:111], v[132:135], v[192:195], v[108:111]
	v_mfma_f32_16x16x32_bf16 v[104:107], v[140:143], v[192:195], v[104:107]
	v_mfma_f32_16x16x32_bf16 v[92:95], v[132:135], v[202:205], v[92:95]
	v_mfma_f32_16x16x32_bf16 v[88:91], v[140:143], v[202:205], v[88:91]
	v_mfma_f32_16x16x32_bf16 v[76:79], v[132:135], v[220:223], v[76:79]
	v_mfma_f32_16x16x32_bf16 v[72:75], v[140:143], v[220:223], v[72:75]
	s_setprio 0
	s_setprio 1
	v_mfma_f32_16x16x32_bf16 v[116:119], v[144:147], v[160:163], 0
	v_mfma_f32_16x16x32_bf16 v[112:115], v[152:155], v[160:163], 0
	v_mfma_f32_16x16x32_bf16 v[100:103], v[144:147], v[188:191], 0
	v_mfma_f32_16x16x32_bf16 v[96:99], v[152:155], v[188:191], 0
	v_mfma_f32_16x16x32_bf16 v[84:87], v[144:147], v[196:199], 0
	v_mfma_f32_16x16x32_bf16 v[80:83], v[152:155], v[196:199], 0
	v_mfma_f32_16x16x32_bf16 v[68:71], v[144:147], v[206:209], 0
	v_mfma_f32_16x16x32_bf16 v[64:67], v[152:155], v[206:209], 0
	v_mfma_f32_16x16x32_bf16 v[116:119], v[148:151], v[164:167], v[116:119]
	v_mfma_f32_16x16x32_bf16 v[112:115], v[156:159], v[164:167], v[112:115]
	v_mfma_f32_16x16x32_bf16 v[100:103], v[148:151], v[192:195], v[100:103]
	v_mfma_f32_16x16x32_bf16 v[96:99], v[156:159], v[192:195], v[96:99]
	v_mfma_f32_16x16x32_bf16 v[84:87], v[148:151], v[202:205], v[84:87]
	v_mfma_f32_16x16x32_bf16 v[80:83], v[156:159], v[202:205], v[80:83]
	v_mfma_f32_16x16x32_bf16 v[68:71], v[148:151], v[220:223], v[68:71]
	v_mfma_f32_16x16x32_bf16 v[64:67], v[156:159], v[220:223], v[64:67]
	s_barrier
	s_setprio 0
	s_add_i32 s66, s50, s34
	v_lshl_add_u64 v[228:229], s[14:15], 0, v[170:171]
	s_mov_b32 m0, s66
	ds_read_b128 v[160:163], v217 offset:16384
	ds_read_b128 v[164:167], v217 offset:17408
	ds_read_b128 v[188:191], v217 offset:18432
	ds_read_b128 v[192:195], v217 offset:19456
	ds_read_b128 v[196:199], v217 offset:20480
	ds_read_b128 v[202:205], v217 offset:21504
	ds_read_b128 v[206:209], v217 offset:22528
	ds_read_b128 v[220:223], v217 offset:23552
	global_load_lds_dwordx4 v[228:229], off
	s_add_i32 m0, s66, 0x2000
	s_add_u32 s66, s14, 0x80000
	v_lshl_add_u64 v[232:233], s[14:15], 0, v[174:175]
	s_addc_u32 s67, s15, 0
	s_add_i32 s68, s51, s34
	global_load_lds_dwordx4 v[232:233], off
	v_lshl_add_u64 v[234:235], s[66:67], 0, v[170:171]
	s_mov_b32 m0, s68
	v_lshl_add_u64 v[236:237], s[26:27], 0, v[172:173]
	global_load_lds_dwordx4 v[234:235], off
	v_lshl_add_u64 v[234:235], s[66:67], 0, v[174:175]
	s_add_i32 m0, s68, 0x2000
	s_nop 0
	global_load_lds_dwordx4 v[234:235], off
	v_lshl_add_u64 v[234:235], s[26:27], 0, v[168:169]
	s_mov_b32 m0, s39
	s_nop 0
	global_load_lds_dwordx4 v[234:235], off
	s_mov_b32 m0, s42
	s_nop 0
	global_load_lds_dwordx4 v[236:237], off
	s_waitcnt vmcnt(8)
	s_waitcnt lgkmcnt(0)
	s_setprio 1
	s_barrier
; #define PG8_STAGE(bufoff, gbase, voff) do { _Pragma("unroll") for (int _i = 0; _i < 2; ++_i) \
;         __builtin_amdgcn_global_load_lds((const unsigned*)((const char*)(gbase) + (voff)[_i]), (PG8_LAS unsigned*)(lds + (bufoff) + ldsw + _i * 8192), 16, 0, 0); } while (0)
; #define PG8_LDA(dst, b, h) do { _Pragma("unroll") for (int m = 0; m < 4; ++m) _Pragma("unroll") for (int k = 0; k < 2; ++k) dst[m][k] = *(const PG8_LAS bf16x8*)(lds + PG8_SA(b, h) + aoff + m * 2048 + k * 1024); } while (0)
; #define PG8_LDB(dst, b, h) do { _Pragma("unroll") for (int n = 0; n < 2; ++n) _Pragma("unroll") for (int k = 0; k < 2; ++k) dst[n][k] = *(const PG8_LAS bf16x8*)(lds + PG8_SB(b, h) + boff + n * 2048 + k * 1024); } while (0)
; #define PG8_MMA(ai, bj, At, Bt) do { __builtin_amdgcn_s_setprio(1); _Pragma("unroll") for (int m = 0; m < 4; ++m) _Pragma("unroll") for (int n = 0; n < 2; ++n) _Pragma("unroll") for (int k = 0; k < 2; ++k) \
;         acc[ai][bj][m][n] = __builtin_amdgcn_mfma_f32_16x16x32_bf16(Bt[n][k], At[m][k], acc[ai][bj][m][n], 0, 0, 0); __builtin_amdgcn_s_setprio(0); } while (0)
; #define PG8_WAIT_V(n) asm volatile("s_waitcnt vmcnt(" #n ")" ::: "memory")
; #define PG8_WAIT_L(n) asm volatile("s_waitcnt lgkmcnt(" #n ")" ::: "memory")
; #define PG8_BAR __builtin_amdgcn_s_barrier()
; #define PG8_SCHED __builtin_amdgcn_sched_barrier(0)
; template <class Epi, class Sched, bool ALIGN_EPI = false, bool SP2 = false, bool DUAL = false>
; __device__ __forceinline__ void gemm_phase(PG8_LAS unsigned char* lds, const Gemm g, const Sched& S, const Epi& E) {
;     ...
;             PG8_WAIT_V(8); PG8_WAIT_L(0); PG8_BAR; PG8_MMA(1, 0, At, B0); PG8_MMA(1, 1, At, B1); PG8_BAR; PG8_SCHED;
;             PG8_LDB(B0, 1, 0); PG8_LDB(B1, 1, 1); PG8_SCHED; PG8_LDA(At, 1, 0); PG8_STAGE(PG8_SA(0, 1), a2 + hstep, voffA);
;             PG8_WAIT_V(8); PG8_WAIT_L(0); PG8_BAR; PG8_MMA(0, 0, At, B0); PG8_MMA(0, 1, At, B1); PG8_BAR; PG8_SCHED;
	v_mfma_f32_16x16x32_bf16 v[60:63], v[128:131], v[160:163], 0
	v_mfma_f32_16x16x32_bf16 v[56:59], v[136:139], v[160:163], 0
	v_mfma_f32_16x16x32_bf16 v[44:47], v[128:131], v[188:191], 0
	v_mfma_f32_16x16x32_bf16 v[40:43], v[136:139], v[188:191], 0
	v_mfma_f32_16x16x32_bf16 v[28:31], v[128:131], v[196:199], 0
	v_mfma_f32_16x16x32_bf16 v[24:27], v[136:139], v[196:199], 0
	v_mfma_f32_16x16x32_bf16 v[12:15], v[128:131], v[206:209], 0
	v_mfma_f32_16x16x32_bf16 v[8:11], v[136:139], v[206:209], 0
	v_mfma_f32_16x16x32_bf16 v[60:63], v[132:135], v[164:167], v[60:63]
	v_mfma_f32_16x16x32_bf16 v[56:59], v[140:143], v[164:167], v[56:59]
	v_mfma_f32_16x16x32_bf16 v[44:47], v[132:135], v[192:195], v[44:47]
	v_mfma_f32_16x16x32_bf16 v[40:43], v[140:143], v[192:195], v[40:43]
	v_mfma_f32_16x16x32_bf16 v[28:31], v[132:135], v[202:205], v[28:31]
	v_mfma_f32_16x16x32_bf16 v[24:27], v[140:143], v[202:205], v[24:27]
	v_mfma_f32_16x16x32_bf16 v[12:15], v[132:135], v[220:223], v[12:15]
	v_mfma_f32_16x16x32_bf16 v[8:11], v[140:143], v[220:223], v[8:11]
	s_setprio 0
	s_setprio 1
	v_mfma_f32_16x16x32_bf16 v[52:55], v[144:147], v[160:163], 0
	v_mfma_f32_16x16x32_bf16 v[48:51], v[152:155], v[160:163], 0
	v_mfma_f32_16x16x32_bf16 v[36:39], v[144:147], v[188:191], 0
	v_mfma_f32_16x16x32_bf16 v[32:35], v[152:155], v[188:191], 0
	v_mfma_f32_16x16x32_bf16 v[20:23], v[144:147], v[196:199], 0
	v_mfma_f32_16x16x32_bf16 v[16:19], v[152:155], v[196:199], 0
	v_mfma_f32_16x16x32_bf16 v[4:7], v[144:147], v[206:209], 0
	v_mfma_f32_16x16x32_bf16 v[0:3], v[152:155], v[206:209], 0
	v_mfma_f32_16x16x32_bf16 v[52:55], v[148:151], v[164:167], v[52:55]
	v_mfma_f32_16x16x32_bf16 v[48:51], v[156:159], v[164:167], v[48:51]
	v_mfma_f32_16x16x32_bf16 v[36:39], v[148:151], v[192:195], v[36:39]
	v_mfma_f32_16x16x32_bf16 v[32:35], v[156:159], v[192:195], v[32:35]
	v_mfma_f32_16x16x32_bf16 v[20:23], v[148:151], v[202:205], v[20:23]
	v_mfma_f32_16x16x32_bf16 v[16:19], v[156:159], v[202:205], v[16:19]
	v_mfma_f32_16x16x32_bf16 v[4:7], v[148:151], v[220:223], v[4:7]
	v_mfma_f32_16x16x32_bf16 v[0:3], v[156:159], v[220:223], v[0:3]
	s_barrier
	s_setprio 0
	s_add_i32 s66, 0, 0x18000
	s_add_i32 s67, 0, 0x1c000
	v_add_u32_e32 v140, s66, v213
	v_add_u32_e32 v156, s67, v213
	ds_read_b128 v[128:131], v140
	ds_read_b128 v[132:135], v140 offset:1024
	ds_read_b128 v[136:139], v140 offset:2048
	ds_read_b128 v[140:143], v140 offset:3072
	ds_read_b128 v[144:147], v156
	ds_read_b128 v[148:151], v156 offset:1024
	ds_read_b128 v[152:155], v156 offset:2048
	ds_read_b128 v[156:159], v156 offset:3072
	s_add_u32 s26, s26, 0x80000
	s_addc_u32 s27, s27, 0
	s_mov_b32 m0, s43
	v_lshl_add_u64 v[238:239], s[26:27], 0, v[168:169]
	ds_read_b128 v[160:163], v217 offset:32768
	ds_read_b128 v[164:167], v217 offset:33792
	ds_read_b128 v[188:191], v217 offset:34816
	ds_read_b128 v[192:195], v217 offset:35840
	ds_read_b128 v[196:199], v217 offset:36864
	ds_read_b128 v[202:205], v217 offset:37888
	ds_read_b128 v[206:209], v217 offset:38912
	ds_read_b128 v[220:223], v217 offset:39936
	global_load_lds_dwordx4 v[238:239], off
	v_lshl_add_u64 v[238:239], s[26:27], 0, v[172:173]
	s_mov_b32 m0, s44
	s_nop 0
	global_load_lds_dwordx4 v[238:239], off
	s_waitcnt vmcnt(8)
	s_waitcnt lgkmcnt(0)
	s_setprio 1
	s_barrier
	v_mfma_f32_16x16x32_bf16 v[124:127], v[128:131], v[160:163], v[124:127]
	v_mfma_f32_16x16x32_bf16 v[120:123], v[136:139], v[160:163], v[120:123]
	v_mfma_f32_16x16x32_bf16 v[108:111], v[128:131], v[188:191], v[108:111]
	v_mfma_f32_16x16x32_bf16 v[104:107], v[136:139], v[188:191], v[104:107]
	v_mfma_f32_16x16x32_bf16 v[92:95], v[128:131], v[196:199], v[92:95]
	v_mfma_f32_16x16x32_bf16 v[88:91], v[136:139], v[196:199], v[88:91]
	v_mfma_f32_16x16x32_bf16 v[76:79], v[128:131], v[206:209], v[76:79]
	v_mfma_f32_16x16x32_bf16 v[72:75], v[136:139], v[206:209], v[72:75]
	v_mfma_f32_16x16x32_bf16 v[124:127], v[132:135], v[164:167], v[124:127]
	v_mfma_f32_16x16x32_bf16 v[120:123], v[140:143], v[164:167], v[120:123]
	v_mfma_f32_16x16x32_bf16 v[108:111], v[132:135], v[192:195], v[108:111]
	v_mfma_f32_16x16x32_bf16 v[104:107], v[140:143], v[192:195], v[104:107]
	v_mfma_f32_16x16x32_bf16 v[92:95], v[132:135], v[202:205], v[92:95]
	v_mfma_f32_16x16x32_bf16 v[88:91], v[140:143], v[202:205], v[88:91]
	v_mfma_f32_16x16x32_bf16 v[76:79], v[132:135], v[220:223], v[76:79]
	v_mfma_f32_16x16x32_bf16 v[72:75], v[140:143], v[220:223], v[72:75]
	s_setprio 0
	s_setprio 1
	v_mfma_f32_16x16x32_bf16 v[116:119], v[144:147], v[160:163], v[116:119]
	v_mfma_f32_16x16x32_bf16 v[112:115], v[152:155], v[160:163], v[112:115]
	v_mfma_f32_16x16x32_bf16 v[100:103], v[144:147], v[188:191], v[100:103]
	v_mfma_f32_16x16x32_bf16 v[96:99], v[152:155], v[188:191], v[96:99]
	v_mfma_f32_16x16x32_bf16 v[84:87], v[144:147], v[196:199], v[84:87]
	v_mfma_f32_16x16x32_bf16 v[80:83], v[152:155], v[196:199], v[80:83]
	v_mfma_f32_16x16x32_bf16 v[68:71], v[144:147], v[206:209], v[68:71]
	v_mfma_f32_16x16x32_bf16 v[64:67], v[152:155], v[206:209], v[64:67]
	v_mfma_f32_16x16x32_bf16 v[116:119], v[148:151], v[164:167], v[116:119]
	v_mfma_f32_16x16x32_bf16 v[112:115], v[156:159], v[164:167], v[112:115]
	v_mfma_f32_16x16x32_bf16 v[100:103], v[148:151], v[192:195], v[100:103]
	v_mfma_f32_16x16x32_bf16 v[96:99], v[156:159], v[192:195], v[96:99]
	v_mfma_f32_16x16x32_bf16 v[84:87], v[148:151], v[202:205], v[84:87]
	v_mfma_f32_16x16x32_bf16 v[80:83], v[156:159], v[202:205], v[80:83]
	v_mfma_f32_16x16x32_bf16 v[68:71], v[148:151], v[220:223], v[68:71]
	v_mfma_f32_16x16x32_bf16 v[64:67], v[156:159], v[220:223], v[64:67]
	s_barrier
; #define PG8_STAGE(bufoff, gbase, voff) do { _Pragma("unroll") for (int _i = 0; _i < 2; ++_i) \
;         __builtin_amdgcn_global_load_lds((const unsigned*)((const char*)(gbase) + (voff)[_i]), (PG8_LAS unsigned*)(lds + (bufoff) + ldsw + _i * 8192), 16, 0, 0); } while (0)
; #define PG8_LDA(dst, b, h) do { _Pragma("unroll") for (int m = 0; m < 4; ++m) _Pragma("unroll") for (int k = 0; k < 2; ++k) dst[m][k] = *(const PG8_LAS bf16x8*)(lds + PG8_SA(b, h) + aoff + m * 2048 + k * 1024); } while (0)
; #define PG8_LDB(dst, b, h) do { _Pragma("unroll") for (int n = 0; n < 2; ++n) _Pragma("unroll") for (int k = 0; k < 2; ++k) dst[n][k] = *(const PG8_LAS bf16x8*)(lds + PG8_SB(b, h) + boff + n * 2048 + k * 1024); } while (0)
; #define PG8_MMA(ai, bj, At, Bt) do { __builtin_amdgcn_s_setprio(1); _Pragma("unroll") for (int m = 0; m < 4; ++m) _Pragma("unroll") for (int n = 0; n < 2; ++n) _Pragma("unroll") for (int k = 0; k < 2; ++k) \
;         acc[ai][bj][m][n] = __builtin_amdgcn_mfma_f32_16x16x32_bf16(Bt[n][k], At[m][k], acc[ai][bj][m][n], 0, 0, 0); __builtin_amdgcn_s_setprio(0); } while (0)
; #define PG8_BAR __builtin_amdgcn_s_barrier()
; template <class Epi, class Sched, bool ALIGN_EPI = false, bool SP2 = false, bool DUAL = false>
; __device__ __forceinline__ void gemm_phase(PG8_LAS unsigned char* lds, const Gemm g, const Sched& S, const Epi& E) {
;     ...
;             PG8_LDB(B0, 0, 0); PG8_LDB(B1, 0, 1); PG8_SCHED; PG8_LDA(At, 0, 0); PG8_STAGE(PG8_SA(1, 1), a1 + hstep, voffA);
;             PG8_WAIT_V(8); PG8_WAIT_L(0); PG8_BAR; PG8_MMA(0, 0, At, B0); PG8_MMA(0, 1, At, B1); PG8_BAR; PG8_SCHED;
;             PG8_LDA(At, 0, 1); PG8_STAGE(PG8_SB(0, 0), b2, voffB); PG8_STAGE(PG8_SB(0, 1), b2 + hstep, voffB); PG8_STAGE(PG8_SA(0, 0), a2, voffA);
;             PG8_WAIT_V(8); PG8_WAIT_L(0); PG8_BAR; PG8_MMA(1, 0, At, B0); PG8_MMA(1, 1, At, B1); PG8_BAR; PG8_SCHED;
;             PG8_LDB(B0, 1, 0); PG8_LDB(B1, 1, 1); PG8_SCHED; PG8_LDA(At, 1, 0); PG8_STAGE(PG8_SA(0, 1), a2 + hstep, voffA);
;             PG8_WAIT_V(8); PG8_WAIT_L(0); PG8_BAR; PG8_MMA(0, 0, At, B0); PG8_MMA(0, 1, At, B1); PG8_BAR; PG8_SCHED;
;             PG8_LDA(At, 1, 1); PG8_STAGE(PG8_SB(1, 0), b3, voffB); PG8_STAGE(PG8_SB(1, 1), b3 + hstep, voffB); PG8_STAGE(PG8_SA(1, 0), a3, voffA);
;             PG8_WAIT_V(8); PG8_WAIT_L(0); PG8_BAR; PG8_MMA(1, 0, At, B0); PG8_MMA(1, 1, At, B1); PG8_BAR; PG8_SCHED;
	s_setprio 0
	s_add_i32 s26, s66, s34
	v_lshl_add_u64 v[228:229], v[228:229], 0, s[12:13]
	s_mov_b32 m0, s26
	ds_read_b128 v[160:163], v217 offset:49152
	ds_read_b128 v[164:167], v217 offset:50176
	ds_read_b128 v[188:191], v217 offset:51200
	ds_read_b128 v[192:195], v217 offset:52224
	ds_read_b128 v[196:199], v217 offset:53248
	ds_read_b128 v[202:205], v217 offset:54272
	ds_read_b128 v[206:209], v217 offset:55296
	ds_read_b128 v[220:223], v217 offset:56320
	global_load_lds_dwordx4 v[228:229], off
	s_add_i32 m0, s26, 0x2000
	s_add_u32 s14, s14, 0x80080
	v_lshl_add_u64 v[228:229], v[232:233], 0, s[12:13]
	s_addc_u32 s15, s15, 0
	s_add_i32 s26, s67, s34
	global_load_lds_dwordx4 v[228:229], off
	v_lshl_add_u64 v[228:229], s[14:15], 0, v[170:171]
	s_mov_b32 m0, s26
	s_nop 0
	global_load_lds_dwordx4 v[228:229], off
	v_lshl_add_u64 v[228:229], s[14:15], 0, v[174:175]
	s_add_i32 m0, s26, 0x2000
	s_nop 0
	global_load_lds_dwordx4 v[228:229], off
	v_lshl_add_u64 v[228:229], v[234:235], 0, s[12:13]
	s_mov_b32 m0, s47
	s_nop 0
	global_load_lds_dwordx4 v[228:229], off
	v_lshl_add_u64 v[228:229], v[236:237], 0, s[12:13]
	s_mov_b32 m0, s48
	s_nop 0
	global_load_lds_dwordx4 v[228:229], off
	s_waitcnt vmcnt(8)
	s_waitcnt lgkmcnt(0)
	s_setprio 1
	s_barrier
	v_mfma_f32_16x16x32_bf16 v[60:63], v[128:131], v[160:163], v[60:63]
	v_mfma_f32_16x16x32_bf16 v[56:59], v[136:139], v[160:163], v[56:59]
	v_mfma_f32_16x16x32_bf16 v[44:47], v[128:131], v[188:191], v[44:47]
	v_mfma_f32_16x16x32_bf16 v[40:43], v[136:139], v[188:191], v[40:43]
	v_mfma_f32_16x16x32_bf16 v[28:31], v[128:131], v[196:199], v[28:31]
	v_mfma_f32_16x16x32_bf16 v[24:27], v[136:139], v[196:199], v[24:27]
	v_mfma_f32_16x16x32_bf16 v[12:15], v[128:131], v[206:209], v[12:15]
	v_mfma_f32_16x16x32_bf16 v[8:11], v[136:139], v[206:209], v[8:11]
	v_mfma_f32_16x16x32_bf16 v[60:63], v[132:135], v[164:167], v[60:63]
	v_mfma_f32_16x16x32_bf16 v[56:59], v[140:143], v[164:167], v[56:59]
	v_mfma_f32_16x16x32_bf16 v[44:47], v[132:135], v[192:195], v[44:47]
	v_mfma_f32_16x16x32_bf16 v[40:43], v[140:143], v[192:195], v[40:43]
	v_mfma_f32_16x16x32_bf16 v[28:31], v[132:135], v[202:205], v[28:31]
	v_mfma_f32_16x16x32_bf16 v[24:27], v[140:143], v[202:205], v[24:27]
	v_mfma_f32_16x16x32_bf16 v[12:15], v[132:135], v[220:223], v[12:15]
	v_mfma_f32_16x16x32_bf16 v[8:11], v[140:143], v[220:223], v[8:11]
	s_setprio 0
	s_setprio 1
	v_mfma_f32_16x16x32_bf16 v[52:55], v[144:147], v[160:163], v[52:55]
	v_mfma_f32_16x16x32_bf16 v[48:51], v[152:155], v[160:163], v[48:51]
	v_mfma_f32_16x16x32_bf16 v[36:39], v[144:147], v[188:191], v[36:39]
	v_mfma_f32_16x16x32_bf16 v[32:35], v[152:155], v[188:191], v[32:35]
	v_mfma_f32_16x16x32_bf16 v[20:23], v[144:147], v[196:199], v[20:23]
	v_mfma_f32_16x16x32_bf16 v[16:19], v[152:155], v[196:199], v[16:19]
	v_mfma_f32_16x16x32_bf16 v[4:7], v[144:147], v[206:209], v[4:7]
	v_mfma_f32_16x16x32_bf16 v[0:3], v[152:155], v[206:209], v[0:3]
	v_mfma_f32_16x16x32_bf16 v[52:55], v[148:151], v[164:167], v[52:55]
	v_mfma_f32_16x16x32_bf16 v[48:51], v[156:159], v[164:167], v[48:51]
	v_mfma_f32_16x16x32_bf16 v[36:39], v[148:151], v[192:195], v[36:39]
	v_mfma_f32_16x16x32_bf16 v[32:35], v[156:159], v[192:195], v[32:35]
	v_mfma_f32_16x16x32_bf16 v[20:23], v[148:151], v[202:205], v[20:23]
	v_mfma_f32_16x16x32_bf16 v[16:19], v[156:159], v[202:205], v[16:19]
	v_mfma_f32_16x16x32_bf16 v[4:7], v[148:151], v[220:223], v[4:7]
	v_mfma_f32_16x16x32_bf16 v[0:3], v[156:159], v[220:223], v[0:3]
	s_barrier
	s_setprio 0
	s_add_i32 s65, s65, 2
	s_add_u32 s40, s40, 0x100
	s_addc_u32 s41, s41, 0
	s_add_u32 s63, s63, 0x100
	s_addc_u32 s64, s64, 0
.LBB0_992:
	ds_read_b128 v[128:131], v215
	ds_read_b128 v[132:135], v215 offset:1024
	ds_read_b128 v[136:139], v215 offset:2048
	ds_read_b128 v[140:143], v215 offset:3072
	ds_read_b128 v[144:147], v216
	ds_read_b128 v[148:151], v216 offset:1024
	ds_read_b128 v[152:155], v216 offset:2048
	ds_read_b128 v[156:159], v216 offset:3072
	s_add_u32 s14, s40, 0xfff80080
	s_addc_u32 s15, s41, -1
	s_cmp_eq_u32 s65, 28
	s_cselect_b32 s27, s25, s15
	s_cselect_b32 s26, s28, s14
	s_cselect_b32 s15, s23, s64
	s_cselect_b32 s14, s29, s63
	v_lshl_add_u64 v[228:229], s[40:41], 0, v[180:181]
	s_add_i32 m0, s39, 0xc000
	ds_read_b128 v[160:163], v217
	ds_read_b128 v[164:167], v217 offset:1024
	ds_read_b128 v[188:191], v217 offset:2048
	ds_read_b128 v[192:195], v217 offset:3072
	ds_read_b128 v[196:199], v217 offset:4096
	ds_read_b128 v[202:205], v217 offset:5120
	ds_read_b128 v[206:209], v217 offset:6144
	ds_read_b128 v[220:223], v217 offset:7168
	global_load_lds_dwordx4 v[228:229], off
	v_lshl_add_u64 v[228:229], s[40:41], 0, v[182:183]
	s_add_i32 m0, s39, 0xe000
	s_nop 0
	global_load_lds_dwordx4 v[228:229], off
	s_waitcnt vmcnt(8)
	s_waitcnt lgkmcnt(0)
	s_setprio 1
	s_barrier
; #define PG8_STAGE(bufoff, gbase, voff) do { _Pragma("unroll") for (int _i = 0; _i < 2; ++_i) \
;         __builtin_amdgcn_global_load_lds((const unsigned*)((const char*)(gbase) + (voff)[_i]), (PG8_LAS unsigned*)(lds + (bufoff) + ldsw + _i * 8192), 16, 0, 0); } while (0)
; #define PG8_LDA(dst, b, h) do { _Pragma("unroll") for (int m = 0; m < 4; ++m) _Pragma("unroll") for (int k = 0; k < 2; ++k) dst[m][k] = *(const PG8_LAS bf16x8*)(lds + PG8_SA(b, h) + aoff + m * 2048 + k * 1024); } while (0)
; #define PG8_MMA(ai, bj, At, Bt) do { __builtin_amdgcn_s_setprio(1); _Pragma("unroll") for (int m = 0; m < 4; ++m) _Pragma("unroll") for (int n = 0; n < 2; ++n) _Pragma("unroll") for (int k = 0; k < 2; ++k) \
;         acc[ai][bj][m][n] = __builtin_amdgcn_mfma_f32_16x16x32_bf16(Bt[n][k], At[m][k], acc[ai][bj][m][n], 0, 0, 0); __builtin_amdgcn_s_setprio(0); } while (0)
; #define PG8_WAIT_V(n) asm volatile("s_waitcnt vmcnt(" #n ")" ::: "memory")
; #define PG8_WAIT_L(n) asm volatile("s_waitcnt lgkmcnt(" #n ")" ::: "memory")
; #define PG8_BAR __builtin_amdgcn_s_barrier()
; #define PG8_SCHED __builtin_amdgcn_sched_barrier(0)
; template <class Epi, class Sched, bool ALIGN_EPI = false, bool SP2 = false, bool DUAL = false>
; __device__ __forceinline__ void gemm_phase(PG8_LAS unsigned char* lds, const Gemm g, const Sched& S, const Epi& E) {
;     ...
;             PG8_WAIT_V(8); PG8_WAIT_L(0); PG8_BAR; PG8_MMA(0, 0, At, B0); PG8_MMA(0, 1, At, B1); PG8_BAR; PG8_SCHED;
;             PG8_LDA(At, 0, 1); PG8_STAGE(PG8_SB(0, 0), b2, voffB); PG8_STAGE(PG8_SB(0, 1), b2 + hstep, voffB); PG8_STAGE(PG8_SA(0, 0), a2, voffA);
;             PG8_WAIT_V(8); PG8_WAIT_L(0); PG8_BAR; PG8_MMA(1, 0, At, B0); PG8_MMA(1, 1, At, B1); PG8_BAR; PG8_SCHED;
	v_mfma_f32_16x16x32_bf16 v[124:127], v[128:131], v[160:163], v[124:127]
	v_mfma_f32_16x16x32_bf16 v[120:123], v[136:139], v[160:163], v[120:123]
	v_mfma_f32_16x16x32_bf16 v[108:111], v[128:131], v[188:191], v[108:111]
	v_mfma_f32_16x16x32_bf16 v[104:107], v[136:139], v[188:191], v[104:107]
	v_mfma_f32_16x16x32_bf16 v[92:95], v[128:131], v[196:199], v[92:95]
	v_mfma_f32_16x16x32_bf16 v[88:91], v[136:139], v[196:199], v[88:91]
	v_mfma_f32_16x16x32_bf16 v[76:79], v[128:131], v[206:209], v[76:79]
	v_mfma_f32_16x16x32_bf16 v[72:75], v[136:139], v[206:209], v[72:75]
	v_mfma_f32_16x16x32_bf16 v[124:127], v[132:135], v[164:167], v[124:127]
	v_mfma_f32_16x16x32_bf16 v[120:123], v[140:143], v[164:167], v[120:123]
	v_mfma_f32_16x16x32_bf16 v[108:111], v[132:135], v[192:195], v[108:111]
	v_mfma_f32_16x16x32_bf16 v[104:107], v[140:143], v[192:195], v[104:107]
	v_mfma_f32_16x16x32_bf16 v[92:95], v[132:135], v[202:205], v[92:95]
	v_mfma_f32_16x16x32_bf16 v[88:91], v[140:143], v[202:205], v[88:91]
	v_mfma_f32_16x16x32_bf16 v[76:79], v[132:135], v[220:223], v[76:79]
	v_mfma_f32_16x16x32_bf16 v[72:75], v[140:143], v[220:223], v[72:75]
	s_setprio 0
	s_setprio 1
	v_mfma_f32_16x16x32_bf16 v[116:119], v[144:147], v[160:163], v[116:119]
	v_mfma_f32_16x16x32_bf16 v[112:115], v[152:155], v[160:163], v[112:115]
	v_mfma_f32_16x16x32_bf16 v[100:103], v[144:147], v[188:191], v[100:103]
	v_mfma_f32_16x16x32_bf16 v[96:99], v[152:155], v[188:191], v[96:99]
	v_mfma_f32_16x16x32_bf16 v[84:87], v[144:147], v[196:199], v[84:87]
	v_mfma_f32_16x16x32_bf16 v[80:83], v[152:155], v[196:199], v[80:83]
	v_mfma_f32_16x16x32_bf16 v[68:71], v[144:147], v[206:209], v[68:71]
	v_mfma_f32_16x16x32_bf16 v[64:67], v[152:155], v[206:209], v[64:67]
	v_mfma_f32_16x16x32_bf16 v[116:119], v[148:151], v[164:167], v[116:119]
	v_mfma_f32_16x16x32_bf16 v[112:115], v[156:159], v[164:167], v[112:115]
	v_mfma_f32_16x16x32_bf16 v[100:103], v[148:151], v[192:195], v[100:103]
	v_mfma_f32_16x16x32_bf16 v[96:99], v[156:159], v[192:195], v[96:99]
	v_mfma_f32_16x16x32_bf16 v[84:87], v[148:151], v[202:205], v[84:87]
	v_mfma_f32_16x16x32_bf16 v[80:83], v[156:159], v[202:205], v[80:83]
	v_mfma_f32_16x16x32_bf16 v[68:71], v[148:151], v[220:223], v[68:71]
	v_mfma_f32_16x16x32_bf16 v[64:67], v[156:159], v[220:223], v[64:67]
	s_barrier
	s_setprio 0
	s_add_i32 s66, s50, s34
	v_lshl_add_u64 v[228:229], s[14:15], 0, v[170:171]
	s_mov_b32 m0, s66
	ds_read_b128 v[160:163], v217 offset:16384
	ds_read_b128 v[164:167], v217 offset:17408
	ds_read_b128 v[188:191], v217 offset:18432
	ds_read_b128 v[192:195], v217 offset:19456
	ds_read_b128 v[196:199], v217 offset:20480
	ds_read_b128 v[202:205], v217 offset:21504
	ds_read_b128 v[206:209], v217 offset:22528
	ds_read_b128 v[220:223], v217 offset:23552
	global_load_lds_dwordx4 v[228:229], off
	s_add_i32 m0, s66, 0x2000
	s_add_u32 s66, s14, 0x80000
	v_lshl_add_u64 v[232:233], s[14:15], 0, v[174:175]
	s_addc_u32 s67, s15, 0
	s_add_i32 s68, s51, s34
	global_load_lds_dwordx4 v[232:233], off
	v_lshl_add_u64 v[234:235], s[66:67], 0, v[170:171]
	s_mov_b32 m0, s68
	v_lshl_add_u64 v[236:237], s[26:27], 0, v[172:173]
	global_load_lds_dwordx4 v[234:235], off
	v_lshl_add_u64 v[234:235], s[66:67], 0, v[174:175]
	s_add_i32 m0, s68, 0x2000
	s_nop 0
	global_load_lds_dwordx4 v[234:235], off
	v_lshl_add_u64 v[234:235], s[26:27], 0, v[168:169]
	s_mov_b32 m0, s39
	s_nop 0
	global_load_lds_dwordx4 v[234:235], off
	s_mov_b32 m0, s42
	s_nop 0
	global_load_lds_dwordx4 v[236:237], off
	s_waitcnt vmcnt(8)
	s_waitcnt lgkmcnt(0)
	s_setprio 1
	s_barrier
	v_mfma_f32_16x16x32_bf16 v[60:63], v[128:131], v[160:163], v[60:63]
	v_mfma_f32_16x16x32_bf16 v[56:59], v[136:139], v[160:163], v[56:59]
	v_mfma_f32_16x16x32_bf16 v[44:47], v[128:131], v[188:191], v[44:47]
	v_mfma_f32_16x16x32_bf16 v[40:43], v[136:139], v[188:191], v[40:43]
	v_mfma_f32_16x16x32_bf16 v[28:31], v[128:131], v[196:199], v[28:31]
	v_mfma_f32_16x16x32_bf16 v[24:27], v[136:139], v[196:199], v[24:27]
	v_mfma_f32_16x16x32_bf16 v[12:15], v[128:131], v[206:209], v[12:15]
	v_mfma_f32_16x16x32_bf16 v[8:11], v[136:139], v[206:209], v[8:11]
	v_mfma_f32_16x16x32_bf16 v[60:63], v[132:135], v[164:167], v[60:63]
	v_mfma_f32_16x16x32_bf16 v[56:59], v[140:143], v[164:167], v[56:59]
	v_mfma_f32_16x16x32_bf16 v[44:47], v[132:135], v[192:195], v[44:47]
	v_mfma_f32_16x16x32_bf16 v[40:43], v[140:143], v[192:195], v[40:43]
	v_mfma_f32_16x16x32_bf16 v[28:31], v[132:135], v[202:205], v[28:31]
	v_mfma_f32_16x16x32_bf16 v[24:27], v[140:143], v[202:205], v[24:27]
	v_mfma_f32_16x16x32_bf16 v[12:15], v[132:135], v[220:223], v[12:15]
	v_mfma_f32_16x16x32_bf16 v[8:11], v[140:143], v[220:223], v[8:11]
	s_setprio 0
	s_setprio 1
	v_mfma_f32_16x16x32_bf16 v[52:55], v[144:147], v[160:163], v[52:55]
	v_mfma_f32_16x16x32_bf16 v[48:51], v[152:155], v[160:163], v[48:51]
	v_mfma_f32_16x16x32_bf16 v[36:39], v[144:147], v[188:191], v[36:39]
	v_mfma_f32_16x16x32_bf16 v[32:35], v[152:155], v[188:191], v[32:35]
	v_mfma_f32_16x16x32_bf16 v[20:23], v[144:147], v[196:199], v[20:23]
	v_mfma_f32_16x16x32_bf16 v[16:19], v[152:155], v[196:199], v[16:19]
	v_mfma_f32_16x16x32_bf16 v[4:7], v[144:147], v[206:209], v[4:7]
	v_mfma_f32_16x16x32_bf16 v[0:3], v[152:155], v[206:209], v[0:3]
	v_mfma_f32_16x16x32_bf16 v[52:55], v[148:151], v[164:167], v[52:55]
	v_mfma_f32_16x16x32_bf16 v[48:51], v[156:159], v[164:167], v[48:51]
	v_mfma_f32_16x16x32_bf16 v[36:39], v[148:151], v[192:195], v[36:39]
	v_mfma_f32_16x16x32_bf16 v[32:35], v[156:159], v[192:195], v[32:35]
	v_mfma_f32_16x16x32_bf16 v[20:23], v[148:151], v[202:205], v[20:23]
	v_mfma_f32_16x16x32_bf16 v[16:19], v[156:159], v[202:205], v[16:19]
	v_mfma_f32_16x16x32_bf16 v[4:7], v[148:151], v[220:223], v[4:7]
	v_mfma_f32_16x16x32_bf16 v[0:3], v[156:159], v[220:223], v[0:3]
	s_barrier
; #define PG8_STAGE(bufoff, gbase, voff) do { _Pragma("unroll") for (int _i = 0; _i < 2; ++_i) \
;         __builtin_amdgcn_global_load_lds((const unsigned*)((const char*)(gbase) + (voff)[_i]), (PG8_LAS unsigned*)(lds + (bufoff) + ldsw + _i * 8192), 16, 0, 0); } while (0)
; #define PG8_LDA(dst, b, h) do { _Pragma("unroll") for (int m = 0; m < 4; ++m) _Pragma("unroll") for (int k = 0; k < 2; ++k) dst[m][k] = *(const PG8_LAS bf16x8*)(lds + PG8_SA(b, h) + aoff + m * 2048 + k * 1024); } while (0)
; #define PG8_LDB(dst, b, h) do { _Pragma("unroll") for (int n = 0; n < 2; ++n) _Pragma("unroll") for (int k = 0; k < 2; ++k) dst[n][k] = *(const PG8_LAS bf16x8*)(lds + PG8_SB(b, h) + boff + n * 2048 + k * 1024); } while (0)
; #define PG8_MMA(ai, bj, At, Bt) do { __builtin_amdgcn_s_setprio(1); _Pragma("unroll") for (int m = 0; m < 4; ++m) _Pragma("unroll") for (int n = 0; n < 2; ++n) _Pragma("unroll") for (int k = 0; k < 2; ++k) \
;         acc[ai][bj][m][n] = __builtin_amdgcn_mfma_f32_16x16x32_bf16(Bt[n][k], At[m][k], acc[ai][bj][m][n], 0, 0, 0); __builtin_amdgcn_s_setprio(0); } while (0)
; #define PG8_WAIT_V(n) asm volatile("s_waitcnt vmcnt(" #n ")" ::: "memory")
; #define PG8_WAIT_L(n) asm volatile("s_waitcnt lgkmcnt(" #n ")" ::: "memory")
; #define PG8_BAR __builtin_amdgcn_s_barrier()
; #define PG8_SCHED __builtin_amdgcn_sched_barrier(0)
; template <class Epi, class Sched, bool ALIGN_EPI = false, bool SP2 = false, bool DUAL = false>
; __device__ __forceinline__ void gemm_phase(PG8_LAS unsigned char* lds, const Gemm g, const Sched& S, const Epi& E) {
;     ...
;             PG8_LDB(B0, 1, 0); PG8_LDB(B1, 1, 1); PG8_SCHED; PG8_LDA(At, 1, 0); PG8_STAGE(PG8_SA(0, 1), a2 + hstep, voffA);
;             PG8_WAIT_V(8); PG8_WAIT_L(0); PG8_BAR; PG8_MMA(0, 0, At, B0); PG8_MMA(0, 1, At, B1); PG8_BAR; PG8_SCHED;
	s_setprio 0
	s_add_i32 s66, 0, 0x18000
	s_add_i32 s67, 0, 0x1c000
	v_add_u32_e32 v140, s66, v213
	v_add_u32_e32 v156, s67, v213
	ds_read_b128 v[128:131], v140
	ds_read_b128 v[132:135], v140 offset:1024
	ds_read_b128 v[136:139], v140 offset:2048
	ds_read_b128 v[140:143], v140 offset:3072
	ds_read_b128 v[144:147], v156
	ds_read_b128 v[148:151], v156 offset:1024
	ds_read_b128 v[152:155], v156 offset:2048
	ds_read_b128 v[156:159], v156 offset:3072
	s_add_u32 s26, s26, 0x80000
	s_addc_u32 s27, s27, 0
	s_mov_b32 m0, s43
	v_lshl_add_u64 v[238:239], s[26:27], 0, v[168:169]
	ds_read_b128 v[160:163], v217 offset:32768
	ds_read_b128 v[164:167], v217 offset:33792
	ds_read_b128 v[188:191], v217 offset:34816
	ds_read_b128 v[192:195], v217 offset:35840
	ds_read_b128 v[196:199], v217 offset:36864
	ds_read_b128 v[202:205], v217 offset:37888
	ds_read_b128 v[206:209], v217 offset:38912
	ds_read_b128 v[220:223], v217 offset:39936
	global_load_lds_dwordx4 v[238:239], off
	v_lshl_add_u64 v[238:239], s[26:27], 0, v[172:173]
	s_mov_b32 m0, s44
	s_nop 0
	global_load_lds_dwordx4 v[238:239], off
	s_waitcnt vmcnt(8)
	s_waitcnt lgkmcnt(0)
	s_setprio 1
	s_barrier
	v_mfma_f32_16x16x32_bf16 v[124:127], v[128:131], v[160:163], v[124:127]
	v_mfma_f32_16x16x32_bf16 v[120:123], v[136:139], v[160:163], v[120:123]
	v_mfma_f32_16x16x32_bf16 v[108:111], v[128:131], v[188:191], v[108:111]
	v_mfma_f32_16x16x32_bf16 v[104:107], v[136:139], v[188:191], v[104:107]
	v_mfma_f32_16x16x32_bf16 v[92:95], v[128:131], v[196:199], v[92:95]
	v_mfma_f32_16x16x32_bf16 v[88:91], v[136:139], v[196:199], v[88:91]
	v_mfma_f32_16x16x32_bf16 v[76:79], v[128:131], v[206:209], v[76:79]
	v_mfma_f32_16x16x32_bf16 v[72:75], v[136:139], v[206:209], v[72:75]
	v_mfma_f32_16x16x32_bf16 v[124:127], v[132:135], v[164:167], v[124:127]
	v_mfma_f32_16x16x32_bf16 v[120:123], v[140:143], v[164:167], v[120:123]
	v_mfma_f32_16x16x32_bf16 v[108:111], v[132:135], v[192:195], v[108:111]
	v_mfma_f32_16x16x32_bf16 v[104:107], v[140:143], v[192:195], v[104:107]
	v_mfma_f32_16x16x32_bf16 v[92:95], v[132:135], v[202:205], v[92:95]
	v_mfma_f32_16x16x32_bf16 v[88:91], v[140:143], v[202:205], v[88:91]
	v_mfma_f32_16x16x32_bf16 v[76:79], v[132:135], v[220:223], v[76:79]
	v_mfma_f32_16x16x32_bf16 v[72:75], v[140:143], v[220:223], v[72:75]
	s_setprio 0
	s_setprio 1
	v_mfma_f32_16x16x32_bf16 v[116:119], v[144:147], v[160:163], v[116:119]
	v_mfma_f32_16x16x32_bf16 v[112:115], v[152:155], v[160:163], v[112:115]
	v_mfma_f32_16x16x32_bf16 v[100:103], v[144:147], v[188:191], v[100:103]
	v_mfma_f32_16x16x32_bf16 v[96:99], v[152:155], v[188:191], v[96:99]
	v_mfma_f32_16x16x32_bf16 v[84:87], v[144:147], v[196:199], v[84:87]
	v_mfma_f32_16x16x32_bf16 v[80:83], v[152:155], v[196:199], v[80:83]
	v_mfma_f32_16x16x32_bf16 v[68:71], v[144:147], v[206:209], v[68:71]
	v_mfma_f32_16x16x32_bf16 v[64:67], v[152:155], v[206:209], v[64:67]
	v_mfma_f32_16x16x32_bf16 v[116:119], v[148:151], v[164:167], v[116:119]
	v_mfma_f32_16x16x32_bf16 v[112:115], v[156:159], v[164:167], v[112:115]
	v_mfma_f32_16x16x32_bf16 v[100:103], v[148:151], v[192:195], v[100:103]
	v_mfma_f32_16x16x32_bf16 v[96:99], v[156:159], v[192:195], v[96:99]
	v_mfma_f32_16x16x32_bf16 v[84:87], v[148:151], v[202:205], v[84:87]
	v_mfma_f32_16x16x32_bf16 v[80:83], v[156:159], v[202:205], v[80:83]
	v_mfma_f32_16x16x32_bf16 v[68:71], v[148:151], v[220:223], v[68:71]
	v_mfma_f32_16x16x32_bf16 v[64:67], v[156:159], v[220:223], v[64:67]
	s_barrier
; #define PG8_STAGE(bufoff, gbase, voff) do { _Pragma("unroll") for (int _i = 0; _i < 2; ++_i) \
;         __builtin_amdgcn_global_load_lds((const unsigned*)((const char*)(gbase) + (voff)[_i]), (PG8_LAS unsigned*)(lds + (bufoff) + ldsw + _i * 8192), 16, 0, 0); } while (0)
; #define PG8_LDA(dst, b, h) do { _Pragma("unroll") for (int m = 0; m < 4; ++m) _Pragma("unroll") for (int k = 0; k < 2; ++k) dst[m][k] = *(const PG8_LAS bf16x8*)(lds + PG8_SA(b, h) + aoff + m * 2048 + k * 1024); } while (0)
; #define PG8_MMA(ai, bj, At, Bt) do { __builtin_amdgcn_s_setprio(1); _Pragma("unroll") for (int m = 0; m < 4; ++m) _Pragma("unroll") for (int n = 0; n < 2; ++n) _Pragma("unroll") for (int k = 0; k < 2; ++k) \
;         acc[ai][bj][m][n] = __builtin_amdgcn_mfma_f32_16x16x32_bf16(Bt[n][k], At[m][k], acc[ai][bj][m][n], 0, 0, 0); __builtin_amdgcn_s_setprio(0); } while (0)
; #define PG8_WAIT_V(n) asm volatile("s_waitcnt vmcnt(" #n ")" ::: "memory")
; #define PG8_WAIT_L(n) asm volatile("s_waitcnt lgkmcnt(" #n ")" ::: "memory")
; #define PG8_BAR __builtin_amdgcn_s_barrier()
; #define PG8_SCHED __builtin_amdgcn_sched_barrier(0)
; template <class Epi, class Sched, bool ALIGN_EPI = false, bool SP2 = false, bool DUAL = false>
; __device__ __forceinline__ void gemm_phase(PG8_LAS unsigned char* lds, const Gemm g, const Sched& S, const Epi& E) {
;     ...
;             PG8_WAIT_V(8); PG8_WAIT_L(0); PG8_BAR; PG8_MMA(0, 0, At, B0); PG8_MMA(0, 1, At, B1); PG8_BAR; PG8_SCHED;
;             PG8_LDA(At, 1, 1); PG8_STAGE(PG8_SB(1, 0), b3, voffB); PG8_STAGE(PG8_SB(1, 1), b3 + hstep, voffB); PG8_STAGE(PG8_SA(1, 0), a3, voffA);
;             PG8_WAIT_V(8); PG8_WAIT_L(0); PG8_BAR; PG8_MMA(1, 0, At, B0); PG8_MMA(1, 1, At, B1); PG8_BAR; PG8_SCHED;
;     ...
;         if constexpr (ALIGN_EPI) { if (wr == 0) PG8_BAR; }
	s_setprio 0
	s_add_i32 s26, s66, s34
	v_lshl_add_u64 v[228:229], v[228:229], 0, s[12:13]
	s_mov_b32 m0, s26
	ds_read_b128 v[160:163], v217 offset:49152
	ds_read_b128 v[164:167], v217 offset:50176
	ds_read_b128 v[188:191], v217 offset:51200
	ds_read_b128 v[192:195], v217 offset:52224
	ds_read_b128 v[196:199], v217 offset:53248
	ds_read_b128 v[202:205], v217 offset:54272
	ds_read_b128 v[206:209], v217 offset:55296
	ds_read_b128 v[220:223], v217 offset:56320
	global_load_lds_dwordx4 v[228:229], off
	s_add_i32 m0, s26, 0x2000
	s_add_u32 s14, s14, 0x80080
	v_lshl_add_u64 v[228:229], v[232:233], 0, s[12:13]
	s_addc_u32 s15, s15, 0
	s_add_i32 s26, s67, s34
	global_load_lds_dwordx4 v[228:229], off
	v_lshl_add_u64 v[228:229], s[14:15], 0, v[170:171]
	s_mov_b32 m0, s26
	s_nop 0
	global_load_lds_dwordx4 v[228:229], off
	v_lshl_add_u64 v[228:229], s[14:15], 0, v[174:175]
	s_add_i32 m0, s26, 0x2000
	s_nop 0
	global_load_lds_dwordx4 v[228:229], off
	v_lshl_add_u64 v[228:229], v[234:235], 0, s[12:13]
	s_mov_b32 m0, s47
	s_nop 0
	global_load_lds_dwordx4 v[228:229], off
	v_lshl_add_u64 v[228:229], v[236:237], 0, s[12:13]
	s_mov_b32 m0, s48
	s_nop 0
	global_load_lds_dwordx4 v[228:229], off
	s_waitcnt vmcnt(8)
	s_waitcnt lgkmcnt(0)
	s_setprio 1
	s_barrier
	v_mfma_f32_16x16x32_bf16 v[60:63], v[128:131], v[160:163], v[60:63]
	v_mfma_f32_16x16x32_bf16 v[56:59], v[136:139], v[160:163], v[56:59]
	v_mfma_f32_16x16x32_bf16 v[44:47], v[128:131], v[188:191], v[44:47]
	v_mfma_f32_16x16x32_bf16 v[40:43], v[136:139], v[188:191], v[40:43]
	v_mfma_f32_16x16x32_bf16 v[28:31], v[128:131], v[196:199], v[28:31]
	v_mfma_f32_16x16x32_bf16 v[24:27], v[136:139], v[196:199], v[24:27]
	v_mfma_f32_16x16x32_bf16 v[12:15], v[128:131], v[206:209], v[12:15]
	v_mfma_f32_16x16x32_bf16 v[8:11], v[136:139], v[206:209], v[8:11]
	v_mfma_f32_16x16x32_bf16 v[60:63], v[132:135], v[164:167], v[60:63]
	v_mfma_f32_16x16x32_bf16 v[56:59], v[140:143], v[164:167], v[56:59]
	v_mfma_f32_16x16x32_bf16 v[44:47], v[132:135], v[192:195], v[44:47]
	v_mfma_f32_16x16x32_bf16 v[40:43], v[140:143], v[192:195], v[40:43]
	v_mfma_f32_16x16x32_bf16 v[28:31], v[132:135], v[202:205], v[28:31]
	v_mfma_f32_16x16x32_bf16 v[24:27], v[140:143], v[202:205], v[24:27]
	v_mfma_f32_16x16x32_bf16 v[12:15], v[132:135], v[220:223], v[12:15]
	v_mfma_f32_16x16x32_bf16 v[8:11], v[140:143], v[220:223], v[8:11]
	s_setprio 0
	s_setprio 1
	v_mfma_f32_16x16x32_bf16 v[52:55], v[144:147], v[160:163], v[52:55]
	v_mfma_f32_16x16x32_bf16 v[48:51], v[152:155], v[160:163], v[48:51]
	v_mfma_f32_16x16x32_bf16 v[36:39], v[144:147], v[188:191], v[36:39]
	v_mfma_f32_16x16x32_bf16 v[32:35], v[152:155], v[188:191], v[32:35]
	v_mfma_f32_16x16x32_bf16 v[20:23], v[144:147], v[196:199], v[20:23]
	v_mfma_f32_16x16x32_bf16 v[16:19], v[152:155], v[196:199], v[16:19]
	v_mfma_f32_16x16x32_bf16 v[4:7], v[144:147], v[206:209], v[4:7]
	v_mfma_f32_16x16x32_bf16 v[0:3], v[152:155], v[206:209], v[0:3]
	v_mfma_f32_16x16x32_bf16 v[52:55], v[148:151], v[164:167], v[52:55]
	v_mfma_f32_16x16x32_bf16 v[48:51], v[156:159], v[164:167], v[48:51]
	v_mfma_f32_16x16x32_bf16 v[36:39], v[148:151], v[192:195], v[36:39]
	v_mfma_f32_16x16x32_bf16 v[32:35], v[156:159], v[192:195], v[32:35]
	v_mfma_f32_16x16x32_bf16 v[20:23], v[148:151], v[202:205], v[20:23]
	v_mfma_f32_16x16x32_bf16 v[16:19], v[156:159], v[202:205], v[16:19]
	v_mfma_f32_16x16x32_bf16 v[4:7], v[148:151], v[220:223], v[4:7]
	v_mfma_f32_16x16x32_bf16 v[0:3], v[156:159], v[220:223], v[0:3]
	s_barrier
	s_setprio 0
	s_add_i32 s65, s65, 2
	s_add_u32 s40, s40, 0x100
	s_addc_u32 s41, s41, 0
	s_add_u32 s63, s63, 0x100
	s_addc_u32 s64, s64, 0
	s_cmp_gt_u32 s65, 29
	s_cbranch_scc0 .LBB0_992
	v_readlane_b32 s64, v254, 20
	v_readlane_b32 s70, v254, 26
	v_readlane_b32 s71, v254, 27
	v_readlane_b32 s72, v254, 28
	v_readlane_b32 s73, v254, 29
	v_readlane_b32 s74, v254, 30
	v_readlane_b32 s75, v254, 31
	v_readlane_b32 s76, v254, 32
	v_readlane_b32 s77, v254, 33
	s_and_b64 vcc, exec, s[16:17]
	s_mov_b64 s[70:71], s[74:75]
	s_mov_b64 s[72:73], s[76:77]
	v_readlane_b32 s65, v254, 21
	v_readlane_b32 s66, v254, 22
	v_readlane_b32 s67, v254, 23
	v_readlane_b32 s68, v254, 24
	v_readlane_b32 s69, v254, 25
	v_readlane_b32 s78, v254, 34
	v_readlane_b32 s79, v254, 35
	s_cbranch_vccz .LBB0_995
	s_barrier

;     __device__ bool next(int i, Unit& u) const { if (!base.next(i >> 1, u)) return false; u.sub = i & 1; return true; }
; #define PG8_STAGE(bufoff, gbase, voff) do { _Pragma("unroll") for (int _i = 0; _i < 2; ++_i) \
;         __builtin_amdgcn_global_load_lds((const unsigned*)((const char*)(gbase) + (voff)[_i]), (PG8_LAS unsigned*)(lds + (bufoff) + ldsw + _i * 8192), 16, 0, 0); } while (0)
; #define PG8_LDA(dst, b, h) do { _Pragma("unroll") for (int m = 0; m < 4; ++m) _Pragma("unroll") for (int k = 0; k < 2; ++k) dst[m][k] = *(const PG8_LAS bf16x8*)(lds + PG8_SA(b, h) + aoff + m * 2048 + k * 1024); } while (0)
; #define PG8_LDB(dst, b, h) do { _Pragma("unroll") for (int n = 0; n < 2; ++n) _Pragma("unroll") for (int k = 0; k < 2; ++k) dst[n][k] = *(const PG8_LAS bf16x8*)(lds + PG8_SB(b, h) + boff + n * 2048 + k * 1024); } while (0)
; #define PG8_WAIT_V(n) asm volatile("s_waitcnt vmcnt(" #n ")" ::: "memory")
; template <class Epi, class Sched, bool ALIGN_EPI = false, bool SP2 = false, bool DUAL = false>
; __device__ __forceinline__ void gemm_phase(PG8_LAS unsigned char* lds, const Gemm g, const Sched& S, const Epi& E) {
;     ...
;         const bool has_next = S.next(ui + 1, nxt);
;         const char* nA = has_next ? (const char*)((DUAL && nxt.sub) ? g.A2 : g.A) + (size_t)nxt.pm * tstep : cA; const char* nB = has_next ? (const char*)((DUAL && nxt.sub) ? g.Bt2 : g.Bt) + (size_t)nxt.pn * tstep : cB;
;         for (int t = 0; t < nt; t += 2) {
;             const bool last = (t == nt - 2);
;             const char* a1 = cA + (size_t)(t + 1) * kstep;
;             const char* a2 = last ? nA : cA + (size_t)(t + 2) * kstep; const char* b2 = last ? nB : cB + (size_t)(t + 2) * kstep;
;             const char* a3 = a2 + kstep; const char* b3 = b2 + kstep;
;             if (last && has_next) S.a_ready(nxt);
;             if constexpr (SP2) {
;             PG8_LDB(B0, 0, 0); PG8_LDB(B1, 0, 1); PG8_SCHED; PG8_LDA(At, 0, 0); PG8_STAGE(PG8_SA(1, 1), a1 + hstep, voffA);
;             PG8_WAIT_V(8); PG8_WAIT_L(0); PG8_BAR; PG8_MMA(0, 0, At, B0); PG8_MMA(0, 1, At, B1); PG8_BAR; PG8_SCHED;
;             PG8_LDA(At, 0, 1); PG8_STAGE(PG8_SB(0, 0), b2, voffB); PG8_STAGE(PG8_SB(0, 1), b2 + hstep, voffB); PG8_STAGE(PG8_SA(0, 0), a2, voffA);
;             PG8_WAIT_V(8); PG8_WAIT_L(0); PG8_BAR; PG8_MMA(1, 0, At, B0); PG8_MMA(1, 1, At, B1); PG8_BAR; PG8_SCHED;
.LBB0_1192:
	s_add_u32 s24, s24, 0x160080
	s_addc_u32 s25, s25, 0
	s_add_u32 s46, s14, 0x100
	s_addc_u32 s47, s15, 0
	s_mov_b32 s48, -2
	ds_read_b128 v[128:131], v201
	ds_read_b128 v[132:135], v201 offset:1024
	ds_read_b128 v[136:139], v201 offset:2048
	ds_read_b128 v[140:143], v201 offset:3072
	ds_read_b128 v[144:147], v202
	ds_read_b128 v[148:151], v202 offset:1024
	ds_read_b128 v[152:155], v202 offset:2048
	ds_read_b128 v[156:159], v202 offset:3072
	s_add_u32 s14, s24, 0xffea0080
	s_addc_u32 s15, s25, -1
	s_cmpk_eq_i32 s48, 0x54
	s_cselect_b32 s27, s5, s15
	s_cselect_b32 s26, s4, s14
	s_cselect_b32 s15, s23, s47
	s_cselect_b32 s14, s22, s46
	v_lshl_add_u64 v[220:221], s[24:25], 0, v[172:173]
	s_add_i32 m0, s31, 0xc000
	ds_read_b128 v[160:163], v203
	ds_read_b128 v[182:185], v203 offset:1024
	ds_read_b128 v[186:189], v203 offset:2048
	ds_read_b128 v[190:193], v203 offset:3072
	ds_read_b128 v[204:207], v203 offset:4096
	ds_read_b128 v[208:211], v203 offset:5120
	ds_read_b128 v[212:215], v203 offset:6144
	ds_read_b128 v[216:219], v203 offset:7168
	global_load_lds_dwordx4 v[220:221], off
	v_lshl_add_u64 v[220:221], s[24:25], 0, v[174:175]
	s_add_i32 m0, s31, 0xe000
	s_nop 0
	global_load_lds_dwordx4 v[220:221], off
	s_waitcnt vmcnt(8)
	s_waitcnt lgkmcnt(0)
	s_setprio 1
	s_barrier
	v_mfma_f32_16x16x32_bf16 v[124:127], v[128:131], v[160:163], 0
	v_mfma_f32_16x16x32_bf16 v[120:123], v[136:139], v[160:163], 0
	v_mfma_f32_16x16x32_bf16 v[112:115], v[128:131], v[186:189], 0
	v_mfma_f32_16x16x32_bf16 v[104:107], v[136:139], v[186:189], 0
	v_mfma_f32_16x16x32_bf16 v[96:99], v[128:131], v[204:207], 0
	v_mfma_f32_16x16x32_bf16 v[88:91], v[136:139], v[204:207], 0
	v_mfma_f32_16x16x32_bf16 v[80:83], v[128:131], v[212:215], 0
	v_mfma_f32_16x16x32_bf16 v[72:75], v[136:139], v[212:215], 0
	v_mfma_f32_16x16x32_bf16 v[124:127], v[132:135], v[182:185], v[124:127]
	v_mfma_f32_16x16x32_bf16 v[120:123], v[140:143], v[182:185], v[120:123]
	v_mfma_f32_16x16x32_bf16 v[112:115], v[132:135], v[190:193], v[112:115]
	v_mfma_f32_16x16x32_bf16 v[104:107], v[140:143], v[190:193], v[104:107]
	v_mfma_f32_16x16x32_bf16 v[96:99], v[132:135], v[208:211], v[96:99]
	v_mfma_f32_16x16x32_bf16 v[88:91], v[140:143], v[208:211], v[88:91]
	v_mfma_f32_16x16x32_bf16 v[80:83], v[132:135], v[216:219], v[80:83]
	v_mfma_f32_16x16x32_bf16 v[72:75], v[140:143], v[216:219], v[72:75]
	s_setprio 0
	s_setprio 1
	v_mfma_f32_16x16x32_bf16 v[116:119], v[144:147], v[160:163], 0
	v_mfma_f32_16x16x32_bf16 v[108:111], v[152:155], v[160:163], 0
	v_mfma_f32_16x16x32_bf16 v[100:103], v[144:147], v[186:189], 0
	v_mfma_f32_16x16x32_bf16 v[92:95], v[152:155], v[186:189], 0
	v_mfma_f32_16x16x32_bf16 v[84:87], v[144:147], v[204:207], 0
	v_mfma_f32_16x16x32_bf16 v[76:79], v[152:155], v[204:207], 0
	v_mfma_f32_16x16x32_bf16 v[68:71], v[144:147], v[212:215], 0
	v_mfma_f32_16x16x32_bf16 v[64:67], v[152:155], v[212:215], 0
	v_mfma_f32_16x16x32_bf16 v[116:119], v[148:151], v[182:185], v[116:119]
	v_mfma_f32_16x16x32_bf16 v[108:111], v[156:159], v[182:185], v[108:111]
	v_mfma_f32_16x16x32_bf16 v[100:103], v[148:151], v[190:193], v[100:103]
	v_mfma_f32_16x16x32_bf16 v[92:95], v[156:159], v[190:193], v[92:95]
	v_mfma_f32_16x16x32_bf16 v[84:87], v[148:151], v[208:211], v[84:87]
	v_mfma_f32_16x16x32_bf16 v[76:79], v[156:159], v[208:211], v[76:79]
	v_mfma_f32_16x16x32_bf16 v[68:71], v[148:151], v[216:219], v[68:71]
	v_mfma_f32_16x16x32_bf16 v[64:67], v[156:159], v[216:219], v[64:67]
	s_barrier
	s_setprio 0
	s_add_i32 s49, s40, s30
	v_lshl_add_u64 v[220:221], s[14:15], 0, v[166:167]
	s_mov_b32 m0, s49
	ds_read_b128 v[160:163], v203 offset:16384
	ds_read_b128 v[182:185], v203 offset:17408
	ds_read_b128 v[186:189], v203 offset:18432
	ds_read_b128 v[190:193], v203 offset:19456
	ds_read_b128 v[204:207], v203 offset:20480
	ds_read_b128 v[208:211], v203 offset:21504
	ds_read_b128 v[212:215], v203 offset:22528
	ds_read_b128 v[216:219], v203 offset:23552
	global_load_lds_dwordx4 v[220:221], off
	s_add_i32 m0, s49, 0x2000
	s_add_u32 s50, s14, 0x160000
	v_lshl_add_u64 v[222:223], s[14:15], 0, v[170:171]
	s_addc_u32 s51, s15, 0
	s_add_i32 s49, s41, s30
	global_load_lds_dwordx4 v[222:223], off
	v_lshl_add_u64 v[224:225], s[50:51], 0, v[166:167]
	s_mov_b32 m0, s49
	v_lshl_add_u64 v[226:227], s[26:27], 0, v[168:169]
	global_load_lds_dwordx4 v[224:225], off
	v_lshl_add_u64 v[224:225], s[50:51], 0, v[170:171]
	s_add_i32 m0, s49, 0x2000
	s_nop 0
	global_load_lds_dwordx4 v[224:225], off
	v_lshl_add_u64 v[224:225], s[26:27], 0, v[164:165]
	s_mov_b32 m0, s31
	s_nop 0
	global_load_lds_dwordx4 v[224:225], off
	s_mov_b32 m0, s33
	s_nop 0
	global_load_lds_dwordx4 v[226:227], off
	s_waitcnt vmcnt(8)
	s_waitcnt lgkmcnt(0)
	s_setprio 1
	s_barrier
; #define PG8_STAGE(bufoff, gbase, voff) do { _Pragma("unroll") for (int _i = 0; _i < 2; ++_i) \
;         __builtin_amdgcn_global_load_lds((const unsigned*)((const char*)(gbase) + (voff)[_i]), (PG8_LAS unsigned*)(lds + (bufoff) + ldsw + _i * 8192), 16, 0, 0); } while (0)
; #define PG8_LDA(dst, b, h) do { _Pragma("unroll") for (int m = 0; m < 4; ++m) _Pragma("unroll") for (int k = 0; k < 2; ++k) dst[m][k] = *(const PG8_LAS bf16x8*)(lds + PG8_SA(b, h) + aoff + m * 2048 + k * 1024); } while (0)
; #define PG8_LDB(dst, b, h) do { _Pragma("unroll") for (int n = 0; n < 2; ++n) _Pragma("unroll") for (int k = 0; k < 2; ++k) dst[n][k] = *(const PG8_LAS bf16x8*)(lds + PG8_SB(b, h) + boff + n * 2048 + k * 1024); } while (0)
; #define PG8_MMA(ai, bj, At, Bt) do { __builtin_amdgcn_s_setprio(1); _Pragma("unroll") for (int m = 0; m < 4; ++m) _Pragma("unroll") for (int n = 0; n < 2; ++n) _Pragma("unroll") for (int k = 0; k < 2; ++k) \
;         acc[ai][bj][m][n] = __builtin_amdgcn_mfma_f32_16x16x32_bf16(Bt[n][k], At[m][k], acc[ai][bj][m][n], 0, 0, 0); __builtin_amdgcn_s_setprio(0); } while (0)
; #define PG8_WAIT_V(n) asm volatile("s_waitcnt vmcnt(" #n ")" ::: "memory")
; #define PG8_WAIT_L(n) asm volatile("s_waitcnt lgkmcnt(" #n ")" ::: "memory")
; #define PG8_BAR __builtin_amdgcn_s_barrier()
; #define PG8_SCHED __builtin_amdgcn_sched_barrier(0)
; template <class Epi, class Sched, bool ALIGN_EPI = false, bool SP2 = false, bool DUAL = false>
; __device__ __forceinline__ void gemm_phase(PG8_LAS unsigned char* lds, const Gemm g, const Sched& S, const Epi& E) {
;     ...
;             PG8_WAIT_V(8); PG8_WAIT_L(0); PG8_BAR; PG8_MMA(1, 0, At, B0); PG8_MMA(1, 1, At, B1); PG8_BAR; PG8_SCHED;
;             PG8_LDB(B0, 1, 0); PG8_LDB(B1, 1, 1); PG8_SCHED; PG8_LDA(At, 1, 0); PG8_STAGE(PG8_SA(0, 1), a2 + hstep, voffA);
;             PG8_WAIT_V(8); PG8_WAIT_L(0); PG8_BAR; PG8_MMA(0, 0, At, B0); PG8_MMA(0, 1, At, B1); PG8_BAR; PG8_SCHED;
	v_mfma_f32_16x16x32_bf16 v[60:63], v[128:131], v[160:163], 0
	v_mfma_f32_16x16x32_bf16 v[56:59], v[136:139], v[160:163], 0
	v_mfma_f32_16x16x32_bf16 v[48:51], v[128:131], v[186:189], 0
	v_mfma_f32_16x16x32_bf16 v[40:43], v[136:139], v[186:189], 0
	v_mfma_f32_16x16x32_bf16 v[32:35], v[128:131], v[204:207], 0
	v_mfma_f32_16x16x32_bf16 v[24:27], v[136:139], v[204:207], 0
	v_mfma_f32_16x16x32_bf16 v[16:19], v[128:131], v[212:215], 0
	v_mfma_f32_16x16x32_bf16 v[8:11], v[136:139], v[212:215], 0
	v_mfma_f32_16x16x32_bf16 v[60:63], v[132:135], v[182:185], v[60:63]
	v_mfma_f32_16x16x32_bf16 v[56:59], v[140:143], v[182:185], v[56:59]
	v_mfma_f32_16x16x32_bf16 v[48:51], v[132:135], v[190:193], v[48:51]
	v_mfma_f32_16x16x32_bf16 v[40:43], v[140:143], v[190:193], v[40:43]
	v_mfma_f32_16x16x32_bf16 v[32:35], v[132:135], v[208:211], v[32:35]
	v_mfma_f32_16x16x32_bf16 v[24:27], v[140:143], v[208:211], v[24:27]
	v_mfma_f32_16x16x32_bf16 v[16:19], v[132:135], v[216:219], v[16:19]
	v_mfma_f32_16x16x32_bf16 v[8:11], v[140:143], v[216:219], v[8:11]
	s_setprio 0
	s_setprio 1
	v_mfma_f32_16x16x32_bf16 v[52:55], v[144:147], v[160:163], 0
	v_mfma_f32_16x16x32_bf16 v[44:47], v[152:155], v[160:163], 0
	v_mfma_f32_16x16x32_bf16 v[36:39], v[144:147], v[186:189], 0
	v_mfma_f32_16x16x32_bf16 v[28:31], v[152:155], v[186:189], 0
	v_mfma_f32_16x16x32_bf16 v[20:23], v[144:147], v[204:207], 0
	v_mfma_f32_16x16x32_bf16 v[12:15], v[152:155], v[204:207], 0
	v_mfma_f32_16x16x32_bf16 v[4:7], v[144:147], v[212:215], 0
	v_mfma_f32_16x16x32_bf16 v[0:3], v[152:155], v[212:215], 0
	v_mfma_f32_16x16x32_bf16 v[52:55], v[148:151], v[182:185], v[52:55]
	v_mfma_f32_16x16x32_bf16 v[44:47], v[156:159], v[182:185], v[44:47]
	v_mfma_f32_16x16x32_bf16 v[36:39], v[148:151], v[190:193], v[36:39]
	v_mfma_f32_16x16x32_bf16 v[28:31], v[156:159], v[190:193], v[28:31]
	v_mfma_f32_16x16x32_bf16 v[20:23], v[148:151], v[208:211], v[20:23]
	v_mfma_f32_16x16x32_bf16 v[12:15], v[156:159], v[208:211], v[12:15]
	v_mfma_f32_16x16x32_bf16 v[4:7], v[148:151], v[216:219], v[4:7]
	v_mfma_f32_16x16x32_bf16 v[0:3], v[156:159], v[216:219], v[0:3]
	s_barrier
	s_setprio 0
	s_add_i32 s49, 0, 0x18000
	s_add_i32 s50, 0, 0x1c000
	v_add_u32_e32 v140, s49, v198
	v_add_u32_e32 v156, s50, v198
	ds_read_b128 v[128:131], v140
	ds_read_b128 v[132:135], v140 offset:1024
	ds_read_b128 v[136:139], v140 offset:2048
	ds_read_b128 v[140:143], v140 offset:3072
	ds_read_b128 v[144:147], v156
	ds_read_b128 v[148:151], v156 offset:1024
	ds_read_b128 v[152:155], v156 offset:2048
	ds_read_b128 v[156:159], v156 offset:3072
	s_add_u32 s26, s26, 0x160000
	s_addc_u32 s27, s27, 0
	s_mov_b32 m0, s34
	v_lshl_add_u64 v[228:229], s[26:27], 0, v[164:165]
	ds_read_b128 v[160:163], v203 offset:32768
	ds_read_b128 v[182:185], v203 offset:33792
	ds_read_b128 v[186:189], v203 offset:34816
	ds_read_b128 v[190:193], v203 offset:35840
	ds_read_b128 v[204:207], v203 offset:36864
	ds_read_b128 v[208:211], v203 offset:37888
	ds_read_b128 v[212:215], v203 offset:38912
	ds_read_b128 v[216:219], v203 offset:39936
	global_load_lds_dwordx4 v[228:229], off
	v_lshl_add_u64 v[228:229], s[26:27], 0, v[168:169]
	s_mov_b32 m0, s35
	s_nop 0
	global_load_lds_dwordx4 v[228:229], off
	s_waitcnt vmcnt(8)
	s_waitcnt lgkmcnt(0)
	s_setprio 1
	s_barrier
	v_mfma_f32_16x16x32_bf16 v[124:127], v[128:131], v[160:163], v[124:127]
	v_mfma_f32_16x16x32_bf16 v[120:123], v[136:139], v[160:163], v[120:123]
	v_mfma_f32_16x16x32_bf16 v[112:115], v[128:131], v[186:189], v[112:115]
	v_mfma_f32_16x16x32_bf16 v[104:107], v[136:139], v[186:189], v[104:107]
	v_mfma_f32_16x16x32_bf16 v[96:99], v[128:131], v[204:207], v[96:99]
	v_mfma_f32_16x16x32_bf16 v[88:91], v[136:139], v[204:207], v[88:91]
	v_mfma_f32_16x16x32_bf16 v[80:83], v[128:131], v[212:215], v[80:83]
	v_mfma_f32_16x16x32_bf16 v[72:75], v[136:139], v[212:215], v[72:75]
	v_mfma_f32_16x16x32_bf16 v[124:127], v[132:135], v[182:185], v[124:127]
	v_mfma_f32_16x16x32_bf16 v[120:123], v[140:143], v[182:185], v[120:123]
	v_mfma_f32_16x16x32_bf16 v[112:115], v[132:135], v[190:193], v[112:115]
	v_mfma_f32_16x16x32_bf16 v[104:107], v[140:143], v[190:193], v[104:107]
	v_mfma_f32_16x16x32_bf16 v[96:99], v[132:135], v[208:211], v[96:99]
	v_mfma_f32_16x16x32_bf16 v[88:91], v[140:143], v[208:211], v[88:91]
	v_mfma_f32_16x16x32_bf16 v[80:83], v[132:135], v[216:219], v[80:83]
	v_mfma_f32_16x16x32_bf16 v[72:75], v[140:143], v[216:219], v[72:75]
	s_setprio 0
	s_setprio 1
	v_mfma_f32_16x16x32_bf16 v[116:119], v[144:147], v[160:163], v[116:119]
	v_mfma_f32_16x16x32_bf16 v[108:111], v[152:155], v[160:163], v[108:111]
	v_mfma_f32_16x16x32_bf16 v[100:103], v[144:147], v[186:189], v[100:103]
	v_mfma_f32_16x16x32_bf16 v[92:95], v[152:155], v[186:189], v[92:95]
	v_mfma_f32_16x16x32_bf16 v[84:87], v[144:147], v[204:207], v[84:87]
	v_mfma_f32_16x16x32_bf16 v[76:79], v[152:155], v[204:207], v[76:79]
	v_mfma_f32_16x16x32_bf16 v[68:71], v[144:147], v[212:215], v[68:71]
	v_mfma_f32_16x16x32_bf16 v[64:67], v[152:155], v[212:215], v[64:67]
	v_mfma_f32_16x16x32_bf16 v[116:119], v[148:151], v[182:185], v[116:119]
	v_mfma_f32_16x16x32_bf16 v[108:111], v[156:159], v[182:185], v[108:111]
	v_mfma_f32_16x16x32_bf16 v[100:103], v[148:151], v[190:193], v[100:103]
	v_mfma_f32_16x16x32_bf16 v[92:95], v[156:159], v[190:193], v[92:95]
	v_mfma_f32_16x16x32_bf16 v[84:87], v[148:151], v[208:211], v[84:87]
	v_mfma_f32_16x16x32_bf16 v[76:79], v[156:159], v[208:211], v[76:79]
	v_mfma_f32_16x16x32_bf16 v[68:71], v[148:151], v[216:219], v[68:71]
	v_mfma_f32_16x16x32_bf16 v[64:67], v[156:159], v[216:219], v[64:67]
	s_barrier
; #define PG8_STAGE(bufoff, gbase, voff) do { _Pragma("unroll") for (int _i = 0; _i < 2; ++_i) \
;         __builtin_amdgcn_global_load_lds((const unsigned*)((const char*)(gbase) + (voff)[_i]), (PG8_LAS unsigned*)(lds + (bufoff) + ldsw + _i * 8192), 16, 0, 0); } while (0)
; #define PG8_LDA(dst, b, h) do { _Pragma("unroll") for (int m = 0; m < 4; ++m) _Pragma("unroll") for (int k = 0; k < 2; ++k) dst[m][k] = *(const PG8_LAS bf16x8*)(lds + PG8_SA(b, h) + aoff + m * 2048 + k * 1024); } while (0)
; #define PG8_LDB(dst, b, h) do { _Pragma("unroll") for (int n = 0; n < 2; ++n) _Pragma("unroll") for (int k = 0; k < 2; ++k) dst[n][k] = *(const PG8_LAS bf16x8*)(lds + PG8_SB(b, h) + boff + n * 2048 + k * 1024); } while (0)
; #define PG8_MMA(ai, bj, At, Bt) do { __builtin_amdgcn_s_setprio(1); _Pragma("unroll") for (int m = 0; m < 4; ++m) _Pragma("unroll") for (int n = 0; n < 2; ++n) _Pragma("unroll") for (int k = 0; k < 2; ++k) \
;         acc[ai][bj][m][n] = __builtin_amdgcn_mfma_f32_16x16x32_bf16(Bt[n][k], At[m][k], acc[ai][bj][m][n], 0, 0, 0); __builtin_amdgcn_s_setprio(0); } while (0)
; #define PG8_WAIT_V(n) asm volatile("s_waitcnt vmcnt(" #n ")" ::: "memory")
; #define PG8_WAIT_L(n) asm volatile("s_waitcnt lgkmcnt(" #n ")" ::: "memory")
; #define PG8_BAR __builtin_amdgcn_s_barrier()
; #define PG8_SCHED __builtin_amdgcn_sched_barrier(0)
; template <class Epi, class Sched, bool ALIGN_EPI = false, bool SP2 = false, bool DUAL = false>
; __device__ __forceinline__ void gemm_phase(PG8_LAS unsigned char* lds, const Gemm g, const Sched& S, const Epi& E) {
;     ...
;             PG8_LDB(B0, 0, 0); PG8_LDB(B1, 0, 1); PG8_SCHED; PG8_LDA(At, 0, 0); PG8_STAGE(PG8_SA(1, 1), a1 + hstep, voffA);
;             PG8_WAIT_V(8); PG8_WAIT_L(0); PG8_BAR; PG8_MMA(0, 0, At, B0); PG8_MMA(0, 1, At, B1); PG8_BAR; PG8_SCHED;
;     ...
;             PG8_LDA(At, 1, 1); PG8_STAGE(PG8_SB(1, 0), b3, voffB); PG8_STAGE(PG8_SB(1, 1), b3 + hstep, voffB); PG8_STAGE(PG8_SA(1, 0), a3, voffA);
;             PG8_WAIT_V(8); PG8_WAIT_L(0); PG8_BAR; PG8_MMA(1, 0, At, B0); PG8_MMA(1, 1, At, B1); PG8_BAR; PG8_SCHED;
	s_setprio 0
	s_add_i32 s26, s49, s30
	v_lshl_add_u64 v[220:221], v[220:221], 0, s[18:19]
	s_mov_b32 m0, s26
	ds_read_b128 v[160:163], v203 offset:49152
	ds_read_b128 v[182:185], v203 offset:50176
	ds_read_b128 v[186:189], v203 offset:51200
	ds_read_b128 v[190:193], v203 offset:52224
	ds_read_b128 v[204:207], v203 offset:53248
	ds_read_b128 v[208:211], v203 offset:54272
	ds_read_b128 v[212:215], v203 offset:55296
	ds_read_b128 v[216:219], v203 offset:56320
	global_load_lds_dwordx4 v[220:221], off
	s_add_i32 m0, s26, 0x2000
	s_add_u32 s14, s14, 0x160080
	v_lshl_add_u64 v[220:221], v[222:223], 0, s[18:19]
	s_addc_u32 s15, s15, 0
	s_add_i32 s26, s50, s30
	global_load_lds_dwordx4 v[220:221], off
	v_lshl_add_u64 v[220:221], s[14:15], 0, v[166:167]
	s_mov_b32 m0, s26
	s_nop 0
	global_load_lds_dwordx4 v[220:221], off
	v_lshl_add_u64 v[220:221], s[14:15], 0, v[170:171]
	s_add_i32 m0, s26, 0x2000
	s_nop 0
	global_load_lds_dwordx4 v[220:221], off
	v_lshl_add_u64 v[220:221], v[224:225], 0, s[18:19]
	s_mov_b32 m0, s37
	s_nop 0
	global_load_lds_dwordx4 v[220:221], off
	v_lshl_add_u64 v[220:221], v[226:227], 0, s[18:19]
	s_mov_b32 m0, s38
	s_nop 0
	global_load_lds_dwordx4 v[220:221], off
	s_waitcnt vmcnt(8)
	s_waitcnt lgkmcnt(0)
	s_setprio 1
	s_barrier
	v_mfma_f32_16x16x32_bf16 v[60:63], v[128:131], v[160:163], v[60:63]
	v_mfma_f32_16x16x32_bf16 v[56:59], v[136:139], v[160:163], v[56:59]
	v_mfma_f32_16x16x32_bf16 v[48:51], v[128:131], v[186:189], v[48:51]
	v_mfma_f32_16x16x32_bf16 v[40:43], v[136:139], v[186:189], v[40:43]
	v_mfma_f32_16x16x32_bf16 v[32:35], v[128:131], v[204:207], v[32:35]
	v_mfma_f32_16x16x32_bf16 v[24:27], v[136:139], v[204:207], v[24:27]
	v_mfma_f32_16x16x32_bf16 v[16:19], v[128:131], v[212:215], v[16:19]
	v_mfma_f32_16x16x32_bf16 v[8:11], v[136:139], v[212:215], v[8:11]
	v_mfma_f32_16x16x32_bf16 v[60:63], v[132:135], v[182:185], v[60:63]
	v_mfma_f32_16x16x32_bf16 v[56:59], v[140:143], v[182:185], v[56:59]
	v_mfma_f32_16x16x32_bf16 v[48:51], v[132:135], v[190:193], v[48:51]
	v_mfma_f32_16x16x32_bf16 v[40:43], v[140:143], v[190:193], v[40:43]
	v_mfma_f32_16x16x32_bf16 v[32:35], v[132:135], v[208:211], v[32:35]
	v_mfma_f32_16x16x32_bf16 v[24:27], v[140:143], v[208:211], v[24:27]
	v_mfma_f32_16x16x32_bf16 v[16:19], v[132:135], v[216:219], v[16:19]
	v_mfma_f32_16x16x32_bf16 v[8:11], v[140:143], v[216:219], v[8:11]
	s_setprio 0
	s_setprio 1
	v_mfma_f32_16x16x32_bf16 v[52:55], v[144:147], v[160:163], v[52:55]
	v_mfma_f32_16x16x32_bf16 v[44:47], v[152:155], v[160:163], v[44:47]
	v_mfma_f32_16x16x32_bf16 v[36:39], v[144:147], v[186:189], v[36:39]
	v_mfma_f32_16x16x32_bf16 v[28:31], v[152:155], v[186:189], v[28:31]
	v_mfma_f32_16x16x32_bf16 v[20:23], v[144:147], v[204:207], v[20:23]
	v_mfma_f32_16x16x32_bf16 v[12:15], v[152:155], v[204:207], v[12:15]
	v_mfma_f32_16x16x32_bf16 v[4:7], v[144:147], v[212:215], v[4:7]
	v_mfma_f32_16x16x32_bf16 v[0:3], v[152:155], v[212:215], v[0:3]
	v_mfma_f32_16x16x32_bf16 v[52:55], v[148:151], v[182:185], v[52:55]
	v_mfma_f32_16x16x32_bf16 v[44:47], v[156:159], v[182:185], v[44:47]
	v_mfma_f32_16x16x32_bf16 v[36:39], v[148:151], v[190:193], v[36:39]
	v_mfma_f32_16x16x32_bf16 v[28:31], v[156:159], v[190:193], v[28:31]
	v_mfma_f32_16x16x32_bf16 v[20:23], v[148:151], v[208:211], v[20:23]
	v_mfma_f32_16x16x32_bf16 v[12:15], v[156:159], v[208:211], v[12:15]
	v_mfma_f32_16x16x32_bf16 v[4:7], v[148:151], v[216:219], v[4:7]
	v_mfma_f32_16x16x32_bf16 v[0:3], v[156:159], v[216:219], v[0:3]
	s_barrier
	s_setprio 0
	s_add_i32 s48, s48, 2
	s_add_u32 s24, s24, 0x100
	s_addc_u32 s25, s25, 0
	s_add_u32 s46, s46, 0x100
	s_addc_u32 s47, s47, 0
.LBB0_1193:
	ds_read_b128 v[128:131], v201
	ds_read_b128 v[132:135], v201 offset:1024
	ds_read_b128 v[136:139], v201 offset:2048
	ds_read_b128 v[140:143], v201 offset:3072
	ds_read_b128 v[144:147], v202
	ds_read_b128 v[148:151], v202 offset:1024
	ds_read_b128 v[152:155], v202 offset:2048
	ds_read_b128 v[156:159], v202 offset:3072
	s_add_u32 s14, s24, 0xffea0080
	s_addc_u32 s15, s25, -1
	s_cmpk_eq_i32 s48, 0x54
	s_cselect_b32 s27, s5, s15
	s_cselect_b32 s26, s4, s14
	s_cselect_b32 s15, s23, s47
	s_cselect_b32 s14, s22, s46
	v_lshl_add_u64 v[220:221], s[24:25], 0, v[172:173]
	s_add_i32 m0, s31, 0xc000
	ds_read_b128 v[160:163], v203
	ds_read_b128 v[182:185], v203 offset:1024
	ds_read_b128 v[186:189], v203 offset:2048
	ds_read_b128 v[190:193], v203 offset:3072
	ds_read_b128 v[204:207], v203 offset:4096
	ds_read_b128 v[208:211], v203 offset:5120
	ds_read_b128 v[212:215], v203 offset:6144
	ds_read_b128 v[216:219], v203 offset:7168
	global_load_lds_dwordx4 v[220:221], off
	v_lshl_add_u64 v[220:221], s[24:25], 0, v[174:175]
	s_add_i32 m0, s31, 0xe000
	s_nop 0
	global_load_lds_dwordx4 v[220:221], off
	s_waitcnt vmcnt(8)
	s_waitcnt lgkmcnt(0)
	s_setprio 1
	s_barrier
; #define PG8_STAGE(bufoff, gbase, voff) do { _Pragma("unroll") for (int _i = 0; _i < 2; ++_i) \
;         __builtin_amdgcn_global_load_lds((const unsigned*)((const char*)(gbase) + (voff)[_i]), (PG8_LAS unsigned*)(lds + (bufoff) + ldsw + _i * 8192), 16, 0, 0); } while (0)
; #define PG8_LDA(dst, b, h) do { _Pragma("unroll") for (int m = 0; m < 4; ++m) _Pragma("unroll") for (int k = 0; k < 2; ++k) dst[m][k] = *(const PG8_LAS bf16x8*)(lds + PG8_SA(b, h) + aoff + m * 2048 + k * 1024); } while (0)
; #define PG8_MMA(ai, bj, At, Bt) do { __builtin_amdgcn_s_setprio(1); _Pragma("unroll") for (int m = 0; m < 4; ++m) _Pragma("unroll") for (int n = 0; n < 2; ++n) _Pragma("unroll") for (int k = 0; k < 2; ++k) \
;         acc[ai][bj][m][n] = __builtin_amdgcn_mfma_f32_16x16x32_bf16(Bt[n][k], At[m][k], acc[ai][bj][m][n], 0, 0, 0); __builtin_amdgcn_s_setprio(0); } while (0)
; #define PG8_WAIT_V(n) asm volatile("s_waitcnt vmcnt(" #n ")" ::: "memory")
; #define PG8_WAIT_L(n) asm volatile("s_waitcnt lgkmcnt(" #n ")" ::: "memory")
; #define PG8_BAR __builtin_amdgcn_s_barrier()
; #define PG8_SCHED __builtin_amdgcn_sched_barrier(0)
; template <class Epi, class Sched, bool ALIGN_EPI = false, bool SP2 = false, bool DUAL = false>
; __device__ __forceinline__ void gemm_phase(PG8_LAS unsigned char* lds, const Gemm g, const Sched& S, const Epi& E) {
;     ...
;             PG8_WAIT_V(8); PG8_WAIT_L(0); PG8_BAR; PG8_MMA(0, 0, At, B0); PG8_MMA(0, 1, At, B1); PG8_BAR; PG8_SCHED;
;             PG8_LDA(At, 0, 1); PG8_STAGE(PG8_SB(0, 0), b2, voffB); PG8_STAGE(PG8_SB(0, 1), b2 + hstep, voffB); PG8_STAGE(PG8_SA(0, 0), a2, voffA);
;             PG8_WAIT_V(8); PG8_WAIT_L(0); PG8_BAR; PG8_MMA(1, 0, At, B0); PG8_MMA(1, 1, At, B1); PG8_BAR; PG8_SCHED;
	v_mfma_f32_16x16x32_bf16 v[124:127], v[128:131], v[160:163], v[124:127]
	v_mfma_f32_16x16x32_bf16 v[120:123], v[136:139], v[160:163], v[120:123]
	v_mfma_f32_16x16x32_bf16 v[112:115], v[128:131], v[186:189], v[112:115]
	v_mfma_f32_16x16x32_bf16 v[104:107], v[136:139], v[186:189], v[104:107]
	v_mfma_f32_16x16x32_bf16 v[96:99], v[128:131], v[204:207], v[96:99]
	v_mfma_f32_16x16x32_bf16 v[88:91], v[136:139], v[204:207], v[88:91]
	v_mfma_f32_16x16x32_bf16 v[80:83], v[128:131], v[212:215], v[80:83]
	v_mfma_f32_16x16x32_bf16 v[72:75], v[136:139], v[212:215], v[72:75]
	v_mfma_f32_16x16x32_bf16 v[124:127], v[132:135], v[182:185], v[124:127]
	v_mfma_f32_16x16x32_bf16 v[120:123], v[140:143], v[182:185], v[120:123]
	v_mfma_f32_16x16x32_bf16 v[112:115], v[132:135], v[190:193], v[112:115]
	v_mfma_f32_16x16x32_bf16 v[104:107], v[140:143], v[190:193], v[104:107]
	v_mfma_f32_16x16x32_bf16 v[96:99], v[132:135], v[208:211], v[96:99]
	v_mfma_f32_16x16x32_bf16 v[88:91], v[140:143], v[208:211], v[88:91]
	v_mfma_f32_16x16x32_bf16 v[80:83], v[132:135], v[216:219], v[80:83]
	v_mfma_f32_16x16x32_bf16 v[72:75], v[140:143], v[216:219], v[72:75]
	s_setprio 0
	s_setprio 1
	v_mfma_f32_16x16x32_bf16 v[116:119], v[144:147], v[160:163], v[116:119]
	v_mfma_f32_16x16x32_bf16 v[108:111], v[152:155], v[160:163], v[108:111]
	v_mfma_f32_16x16x32_bf16 v[100:103], v[144:147], v[186:189], v[100:103]
	v_mfma_f32_16x16x32_bf16 v[92:95], v[152:155], v[186:189], v[92:95]
	v_mfma_f32_16x16x32_bf16 v[84:87], v[144:147], v[204:207], v[84:87]
	v_mfma_f32_16x16x32_bf16 v[76:79], v[152:155], v[204:207], v[76:79]
	v_mfma_f32_16x16x32_bf16 v[68:71], v[144:147], v[212:215], v[68:71]
	v_mfma_f32_16x16x32_bf16 v[64:67], v[152:155], v[212:215], v[64:67]
	v_mfma_f32_16x16x32_bf16 v[116:119], v[148:151], v[182:185], v[116:119]
	v_mfma_f32_16x16x32_bf16 v[108:111], v[156:159], v[182:185], v[108:111]
	v_mfma_f32_16x16x32_bf16 v[100:103], v[148:151], v[190:193], v[100:103]
	v_mfma_f32_16x16x32_bf16 v[92:95], v[156:159], v[190:193], v[92:95]
	v_mfma_f32_16x16x32_bf16 v[84:87], v[148:151], v[208:211], v[84:87]
	v_mfma_f32_16x16x32_bf16 v[76:79], v[156:159], v[208:211], v[76:79]
	v_mfma_f32_16x16x32_bf16 v[68:71], v[148:151], v[216:219], v[68:71]
	v_mfma_f32_16x16x32_bf16 v[64:67], v[156:159], v[216:219], v[64:67]
	s_barrier
	s_setprio 0
	s_add_i32 s49, s40, s30
	v_lshl_add_u64 v[220:221], s[14:15], 0, v[166:167]
	s_mov_b32 m0, s49
	ds_read_b128 v[160:163], v203 offset:16384
	ds_read_b128 v[182:185], v203 offset:17408
	ds_read_b128 v[186:189], v203 offset:18432
	ds_read_b128 v[190:193], v203 offset:19456
	ds_read_b128 v[204:207], v203 offset:20480
	ds_read_b128 v[208:211], v203 offset:21504
	ds_read_b128 v[212:215], v203 offset:22528
	ds_read_b128 v[216:219], v203 offset:23552
	global_load_lds_dwordx4 v[220:221], off
	s_add_i32 m0, s49, 0x2000
	s_add_u32 s50, s14, 0x160000
	v_lshl_add_u64 v[222:223], s[14:15], 0, v[170:171]
	s_addc_u32 s51, s15, 0
	s_add_i32 s49, s41, s30
	global_load_lds_dwordx4 v[222:223], off
	v_lshl_add_u64 v[224:225], s[50:51], 0, v[166:167]
	s_mov_b32 m0, s49
	v_lshl_add_u64 v[226:227], s[26:27], 0, v[168:169]
	global_load_lds_dwordx4 v[224:225], off
	v_lshl_add_u64 v[224:225], s[50:51], 0, v[170:171]
	s_add_i32 m0, s49, 0x2000
	s_nop 0
	global_load_lds_dwordx4 v[224:225], off
	v_lshl_add_u64 v[224:225], s[26:27], 0, v[164:165]
	s_mov_b32 m0, s31
	s_nop 0
	global_load_lds_dwordx4 v[224:225], off
	s_mov_b32 m0, s33
	s_nop 0
	global_load_lds_dwordx4 v[226:227], off
	s_waitcnt vmcnt(8)
	s_waitcnt lgkmcnt(0)
	s_setprio 1
	s_barrier
	v_mfma_f32_16x16x32_bf16 v[60:63], v[128:131], v[160:163], v[60:63]
	v_mfma_f32_16x16x32_bf16 v[56:59], v[136:139], v[160:163], v[56:59]
	v_mfma_f32_16x16x32_bf16 v[48:51], v[128:131], v[186:189], v[48:51]
	v_mfma_f32_16x16x32_bf16 v[40:43], v[136:139], v[186:189], v[40:43]
	v_mfma_f32_16x16x32_bf16 v[32:35], v[128:131], v[204:207], v[32:35]
	v_mfma_f32_16x16x32_bf16 v[24:27], v[136:139], v[204:207], v[24:27]
	v_mfma_f32_16x16x32_bf16 v[16:19], v[128:131], v[212:215], v[16:19]
	v_mfma_f32_16x16x32_bf16 v[8:11], v[136:139], v[212:215], v[8:11]
	v_mfma_f32_16x16x32_bf16 v[60:63], v[132:135], v[182:185], v[60:63]
	v_mfma_f32_16x16x32_bf16 v[56:59], v[140:143], v[182:185], v[56:59]
	v_mfma_f32_16x16x32_bf16 v[48:51], v[132:135], v[190:193], v[48:51]
	v_mfma_f32_16x16x32_bf16 v[40:43], v[140:143], v[190:193], v[40:43]
	v_mfma_f32_16x16x32_bf16 v[32:35], v[132:135], v[208:211], v[32:35]
	v_mfma_f32_16x16x32_bf16 v[24:27], v[140:143], v[208:211], v[24:27]
	v_mfma_f32_16x16x32_bf16 v[16:19], v[132:135], v[216:219], v[16:19]
	v_mfma_f32_16x16x32_bf16 v[8:11], v[140:143], v[216:219], v[8:11]
	s_setprio 0
	s_setprio 1
	v_mfma_f32_16x16x32_bf16 v[52:55], v[144:147], v[160:163], v[52:55]
	v_mfma_f32_16x16x32_bf16 v[44:47], v[152:155], v[160:163], v[44:47]
	v_mfma_f32_16x16x32_bf16 v[36:39], v[144:147], v[186:189], v[36:39]
	v_mfma_f32_16x16x32_bf16 v[28:31], v[152:155], v[186:189], v[28:31]
	v_mfma_f32_16x16x32_bf16 v[20:23], v[144:147], v[204:207], v[20:23]
	v_mfma_f32_16x16x32_bf16 v[12:15], v[152:155], v[204:207], v[12:15]
	v_mfma_f32_16x16x32_bf16 v[4:7], v[144:147], v[212:215], v[4:7]
	v_mfma_f32_16x16x32_bf16 v[0:3], v[152:155], v[212:215], v[0:3]
	v_mfma_f32_16x16x32_bf16 v[52:55], v[148:151], v[182:185], v[52:55]
	v_mfma_f32_16x16x32_bf16 v[44:47], v[156:159], v[182:185], v[44:47]
	v_mfma_f32_16x16x32_bf16 v[36:39], v[148:151], v[190:193], v[36:39]
	v_mfma_f32_16x16x32_bf16 v[28:31], v[156:159], v[190:193], v[28:31]
	v_mfma_f32_16x16x32_bf16 v[20:23], v[148:151], v[208:211], v[20:23]
	v_mfma_f32_16x16x32_bf16 v[12:15], v[156:159], v[208:211], v[12:15]
	v_mfma_f32_16x16x32_bf16 v[4:7], v[148:151], v[216:219], v[4:7]
	v_mfma_f32_16x16x32_bf16 v[0:3], v[156:159], v[216:219], v[0:3]
	s_barrier
; #define PG8_STAGE(bufoff, gbase, voff) do { _Pragma("unroll") for (int _i = 0; _i < 2; ++_i) \
;         __builtin_amdgcn_global_load_lds((const unsigned*)((const char*)(gbase) + (voff)[_i]), (PG8_LAS unsigned*)(lds + (bufoff) + ldsw + _i * 8192), 16, 0, 0); } while (0)
; #define PG8_LDA(dst, b, h) do { _Pragma("unroll") for (int m = 0; m < 4; ++m) _Pragma("unroll") for (int k = 0; k < 2; ++k) dst[m][k] = *(const PG8_LAS bf16x8*)(lds + PG8_SA(b, h) + aoff + m * 2048 + k * 1024); } while (0)
; #define PG8_LDB(dst, b, h) do { _Pragma("unroll") for (int n = 0; n < 2; ++n) _Pragma("unroll") for (int k = 0; k < 2; ++k) dst[n][k] = *(const PG8_LAS bf16x8*)(lds + PG8_SB(b, h) + boff + n * 2048 + k * 1024); } while (0)
; #define PG8_MMA(ai, bj, At, Bt) do { __builtin_amdgcn_s_setprio(1); _Pragma("unroll") for (int m = 0; m < 4; ++m) _Pragma("unroll") for (int n = 0; n < 2; ++n) _Pragma("unroll") for (int k = 0; k < 2; ++k) \
;         acc[ai][bj][m][n] = __builtin_amdgcn_mfma_f32_16x16x32_bf16(Bt[n][k], At[m][k], acc[ai][bj][m][n], 0, 0, 0); __builtin_amdgcn_s_setprio(0); } while (0)
; #define PG8_WAIT_V(n) asm volatile("s_waitcnt vmcnt(" #n ")" ::: "memory")
; #define PG8_WAIT_L(n) asm volatile("s_waitcnt lgkmcnt(" #n ")" ::: "memory")
; #define PG8_BAR __builtin_amdgcn_s_barrier()
; #define PG8_SCHED __builtin_amdgcn_sched_barrier(0)
; template <class Epi, class Sched, bool ALIGN_EPI = false, bool SP2 = false, bool DUAL = false>
; __device__ __forceinline__ void gemm_phase(PG8_LAS unsigned char* lds, const Gemm g, const Sched& S, const Epi& E) {
;     ...
;             PG8_LDB(B0, 1, 0); PG8_LDB(B1, 1, 1); PG8_SCHED; PG8_LDA(At, 1, 0); PG8_STAGE(PG8_SA(0, 1), a2 + hstep, voffA);
;             PG8_WAIT_V(8); PG8_WAIT_L(0); PG8_BAR; PG8_MMA(0, 0, At, B0); PG8_MMA(0, 1, At, B1); PG8_BAR; PG8_SCHED;
	s_setprio 0
	s_add_i32 s49, 0, 0x18000
	s_add_i32 s50, 0, 0x1c000
	v_add_u32_e32 v140, s49, v198
	v_add_u32_e32 v156, s50, v198
	ds_read_b128 v[128:131], v140
	ds_read_b128 v[132:135], v140 offset:1024
	ds_read_b128 v[136:139], v140 offset:2048
	ds_read_b128 v[140:143], v140 offset:3072
	ds_read_b128 v[144:147], v156
	ds_read_b128 v[148:151], v156 offset:1024
	ds_read_b128 v[152:155], v156 offset:2048
	ds_read_b128 v[156:159], v156 offset:3072
	s_add_u32 s26, s26, 0x160000
	s_addc_u32 s27, s27, 0
	s_mov_b32 m0, s34
	v_lshl_add_u64 v[228:229], s[26:27], 0, v[164:165]
	ds_read_b128 v[160:163], v203 offset:32768
	ds_read_b128 v[182:185], v203 offset:33792
	ds_read_b128 v[186:189], v203 offset:34816
	ds_read_b128 v[190:193], v203 offset:35840
	ds_read_b128 v[204:207], v203 offset:36864
	ds_read_b128 v[208:211], v203 offset:37888
	ds_read_b128 v[212:215], v203 offset:38912
	ds_read_b128 v[216:219], v203 offset:39936
	global_load_lds_dwordx4 v[228:229], off
	v_lshl_add_u64 v[228:229], s[26:27], 0, v[168:169]
	s_mov_b32 m0, s35
	s_nop 0
	global_load_lds_dwordx4 v[228:229], off
	s_waitcnt vmcnt(8)
	s_waitcnt lgkmcnt(0)
	s_setprio 1
	s_barrier
	v_mfma_f32_16x16x32_bf16 v[124:127], v[128:131], v[160:163], v[124:127]
	v_mfma_f32_16x16x32_bf16 v[120:123], v[136:139], v[160:163], v[120:123]
	v_mfma_f32_16x16x32_bf16 v[112:115], v[128:131], v[186:189], v[112:115]
	v_mfma_f32_16x16x32_bf16 v[104:107], v[136:139], v[186:189], v[104:107]
	v_mfma_f32_16x16x32_bf16 v[96:99], v[128:131], v[204:207], v[96:99]
	v_mfma_f32_16x16x32_bf16 v[88:91], v[136:139], v[204:207], v[88:91]
	v_mfma_f32_16x16x32_bf16 v[80:83], v[128:131], v[212:215], v[80:83]
	v_mfma_f32_16x16x32_bf16 v[72:75], v[136:139], v[212:215], v[72:75]
	v_mfma_f32_16x16x32_bf16 v[124:127], v[132:135], v[182:185], v[124:127]
	v_mfma_f32_16x16x32_bf16 v[120:123], v[140:143], v[182:185], v[120:123]
	v_mfma_f32_16x16x32_bf16 v[112:115], v[132:135], v[190:193], v[112:115]
	v_mfma_f32_16x16x32_bf16 v[104:107], v[140:143], v[190:193], v[104:107]
	v_mfma_f32_16x16x32_bf16 v[96:99], v[132:135], v[208:211], v[96:99]
	v_mfma_f32_16x16x32_bf16 v[88:91], v[140:143], v[208:211], v[88:91]
	v_mfma_f32_16x16x32_bf16 v[80:83], v[132:135], v[216:219], v[80:83]
	v_mfma_f32_16x16x32_bf16 v[72:75], v[140:143], v[216:219], v[72:75]
	s_setprio 0
	s_setprio 1
	v_mfma_f32_16x16x32_bf16 v[116:119], v[144:147], v[160:163], v[116:119]
	v_mfma_f32_16x16x32_bf16 v[108:111], v[152:155], v[160:163], v[108:111]
	v_mfma_f32_16x16x32_bf16 v[100:103], v[144:147], v[186:189], v[100:103]
	v_mfma_f32_16x16x32_bf16 v[92:95], v[152:155], v[186:189], v[92:95]
	v_mfma_f32_16x16x32_bf16 v[84:87], v[144:147], v[204:207], v[84:87]
	v_mfma_f32_16x16x32_bf16 v[76:79], v[152:155], v[204:207], v[76:79]
	v_mfma_f32_16x16x32_bf16 v[68:71], v[144:147], v[212:215], v[68:71]
	v_mfma_f32_16x16x32_bf16 v[64:67], v[152:155], v[212:215], v[64:67]
	v_mfma_f32_16x16x32_bf16 v[116:119], v[148:151], v[182:185], v[116:119]
	v_mfma_f32_16x16x32_bf16 v[108:111], v[156:159], v[182:185], v[108:111]
	v_mfma_f32_16x16x32_bf16 v[100:103], v[148:151], v[190:193], v[100:103]
	v_mfma_f32_16x16x32_bf16 v[92:95], v[156:159], v[190:193], v[92:95]
	v_mfma_f32_16x16x32_bf16 v[84:87], v[148:151], v[208:211], v[84:87]
	v_mfma_f32_16x16x32_bf16 v[76:79], v[156:159], v[208:211], v[76:79]
	v_mfma_f32_16x16x32_bf16 v[68:71], v[148:151], v[216:219], v[68:71]
	v_mfma_f32_16x16x32_bf16 v[64:67], v[156:159], v[216:219], v[64:67]
	s_barrier
; #define PG8_STAGE(bufoff, gbase, voff) do { _Pragma("unroll") for (int _i = 0; _i < 2; ++_i) \
;         __builtin_amdgcn_global_load_lds((const unsigned*)((const char*)(gbase) + (voff)[_i]), (PG8_LAS unsigned*)(lds + (bufoff) + ldsw + _i * 8192), 16, 0, 0); } while (0)
; #define PG8_LDA(dst, b, h) do { _Pragma("unroll") for (int m = 0; m < 4; ++m) _Pragma("unroll") for (int k = 0; k < 2; ++k) dst[m][k] = *(const PG8_LAS bf16x8*)(lds + PG8_SA(b, h) + aoff + m * 2048 + k * 1024); } while (0)
; #define PG8_MMA(ai, bj, At, Bt) do { __builtin_amdgcn_s_setprio(1); _Pragma("unroll") for (int m = 0; m < 4; ++m) _Pragma("unroll") for (int n = 0; n < 2; ++n) _Pragma("unroll") for (int k = 0; k < 2; ++k) \
;         acc[ai][bj][m][n] = __builtin_amdgcn_mfma_f32_16x16x32_bf16(Bt[n][k], At[m][k], acc[ai][bj][m][n], 0, 0, 0); __builtin_amdgcn_s_setprio(0); } while (0)
; #define PG8_WAIT_V(n) asm volatile("s_waitcnt vmcnt(" #n ")" ::: "memory")
; #define PG8_WAIT_L(n) asm volatile("s_waitcnt lgkmcnt(" #n ")" ::: "memory")
; #define PG8_BAR __builtin_amdgcn_s_barrier()
; #define PG8_SCHED __builtin_amdgcn_sched_barrier(0)
; template <class Epi, class Sched, bool ALIGN_EPI = false, bool SP2 = false, bool DUAL = false>
; __device__ __forceinline__ void gemm_phase(PG8_LAS unsigned char* lds, const Gemm g, const Sched& S, const Epi& E) {
;     ...
;             PG8_LDA(At, 1, 1); PG8_STAGE(PG8_SB(1, 0), b3, voffB); PG8_STAGE(PG8_SB(1, 1), b3 + hstep, voffB); PG8_STAGE(PG8_SA(1, 0), a3, voffA);
;             PG8_WAIT_V(8); PG8_WAIT_L(0); PG8_BAR; PG8_MMA(1, 0, At, B0); PG8_MMA(1, 1, At, B1); PG8_BAR; PG8_SCHED;
;     ...
;         if constexpr (ALIGN_EPI) { if (wr == 0) PG8_BAR; }
	s_setprio 0
	s_add_i32 s26, s49, s30
	v_lshl_add_u64 v[220:221], v[220:221], 0, s[18:19]
	s_mov_b32 m0, s26
	ds_read_b128 v[160:163], v203 offset:49152
	ds_read_b128 v[182:185], v203 offset:50176
	ds_read_b128 v[186:189], v203 offset:51200
	ds_read_b128 v[190:193], v203 offset:52224
	ds_read_b128 v[204:207], v203 offset:53248
	ds_read_b128 v[208:211], v203 offset:54272
	ds_read_b128 v[212:215], v203 offset:55296
	ds_read_b128 v[216:219], v203 offset:56320
	global_load_lds_dwordx4 v[220:221], off
	s_add_i32 m0, s26, 0x2000
	s_add_u32 s14, s14, 0x160080
	v_lshl_add_u64 v[220:221], v[222:223], 0, s[18:19]
	s_addc_u32 s15, s15, 0
	s_add_i32 s26, s50, s30
	global_load_lds_dwordx4 v[220:221], off
	v_lshl_add_u64 v[220:221], s[14:15], 0, v[166:167]
	s_mov_b32 m0, s26
	s_nop 0
	global_load_lds_dwordx4 v[220:221], off
	v_lshl_add_u64 v[220:221], s[14:15], 0, v[170:171]
	s_add_i32 m0, s26, 0x2000
	s_nop 0
	global_load_lds_dwordx4 v[220:221], off
	v_lshl_add_u64 v[220:221], v[224:225], 0, s[18:19]
	s_mov_b32 m0, s37
	s_nop 0
	global_load_lds_dwordx4 v[220:221], off
	v_lshl_add_u64 v[220:221], v[226:227], 0, s[18:19]
	s_mov_b32 m0, s38
	s_nop 0
	global_load_lds_dwordx4 v[220:221], off
	s_waitcnt vmcnt(8)
	s_waitcnt lgkmcnt(0)
	s_setprio 1
	s_barrier
	v_mfma_f32_16x16x32_bf16 v[60:63], v[128:131], v[160:163], v[60:63]
	v_mfma_f32_16x16x32_bf16 v[56:59], v[136:139], v[160:163], v[56:59]
	v_mfma_f32_16x16x32_bf16 v[48:51], v[128:131], v[186:189], v[48:51]
	v_mfma_f32_16x16x32_bf16 v[40:43], v[136:139], v[186:189], v[40:43]
	v_mfma_f32_16x16x32_bf16 v[32:35], v[128:131], v[204:207], v[32:35]
	v_mfma_f32_16x16x32_bf16 v[24:27], v[136:139], v[204:207], v[24:27]
	v_mfma_f32_16x16x32_bf16 v[16:19], v[128:131], v[212:215], v[16:19]
	v_mfma_f32_16x16x32_bf16 v[8:11], v[136:139], v[212:215], v[8:11]
	v_mfma_f32_16x16x32_bf16 v[60:63], v[132:135], v[182:185], v[60:63]
	v_mfma_f32_16x16x32_bf16 v[56:59], v[140:143], v[182:185], v[56:59]
	v_mfma_f32_16x16x32_bf16 v[48:51], v[132:135], v[190:193], v[48:51]
	v_mfma_f32_16x16x32_bf16 v[40:43], v[140:143], v[190:193], v[40:43]
	v_mfma_f32_16x16x32_bf16 v[32:35], v[132:135], v[208:211], v[32:35]
	v_mfma_f32_16x16x32_bf16 v[24:27], v[140:143], v[208:211], v[24:27]
	v_mfma_f32_16x16x32_bf16 v[16:19], v[132:135], v[216:219], v[16:19]
	v_mfma_f32_16x16x32_bf16 v[8:11], v[140:143], v[216:219], v[8:11]
	s_setprio 0
	s_setprio 1
	v_mfma_f32_16x16x32_bf16 v[52:55], v[144:147], v[160:163], v[52:55]
	v_mfma_f32_16x16x32_bf16 v[44:47], v[152:155], v[160:163], v[44:47]
	v_mfma_f32_16x16x32_bf16 v[36:39], v[144:147], v[186:189], v[36:39]
	v_mfma_f32_16x16x32_bf16 v[28:31], v[152:155], v[186:189], v[28:31]
	v_mfma_f32_16x16x32_bf16 v[20:23], v[144:147], v[204:207], v[20:23]
	v_mfma_f32_16x16x32_bf16 v[12:15], v[152:155], v[204:207], v[12:15]
	v_mfma_f32_16x16x32_bf16 v[4:7], v[144:147], v[212:215], v[4:7]
	v_mfma_f32_16x16x32_bf16 v[0:3], v[152:155], v[212:215], v[0:3]
	v_mfma_f32_16x16x32_bf16 v[52:55], v[148:151], v[182:185], v[52:55]
	v_mfma_f32_16x16x32_bf16 v[44:47], v[156:159], v[182:185], v[44:47]
	v_mfma_f32_16x16x32_bf16 v[36:39], v[148:151], v[190:193], v[36:39]
	v_mfma_f32_16x16x32_bf16 v[28:31], v[156:159], v[190:193], v[28:31]
	v_mfma_f32_16x16x32_bf16 v[20:23], v[148:151], v[208:211], v[20:23]
	v_mfma_f32_16x16x32_bf16 v[12:15], v[156:159], v[208:211], v[12:15]
	v_mfma_f32_16x16x32_bf16 v[4:7], v[148:151], v[216:219], v[4:7]
	v_mfma_f32_16x16x32_bf16 v[0:3], v[156:159], v[216:219], v[0:3]
	s_barrier
	s_setprio 0
	s_add_i32 s48, s48, 2
	s_add_u32 s24, s24, 0x100
	s_addc_u32 s25, s25, 0
	s_add_u32 s46, s46, 0x100
	s_addc_u32 s47, s47, 0
	s_cmpk_gt_u32 s48, 0x55
	s_cbranch_scc0 .LBB0_1193
	s_and_b64 vcc, exec, s[20:21]
	s_cbranch_vccz .LBB0_1196
	s_barrier
